# q-rope epilogue cos/sin loads hoisted with counted waits; norm loops: gain-vector loads hoisted out of row loops and last butterfly hop batched
# speedup vs baseline: 1.0456x; 1.0013x over previous
.LBB0_432:
	v_mov_b32_e32 v137, v141
	v_mov_b32_e32 v136, v140
	s_lshl_b32 s0, s50, 8
	s_add_i32 s0, s0, s42
	v_add_u32_e32 v136, s0, v136
	v_lshlrev_b32_e32 v152, 2, v137
	v_ashrrev_i32_e32 v137, 31, v136
	v_ashrrev_i32_e32 v153, 31, v152
	v_lshlrev_b64 v[148:149], 6, v[136:137]
	v_lshl_add_u64 v[144:145], s[14:15], 0, v[148:149]
	v_lshlrev_b64 v[138:139], 2, v[152:153]
	v_lshl_add_u64 v[148:149], s[16:17], 0, v[148:149]
	v_lshl_add_u64 v[188:189], v[144:145], 0, v[138:139]
	v_lshl_add_u64 v[190:191], v[148:149], 0, v[138:139]
	global_load_dwordx4 v[144:147], v[188:189], off
	s_lshl_b32 s0, s33, 8
	global_load_dwordx4 v[148:151], v[190:191], off
	s_mov_b64 s[98:99], 0x2000
	global_load_dwordx4 v[164:167], v[188:189], off offset:1024
	global_load_dwordx4 v[168:171], v[190:191], off offset:1024
	v_lshl_add_u64 v[228:229], v[188:189], 0, s[98:99]
	v_lshl_add_u64 v[230:231], v[190:191], 0, s[98:99]
	global_load_dwordx4 v[172:175], v[188:189], off offset:2048
	global_load_dwordx4 v[176:179], v[190:191], off offset:2048
	global_load_dwordx4 v[180:183], v[188:189], off offset:3072
	global_load_dwordx4 v[184:187], v[190:191], off offset:3072
	global_load_dwordx4 v[204:207], v[228:229], off
	global_load_dwordx4 v[208:211], v[230:231], off
	global_load_dwordx4 v[212:215], v[228:229], off offset:1024
	global_load_dwordx4 v[216:219], v[230:231], off offset:1024
	global_load_dwordx4 v[220:223], v[228:229], off offset:2048
	global_load_dwordx4 v[224:227], v[230:231], off offset:2048
	global_load_dwordx4 v[242:245], v[228:229], off offset:3072
	global_load_dwordx4 v[246:249], v[230:231], off offset:3072
	s_or_b32 s28, s0, s43
	s_ashr_i32 s0, s28, 5
	s_mul_hi_i32 s1, s0, 0x55555556
	s_lshr_b32 s26, s1, 31
	s_add_i32 s1, s1, s26
	s_mul_i32 s1, s1, 3
	s_sub_i32 s0, s0, s1
	s_cmp_eq_u32 s0, 2
	s_cselect_b64 s[0:1], -1, 0
	s_ashr_i32 s29, s28, 31
	s_waitcnt vmcnt(14)
	v_pk_mul_f32 v[160:161], v[126:127], v[148:149]
	v_pk_mul_f32 v[156:157], v[122:123], v[148:149]
	v_pk_mul_f32 v[158:159], v[128:129], v[150:151]
	v_pk_fma_f32 v[160:161], v[122:123], v[144:145], v[160:161]
	v_pk_mul_f32 v[154:155], v[124:125], v[150:151]
	v_pk_fma_f32 v[156:157], v[126:127], v[144:145], v[156:157] neg_lo:[0,0,1] neg_hi:[0,0,1]
	v_pk_fma_f32 v[158:159], v[124:125], v[146:147], v[158:159]
	v_cndmask_b32_e64 v123, v123, v161, s[0:1]
	v_cndmask_b32_e64 v122, v122, v160, s[0:1]
	v_pk_fma_f32 v[154:155], v[128:129], v[146:147], v[154:155] neg_lo:[0,0,1] neg_hi:[0,0,1]
	v_cndmask_b32_e64 v127, v127, v157, s[0:1]
	v_cndmask_b32_e64 v126, v126, v156, s[0:1]
	v_cndmask_b32_e64 v125, v125, v159, s[0:1]
	v_cndmask_b32_e64 v124, v124, v158, s[0:1]
	v_pk_mul_f32 v[156:157], v[122:123], s[60:61] op_sel_hi:[1,0]
	v_mov_b64_e32 v[122:123], s[12:13]
	v_cndmask_b32_e64 v129, v129, v155, s[0:1]
	v_cndmask_b32_e64 v128, v128, v154, s[0:1]
	v_pk_mul_f32 v[154:155], v[124:125], s[60:61] op_sel_hi:[1,0]
	v_mad_i64_i32 v[124:125], s[26:27], v136, s59, v[122:123]
	s_lshl_b64 s[26:27], s[28:29], 1
	s_bitset1_b32 s28, 7
	s_ashr_i32 s28, s28, 5
	s_mul_hi_i32 s29, s28, 0x55555556
	s_lshr_b32 s33, s29, 31
	s_add_i32 s29, s29, s33
	v_pk_mul_f32 v[128:129], v[128:129], s[60:61] op_sel_hi:[1,0]
	v_pk_mul_f32 v[126:127], v[126:127], s[60:61] op_sel_hi:[1,0]
	v_lshl_add_u64 v[158:159], v[124:125], 0, s[26:27]
	v_lshlrev_b64 v[124:125], 1, v[152:153]
	s_mul_i32 s29, s29, 3
	v_lshl_add_u64 v[152:153], v[158:159], 0, v[124:125]
	v_cvt_pk_bf16_f32 v126, v126, v127
	v_cvt_pk_bf16_f32 v127, v128, v129
	v_cvt_pk_bf16_f32 v128, v156, v157
	v_cvt_pk_bf16_f32 v129, v154, v155
	s_sub_i32 s28, s28, s29
	global_store_dwordx2 v[152:153], v[126:127], off
	global_store_dwordx2 v[152:153], v[128:129], off offset:32
	s_cmp_eq_u32 s28, 2
	v_pk_mul_f32 v[128:129], v[114:115], v[148:149]
	s_cselect_b64 vcc, -1, 0
	v_pk_mul_f32 v[126:127], v[116:117], v[150:151]
	v_pk_fma_f32 v[128:129], v[118:119], v[144:145], v[128:129] neg_lo:[0,0,1] neg_hi:[0,0,1]
	v_pk_mul_f32 v[148:149], v[118:119], v[148:149]
	v_pk_fma_f32 v[126:127], v[120:121], v[146:147], v[126:127] neg_lo:[0,0,1] neg_hi:[0,0,1]
	v_pk_mul_f32 v[150:151], v[120:121], v[150:151]
	v_pk_fma_f32 v[144:145], v[114:115], v[144:145], v[148:149]
	v_cndmask_b32_e32 v119, v119, v129, vcc
	v_cndmask_b32_e32 v118, v118, v128, vcc
	v_pk_fma_f32 v[146:147], v[116:117], v[146:147], v[150:151]
	v_cndmask_b32_e32 v121, v121, v127, vcc
	v_cndmask_b32_e32 v120, v120, v126, vcc
	v_cndmask_b32_e32 v115, v115, v145, vcc
	v_cndmask_b32_e32 v114, v114, v144, vcc
	v_pk_mul_f32 v[118:119], v[118:119], s[60:61] op_sel_hi:[1,0]
	v_cndmask_b32_e32 v117, v117, v147, vcc
	v_cndmask_b32_e32 v116, v116, v146, vcc
	v_pk_mul_f32 v[120:121], v[120:121], s[60:61] op_sel_hi:[1,0]
	v_pk_mul_f32 v[114:115], v[114:115], s[60:61] op_sel_hi:[1,0]
	v_cvt_pk_bf16_f32 v118, v118, v119
	v_cvt_pk_bf16_f32 v119, v120, v121
	v_pk_mul_f32 v[116:117], v[116:117], s[60:61] op_sel_hi:[1,0]
	v_cvt_pk_bf16_f32 v114, v114, v115
	s_nop 0
	v_cvt_pk_bf16_f32 v115, v116, v117
	global_store_dwordx2 v[152:153], v[118:119], off offset:256
	global_store_dwordx2 v[152:153], v[114:115], off offset:288
	v_add_u32_e32 v118, 16, v136
	v_mad_i64_i32 v[118:119], s[28:29], v118, s59, v[122:123]
	v_lshl_add_u64 v[118:119], v[118:119], 0, s[26:27]
	v_lshl_add_u64 v[118:119], v[118:119], 0, v[124:125]
	s_waitcnt vmcnt(16)
	v_pk_mul_f32 v[144:145], v[106:107], v[168:169]
	v_pk_mul_f32 v[146:147], v[112:113], v[170:171]
	v_pk_mul_f32 v[148:149], v[110:111], v[168:169]
	v_pk_mul_f32 v[120:121], v[108:109], v[170:171]
	v_pk_fma_f32 v[144:145], v[110:111], v[164:165], v[144:145] neg_lo:[0,0,1] neg_hi:[0,0,1]
	v_pk_fma_f32 v[146:147], v[108:109], v[166:167], v[146:147]
	v_pk_fma_f32 v[148:149], v[106:107], v[164:165], v[148:149]
	v_pk_fma_f32 v[120:121], v[112:113], v[166:167], v[120:121] neg_lo:[0,0,1] neg_hi:[0,0,1]
	v_cndmask_b32_e64 v111, v111, v145, s[0:1]
	v_cndmask_b32_e64 v110, v110, v144, s[0:1]
	v_cndmask_b32_e64 v109, v109, v147, s[0:1]
	v_cndmask_b32_e64 v108, v108, v146, s[0:1]
	v_cndmask_b32_e64 v107, v107, v149, s[0:1]
	v_cndmask_b32_e64 v106, v106, v148, s[0:1]
	v_cndmask_b32_e64 v113, v113, v121, s[0:1]
	v_cndmask_b32_e64 v112, v112, v120, s[0:1]
	v_pk_mul_f32 v[110:111], v[110:111], s[60:61] op_sel_hi:[1,0]
	v_pk_mul_f32 v[108:109], v[108:109], s[60:61] op_sel_hi:[1,0]
	v_pk_mul_f32 v[106:107], v[106:107], s[60:61] op_sel_hi:[1,0]
	v_pk_mul_f32 v[112:113], v[112:113], s[60:61] op_sel_hi:[1,0]
	v_cvt_pk_bf16_f32 v110, v110, v111
	v_cvt_pk_bf16_f32 v106, v106, v107
	v_cvt_pk_bf16_f32 v107, v108, v109
	v_pk_mul_f32 v[108:109], v[98:99], v[168:169]
	v_cvt_pk_bf16_f32 v111, v112, v113
	global_store_dwordx2 v[118:119], v[110:111], off
	global_store_dwordx2 v[118:119], v[106:107], off offset:32
	v_pk_mul_f32 v[106:107], v[100:101], v[170:171]
	v_pk_fma_f32 v[108:109], v[102:103], v[164:165], v[108:109] neg_lo:[0,0,1] neg_hi:[0,0,1]
	v_pk_mul_f32 v[112:113], v[102:103], v[168:169]
	v_pk_fma_f32 v[106:107], v[104:105], v[166:167], v[106:107] neg_lo:[0,0,1] neg_hi:[0,0,1]
	v_pk_mul_f32 v[110:111], v[104:105], v[170:171]
	v_pk_fma_f32 v[112:113], v[98:99], v[164:165], v[112:113]
	v_cndmask_b32_e32 v103, v103, v109, vcc
	v_cndmask_b32_e32 v102, v102, v108, vcc
	v_pk_fma_f32 v[110:111], v[100:101], v[166:167], v[110:111]
	v_cndmask_b32_e32 v105, v105, v107, vcc
	v_cndmask_b32_e32 v104, v104, v106, vcc
	v_cndmask_b32_e32 v99, v99, v113, vcc
	v_cndmask_b32_e32 v98, v98, v112, vcc
	v_pk_mul_f32 v[102:103], v[102:103], s[60:61] op_sel_hi:[1,0]
	v_cndmask_b32_e32 v101, v101, v111, vcc
	v_cndmask_b32_e32 v100, v100, v110, vcc
	v_pk_mul_f32 v[104:105], v[104:105], s[60:61] op_sel_hi:[1,0]
	v_pk_mul_f32 v[98:99], v[98:99], s[60:61] op_sel_hi:[1,0]
	v_cvt_pk_bf16_f32 v102, v102, v103
	v_cvt_pk_bf16_f32 v103, v104, v105
	v_pk_mul_f32 v[100:101], v[100:101], s[60:61] op_sel_hi:[1,0]
	v_cvt_pk_bf16_f32 v98, v98, v99
	s_nop 0
	v_cvt_pk_bf16_f32 v99, v100, v101
	global_store_dwordx2 v[118:119], v[102:103], off offset:256
	global_store_dwordx2 v[118:119], v[98:99], off offset:288
	v_add_u32_e32 v102, 32, v136
	v_mad_i64_i32 v[102:103], s[28:29], v102, s59, v[122:123]
	v_lshl_add_u64 v[102:103], v[102:103], 0, s[26:27]
	v_lshl_add_u64 v[102:103], v[102:103], 0, v[124:125]
	s_waitcnt vmcnt(18)
	v_pk_mul_f32 v[110:111], v[90:91], v[176:177]
	v_pk_mul_f32 v[112:113], v[96:97], v[178:179]
	v_pk_mul_f32 v[114:115], v[94:95], v[176:177]
	v_pk_mul_f32 v[108:109], v[92:93], v[178:179]
	v_pk_fma_f32 v[110:111], v[94:95], v[172:173], v[110:111] neg_lo:[0,0,1] neg_hi:[0,0,1]
	v_pk_fma_f32 v[112:113], v[92:93], v[174:175], v[112:113]
	v_pk_fma_f32 v[114:115], v[90:91], v[172:173], v[114:115]
	v_pk_fma_f32 v[108:109], v[96:97], v[174:175], v[108:109] neg_lo:[0,0,1] neg_hi:[0,0,1]
	v_cndmask_b32_e64 v95, v95, v111, s[0:1]
	v_cndmask_b32_e64 v94, v94, v110, s[0:1]
	v_cndmask_b32_e64 v93, v93, v113, s[0:1]
	v_cndmask_b32_e64 v92, v92, v112, s[0:1]
	v_cndmask_b32_e64 v91, v91, v115, s[0:1]
	v_cndmask_b32_e64 v90, v90, v114, s[0:1]
	v_cndmask_b32_e64 v97, v97, v109, s[0:1]
	v_cndmask_b32_e64 v96, v96, v108, s[0:1]
	v_pk_mul_f32 v[94:95], v[94:95], s[60:61] op_sel_hi:[1,0]
	v_pk_mul_f32 v[92:93], v[92:93], s[60:61] op_sel_hi:[1,0]
	v_pk_mul_f32 v[90:91], v[90:91], s[60:61] op_sel_hi:[1,0]
	v_pk_mul_f32 v[96:97], v[96:97], s[60:61] op_sel_hi:[1,0]
	v_cvt_pk_bf16_f32 v94, v94, v95
	v_cvt_pk_bf16_f32 v90, v90, v91
	v_cvt_pk_bf16_f32 v91, v92, v93
	v_pk_mul_f32 v[92:93], v[82:83], v[176:177]
	v_cvt_pk_bf16_f32 v95, v96, v97
	global_store_dwordx2 v[102:103], v[94:95], off
	global_store_dwordx2 v[102:103], v[90:91], off offset:32
	v_pk_mul_f32 v[90:91], v[84:85], v[178:179]
	v_pk_fma_f32 v[92:93], v[86:87], v[172:173], v[92:93] neg_lo:[0,0,1] neg_hi:[0,0,1]
	v_pk_mul_f32 v[96:97], v[86:87], v[176:177]
	v_pk_fma_f32 v[90:91], v[88:89], v[174:175], v[90:91] neg_lo:[0,0,1] neg_hi:[0,0,1]
	v_pk_mul_f32 v[94:95], v[88:89], v[178:179]
	v_pk_fma_f32 v[96:97], v[82:83], v[172:173], v[96:97]
	v_cndmask_b32_e32 v87, v87, v93, vcc
	v_cndmask_b32_e32 v86, v86, v92, vcc
	v_pk_fma_f32 v[94:95], v[84:85], v[174:175], v[94:95]
	v_cndmask_b32_e32 v89, v89, v91, vcc
	v_cndmask_b32_e32 v88, v88, v90, vcc
	v_cndmask_b32_e32 v83, v83, v97, vcc
	v_cndmask_b32_e32 v82, v82, v96, vcc
	v_pk_mul_f32 v[86:87], v[86:87], s[60:61] op_sel_hi:[1,0]
	v_cndmask_b32_e32 v85, v85, v95, vcc
	v_cndmask_b32_e32 v84, v84, v94, vcc
	v_pk_mul_f32 v[88:89], v[88:89], s[60:61] op_sel_hi:[1,0]
	v_pk_mul_f32 v[82:83], v[82:83], s[60:61] op_sel_hi:[1,0]
	v_cvt_pk_bf16_f32 v86, v86, v87
	v_cvt_pk_bf16_f32 v87, v88, v89
	v_pk_mul_f32 v[84:85], v[84:85], s[60:61] op_sel_hi:[1,0]
	v_cvt_pk_bf16_f32 v82, v82, v83
	s_nop 0
	v_cvt_pk_bf16_f32 v83, v84, v85
	global_store_dwordx2 v[102:103], v[86:87], off offset:256
	global_store_dwordx2 v[102:103], v[82:83], off offset:288
	v_add_u32_e32 v86, 48, v136
	v_mad_i64_i32 v[86:87], s[28:29], v86, s59, v[122:123]
	v_lshl_add_u64 v[86:87], v[86:87], 0, s[26:27]
	v_lshl_add_u64 v[86:87], v[86:87], 0, v[124:125]
	s_waitcnt vmcnt(20)
	v_pk_mul_f32 v[94:95], v[74:75], v[184:185]
	v_pk_mul_f32 v[96:97], v[80:81], v[186:187]
	v_pk_mul_f32 v[98:99], v[78:79], v[184:185]
	v_pk_mul_f32 v[92:93], v[76:77], v[186:187]
	v_pk_fma_f32 v[94:95], v[78:79], v[180:181], v[94:95] neg_lo:[0,0,1] neg_hi:[0,0,1]
	v_pk_fma_f32 v[96:97], v[76:77], v[182:183], v[96:97]
	v_pk_fma_f32 v[98:99], v[74:75], v[180:181], v[98:99]
	v_pk_fma_f32 v[92:93], v[80:81], v[182:183], v[92:93] neg_lo:[0,0,1] neg_hi:[0,0,1]
	v_cndmask_b32_e64 v79, v79, v95, s[0:1]
	v_cndmask_b32_e64 v78, v78, v94, s[0:1]
	v_cndmask_b32_e64 v77, v77, v97, s[0:1]
	v_cndmask_b32_e64 v76, v76, v96, s[0:1]
	v_cndmask_b32_e64 v75, v75, v99, s[0:1]
	v_cndmask_b32_e64 v74, v74, v98, s[0:1]
	v_cndmask_b32_e64 v81, v81, v93, s[0:1]
	v_cndmask_b32_e64 v80, v80, v92, s[0:1]
	v_pk_mul_f32 v[78:79], v[78:79], s[60:61] op_sel_hi:[1,0]
	v_pk_mul_f32 v[76:77], v[76:77], s[60:61] op_sel_hi:[1,0]
	v_pk_mul_f32 v[74:75], v[74:75], s[60:61] op_sel_hi:[1,0]
	v_pk_mul_f32 v[80:81], v[80:81], s[60:61] op_sel_hi:[1,0]
	v_cvt_pk_bf16_f32 v78, v78, v79
	v_cvt_pk_bf16_f32 v74, v74, v75
	v_cvt_pk_bf16_f32 v75, v76, v77
	v_pk_mul_f32 v[76:77], v[66:67], v[184:185]
	v_cvt_pk_bf16_f32 v79, v80, v81
	global_store_dwordx2 v[86:87], v[78:79], off
	global_store_dwordx2 v[86:87], v[74:75], off offset:32
	v_pk_mul_f32 v[74:75], v[68:69], v[186:187]
	v_pk_fma_f32 v[76:77], v[70:71], v[180:181], v[76:77] neg_lo:[0,0,1] neg_hi:[0,0,1]
	v_pk_mul_f32 v[80:81], v[70:71], v[184:185]
	v_pk_fma_f32 v[74:75], v[72:73], v[182:183], v[74:75] neg_lo:[0,0,1] neg_hi:[0,0,1]
	v_pk_mul_f32 v[78:79], v[72:73], v[186:187]
	v_pk_fma_f32 v[80:81], v[66:67], v[180:181], v[80:81]
	v_cndmask_b32_e32 v71, v71, v77, vcc
	v_cndmask_b32_e32 v70, v70, v76, vcc
	v_pk_fma_f32 v[78:79], v[68:69], v[182:183], v[78:79]
	v_cndmask_b32_e32 v73, v73, v75, vcc
	v_cndmask_b32_e32 v72, v72, v74, vcc
	v_cndmask_b32_e32 v67, v67, v81, vcc
	v_cndmask_b32_e32 v66, v66, v80, vcc
	v_pk_mul_f32 v[70:71], v[70:71], s[60:61] op_sel_hi:[1,0]
	v_cndmask_b32_e32 v69, v69, v79, vcc
	v_cndmask_b32_e32 v68, v68, v78, vcc
	v_pk_mul_f32 v[72:73], v[72:73], s[60:61] op_sel_hi:[1,0]
	v_pk_mul_f32 v[66:67], v[66:67], s[60:61] op_sel_hi:[1,0]
	v_cvt_pk_bf16_f32 v70, v70, v71
	v_cvt_pk_bf16_f32 v71, v72, v73
	v_pk_mul_f32 v[68:69], v[68:69], s[60:61] op_sel_hi:[1,0]
	v_cvt_pk_bf16_f32 v66, v66, v67
	s_nop 0
	v_cvt_pk_bf16_f32 v67, v68, v69
	global_store_dwordx2 v[86:87], v[70:71], off offset:256
	global_store_dwordx2 v[86:87], v[66:67], off offset:288
	v_add_u32_e32 v70, 0x80, v136
	v_mad_i64_i32 v[70:71], s[28:29], v70, s59, v[122:123]
	v_lshl_add_u64 v[70:71], v[70:71], 0, s[26:27]
	v_lshl_add_u64 v[70:71], v[70:71], 0, v[124:125]
	s_waitcnt vmcnt(22)
	v_pk_mul_f32 v[78:79], v[58:59], v[208:209]
	v_pk_mul_f32 v[80:81], v[64:65], v[210:211]
	v_pk_mul_f32 v[82:83], v[62:63], v[208:209]
	v_pk_mul_f32 v[76:77], v[60:61], v[210:211]
	v_pk_fma_f32 v[78:79], v[62:63], v[204:205], v[78:79] neg_lo:[0,0,1] neg_hi:[0,0,1]
	v_pk_fma_f32 v[80:81], v[60:61], v[206:207], v[80:81]
	v_pk_fma_f32 v[82:83], v[58:59], v[204:205], v[82:83]
	v_pk_fma_f32 v[76:77], v[64:65], v[206:207], v[76:77] neg_lo:[0,0,1] neg_hi:[0,0,1]
	v_cndmask_b32_e64 v63, v63, v79, s[0:1]
	v_cndmask_b32_e64 v62, v62, v78, s[0:1]
	v_cndmask_b32_e64 v61, v61, v81, s[0:1]
	v_cndmask_b32_e64 v60, v60, v80, s[0:1]
	v_cndmask_b32_e64 v59, v59, v83, s[0:1]
	v_cndmask_b32_e64 v58, v58, v82, s[0:1]
	v_cndmask_b32_e64 v65, v65, v77, s[0:1]
	v_cndmask_b32_e64 v64, v64, v76, s[0:1]
	v_pk_mul_f32 v[62:63], v[62:63], s[60:61] op_sel_hi:[1,0]
	v_pk_mul_f32 v[60:61], v[60:61], s[60:61] op_sel_hi:[1,0]
	v_pk_mul_f32 v[58:59], v[58:59], s[60:61] op_sel_hi:[1,0]
	v_pk_mul_f32 v[64:65], v[64:65], s[60:61] op_sel_hi:[1,0]
	v_cvt_pk_bf16_f32 v62, v62, v63
	v_cvt_pk_bf16_f32 v58, v58, v59
	v_cvt_pk_bf16_f32 v59, v60, v61
	v_pk_mul_f32 v[60:61], v[50:51], v[208:209]
	v_cvt_pk_bf16_f32 v63, v64, v65
	global_store_dwordx2 v[70:71], v[62:63], off
	global_store_dwordx2 v[70:71], v[58:59], off offset:32
	v_pk_mul_f32 v[58:59], v[52:53], v[210:211]
	v_pk_fma_f32 v[60:61], v[54:55], v[204:205], v[60:61] neg_lo:[0,0,1] neg_hi:[0,0,1]
	v_pk_mul_f32 v[64:65], v[54:55], v[208:209]
	v_pk_fma_f32 v[58:59], v[56:57], v[206:207], v[58:59] neg_lo:[0,0,1] neg_hi:[0,0,1]
	v_pk_mul_f32 v[62:63], v[56:57], v[210:211]
	v_pk_fma_f32 v[64:65], v[50:51], v[204:205], v[64:65]
	v_cndmask_b32_e32 v55, v55, v61, vcc
	v_cndmask_b32_e32 v54, v54, v60, vcc
	v_pk_fma_f32 v[62:63], v[52:53], v[206:207], v[62:63]
	v_cndmask_b32_e32 v57, v57, v59, vcc
	v_cndmask_b32_e32 v56, v56, v58, vcc
	v_cndmask_b32_e32 v51, v51, v65, vcc
	v_cndmask_b32_e32 v50, v50, v64, vcc
	v_pk_mul_f32 v[54:55], v[54:55], s[60:61] op_sel_hi:[1,0]
	v_cndmask_b32_e32 v53, v53, v63, vcc
	v_cndmask_b32_e32 v52, v52, v62, vcc
	v_pk_mul_f32 v[56:57], v[56:57], s[60:61] op_sel_hi:[1,0]
	v_pk_mul_f32 v[50:51], v[50:51], s[60:61] op_sel_hi:[1,0]
	v_cvt_pk_bf16_f32 v54, v54, v55
	v_cvt_pk_bf16_f32 v55, v56, v57
	v_pk_mul_f32 v[52:53], v[52:53], s[60:61] op_sel_hi:[1,0]
	v_cvt_pk_bf16_f32 v50, v50, v51
	s_nop 0
	v_cvt_pk_bf16_f32 v51, v52, v53
	global_store_dwordx2 v[70:71], v[54:55], off offset:256
	global_store_dwordx2 v[70:71], v[50:51], off offset:288
	v_add_u32_e32 v54, 0x90, v136
	v_mad_i64_i32 v[54:55], s[28:29], v54, s59, v[122:123]
	v_lshl_add_u64 v[54:55], v[54:55], 0, s[26:27]
	v_lshl_add_u64 v[54:55], v[54:55], 0, v[124:125]
	s_waitcnt vmcnt(24)
	v_pk_mul_f32 v[62:63], v[42:43], v[216:217]
	v_pk_mul_f32 v[64:65], v[48:49], v[218:219]
	v_pk_mul_f32 v[66:67], v[46:47], v[216:217]
	v_pk_mul_f32 v[60:61], v[44:45], v[218:219]
	v_pk_fma_f32 v[62:63], v[46:47], v[212:213], v[62:63] neg_lo:[0,0,1] neg_hi:[0,0,1]
	v_pk_fma_f32 v[64:65], v[44:45], v[214:215], v[64:65]
	v_pk_fma_f32 v[66:67], v[42:43], v[212:213], v[66:67]
	v_pk_fma_f32 v[60:61], v[48:49], v[214:215], v[60:61] neg_lo:[0,0,1] neg_hi:[0,0,1]
	v_cndmask_b32_e64 v47, v47, v63, s[0:1]
	v_cndmask_b32_e64 v46, v46, v62, s[0:1]
	v_cndmask_b32_e64 v45, v45, v65, s[0:1]
	v_cndmask_b32_e64 v44, v44, v64, s[0:1]
	v_cndmask_b32_e64 v43, v43, v67, s[0:1]
	v_cndmask_b32_e64 v42, v42, v66, s[0:1]
	v_cndmask_b32_e64 v49, v49, v61, s[0:1]
	v_cndmask_b32_e64 v48, v48, v60, s[0:1]
	v_pk_mul_f32 v[46:47], v[46:47], s[60:61] op_sel_hi:[1,0]
	v_pk_mul_f32 v[44:45], v[44:45], s[60:61] op_sel_hi:[1,0]
	v_pk_mul_f32 v[42:43], v[42:43], s[60:61] op_sel_hi:[1,0]
	v_pk_mul_f32 v[48:49], v[48:49], s[60:61] op_sel_hi:[1,0]
	v_cvt_pk_bf16_f32 v46, v46, v47
	v_cvt_pk_bf16_f32 v42, v42, v43
	v_cvt_pk_bf16_f32 v43, v44, v45
	v_pk_mul_f32 v[44:45], v[34:35], v[216:217]
	v_cvt_pk_bf16_f32 v47, v48, v49
	global_store_dwordx2 v[54:55], v[46:47], off
	global_store_dwordx2 v[54:55], v[42:43], off offset:32
	v_pk_mul_f32 v[42:43], v[36:37], v[218:219]
	v_pk_fma_f32 v[44:45], v[38:39], v[212:213], v[44:45] neg_lo:[0,0,1] neg_hi:[0,0,1]
	v_pk_mul_f32 v[48:49], v[38:39], v[216:217]
	v_pk_fma_f32 v[42:43], v[40:41], v[214:215], v[42:43] neg_lo:[0,0,1] neg_hi:[0,0,1]
	v_pk_mul_f32 v[46:47], v[40:41], v[218:219]
	v_pk_fma_f32 v[48:49], v[34:35], v[212:213], v[48:49]
	v_cndmask_b32_e32 v39, v39, v45, vcc
	v_cndmask_b32_e32 v38, v38, v44, vcc
	v_pk_fma_f32 v[46:47], v[36:37], v[214:215], v[46:47]
	v_cndmask_b32_e32 v41, v41, v43, vcc
	v_cndmask_b32_e32 v40, v40, v42, vcc
	v_cndmask_b32_e32 v35, v35, v49, vcc
	v_cndmask_b32_e32 v34, v34, v48, vcc
	v_pk_mul_f32 v[38:39], v[38:39], s[60:61] op_sel_hi:[1,0]
	v_cndmask_b32_e32 v37, v37, v47, vcc
	v_cndmask_b32_e32 v36, v36, v46, vcc
	v_pk_mul_f32 v[40:41], v[40:41], s[60:61] op_sel_hi:[1,0]
	v_pk_mul_f32 v[34:35], v[34:35], s[60:61] op_sel_hi:[1,0]
	v_cvt_pk_bf16_f32 v38, v38, v39
	v_cvt_pk_bf16_f32 v39, v40, v41
	v_pk_mul_f32 v[36:37], v[36:37], s[60:61] op_sel_hi:[1,0]
	v_cvt_pk_bf16_f32 v34, v34, v35
	s_nop 0
	v_cvt_pk_bf16_f32 v35, v36, v37
	global_store_dwordx2 v[54:55], v[38:39], off offset:256
	global_store_dwordx2 v[54:55], v[34:35], off offset:288
	v_add_u32_e32 v38, 0xa0, v136
	v_mad_i64_i32 v[38:39], s[28:29], v38, s59, v[122:123]
	v_lshl_add_u64 v[38:39], v[38:39], 0, s[26:27]
	v_lshl_add_u64 v[38:39], v[38:39], 0, v[124:125]
	s_waitcnt vmcnt(26)
	v_pk_mul_f32 v[46:47], v[26:27], v[224:225]
	v_pk_mul_f32 v[48:49], v[32:33], v[226:227]
	v_pk_mul_f32 v[50:51], v[30:31], v[224:225]
	v_pk_mul_f32 v[44:45], v[28:29], v[226:227]
	v_pk_fma_f32 v[46:47], v[30:31], v[220:221], v[46:47] neg_lo:[0,0,1] neg_hi:[0,0,1]
	v_pk_fma_f32 v[48:49], v[28:29], v[222:223], v[48:49]
	v_pk_fma_f32 v[50:51], v[26:27], v[220:221], v[50:51]
	v_pk_fma_f32 v[44:45], v[32:33], v[222:223], v[44:45] neg_lo:[0,0,1] neg_hi:[0,0,1]
	v_cndmask_b32_e64 v31, v31, v47, s[0:1]
	v_cndmask_b32_e64 v30, v30, v46, s[0:1]
	v_cndmask_b32_e64 v29, v29, v49, s[0:1]
	v_cndmask_b32_e64 v28, v28, v48, s[0:1]
	v_cndmask_b32_e64 v27, v27, v51, s[0:1]
	v_cndmask_b32_e64 v26, v26, v50, s[0:1]
	v_cndmask_b32_e64 v33, v33, v45, s[0:1]
	v_cndmask_b32_e64 v32, v32, v44, s[0:1]
	v_pk_mul_f32 v[30:31], v[30:31], s[60:61] op_sel_hi:[1,0]
	v_pk_mul_f32 v[28:29], v[28:29], s[60:61] op_sel_hi:[1,0]
	v_pk_mul_f32 v[26:27], v[26:27], s[60:61] op_sel_hi:[1,0]
	v_pk_mul_f32 v[32:33], v[32:33], s[60:61] op_sel_hi:[1,0]
	v_cvt_pk_bf16_f32 v30, v30, v31
	v_cvt_pk_bf16_f32 v26, v26, v27
	v_cvt_pk_bf16_f32 v27, v28, v29
	v_pk_mul_f32 v[28:29], v[18:19], v[224:225]
	v_cvt_pk_bf16_f32 v31, v32, v33
	global_store_dwordx2 v[38:39], v[30:31], off
	global_store_dwordx2 v[38:39], v[26:27], off offset:32
	v_pk_mul_f32 v[26:27], v[20:21], v[226:227]
	v_pk_fma_f32 v[28:29], v[22:23], v[220:221], v[28:29] neg_lo:[0,0,1] neg_hi:[0,0,1]
	v_pk_mul_f32 v[32:33], v[22:23], v[224:225]
	v_pk_fma_f32 v[26:27], v[24:25], v[222:223], v[26:27] neg_lo:[0,0,1] neg_hi:[0,0,1]
	v_pk_mul_f32 v[30:31], v[24:25], v[226:227]
	v_pk_fma_f32 v[32:33], v[18:19], v[220:221], v[32:33]
	v_cndmask_b32_e32 v23, v23, v29, vcc
	v_cndmask_b32_e32 v22, v22, v28, vcc
	v_pk_fma_f32 v[30:31], v[20:21], v[222:223], v[30:31]
	v_cndmask_b32_e32 v25, v25, v27, vcc
	v_cndmask_b32_e32 v24, v24, v26, vcc
	v_cndmask_b32_e32 v19, v19, v33, vcc
	v_cndmask_b32_e32 v18, v18, v32, vcc
	v_pk_mul_f32 v[22:23], v[22:23], s[60:61] op_sel_hi:[1,0]
	v_cndmask_b32_e32 v21, v21, v31, vcc
	v_cndmask_b32_e32 v20, v20, v30, vcc
	v_pk_mul_f32 v[24:25], v[24:25], s[60:61] op_sel_hi:[1,0]
	v_pk_mul_f32 v[18:19], v[18:19], s[60:61] op_sel_hi:[1,0]
	v_cvt_pk_bf16_f32 v22, v22, v23
	v_cvt_pk_bf16_f32 v23, v24, v25
	v_pk_mul_f32 v[20:21], v[20:21], s[60:61] op_sel_hi:[1,0]
	v_cvt_pk_bf16_f32 v18, v18, v19
	s_nop 0
	v_cvt_pk_bf16_f32 v19, v20, v21
	global_store_dwordx2 v[38:39], v[22:23], off offset:256
	global_store_dwordx2 v[38:39], v[18:19], off offset:288
	v_add_u32_e32 v22, 0xb0, v136
	s_nop 0
	s_waitcnt vmcnt(28)
	v_pk_mul_f32 v[28:29], v[12:13], v[248:249]
	v_pk_mul_f32 v[30:31], v[10:11], v[246:247]
	v_pk_mul_f32 v[32:33], v[16:17], v[248:249]
	v_pk_mul_f32 v[34:35], v[14:15], v[246:247]
	v_pk_fma_f32 v[28:29], v[16:17], v[244:245], v[28:29] neg_lo:[0,0,1] neg_hi:[0,0,1]
	v_pk_fma_f32 v[30:31], v[14:15], v[242:243], v[30:31] neg_lo:[0,0,1] neg_hi:[0,0,1]
	v_pk_fma_f32 v[32:33], v[12:13], v[244:245], v[32:33]
	v_pk_fma_f32 v[34:35], v[10:11], v[242:243], v[34:35]
	v_cndmask_b32_e64 v17, v17, v29, s[0:1]
	v_cndmask_b32_e64 v16, v16, v28, s[0:1]
	v_cndmask_b32_e64 v15, v15, v31, s[0:1]
	v_cndmask_b32_e64 v14, v14, v30, s[0:1]
	v_cndmask_b32_e64 v13, v13, v33, s[0:1]
	v_cndmask_b32_e64 v12, v12, v32, s[0:1]
	v_cndmask_b32_e64 v11, v11, v35, s[0:1]
	v_cndmask_b32_e64 v10, v10, v34, s[0:1]
	v_mad_i64_i32 v[22:23], s[0:1], v22, s59, v[122:123]
	v_pk_mul_f32 v[14:15], v[14:15], s[60:61] op_sel_hi:[1,0]
	v_pk_mul_f32 v[12:13], v[12:13], s[60:61] op_sel_hi:[1,0]
	v_pk_mul_f32 v[10:11], v[10:11], s[60:61] op_sel_hi:[1,0]
	v_lshl_add_u64 v[22:23], v[22:23], 0, s[26:27]
	v_pk_mul_f32 v[16:17], v[16:17], s[60:61] op_sel_hi:[1,0]
	v_lshl_add_u64 v[22:23], v[22:23], 0, v[124:125]
	v_cvt_pk_bf16_f32 v14, v14, v15
	v_cvt_pk_bf16_f32 v15, v16, v17
	v_cvt_pk_bf16_f32 v10, v10, v11
	v_cvt_pk_bf16_f32 v11, v12, v13
	v_pk_mul_f32 v[12:13], v[2:3], v[246:247]
	global_store_dwordx2 v[22:23], v[14:15], off
	global_store_dwordx2 v[22:23], v[10:11], off offset:32
	v_pk_mul_f32 v[10:11], v[4:5], v[248:249]
	v_pk_fma_f32 v[12:13], v[6:7], v[242:243], v[12:13] neg_lo:[0,0,1] neg_hi:[0,0,1]
	v_pk_mul_f32 v[16:17], v[6:7], v[246:247]
	v_pk_fma_f32 v[10:11], v[8:9], v[244:245], v[10:11] neg_lo:[0,0,1] neg_hi:[0,0,1]
	v_pk_mul_f32 v[14:15], v[8:9], v[248:249]
	v_pk_fma_f32 v[16:17], v[2:3], v[242:243], v[16:17]
	v_cndmask_b32_e32 v7, v7, v13, vcc
	v_cndmask_b32_e32 v6, v6, v12, vcc
	v_pk_fma_f32 v[14:15], v[4:5], v[244:245], v[14:15]
	v_cndmask_b32_e32 v9, v9, v11, vcc
	v_cndmask_b32_e32 v8, v8, v10, vcc
	v_cndmask_b32_e32 v3, v3, v17, vcc
	v_cndmask_b32_e32 v2, v2, v16, vcc
	v_pk_mul_f32 v[6:7], v[6:7], s[60:61] op_sel_hi:[1,0]
	v_cndmask_b32_e32 v5, v5, v15, vcc
	v_cndmask_b32_e32 v4, v4, v14, vcc
	v_pk_mul_f32 v[8:9], v[8:9], s[60:61] op_sel_hi:[1,0]
	v_pk_mul_f32 v[2:3], v[2:3], s[60:61] op_sel_hi:[1,0]
	v_cvt_pk_bf16_f32 v6, v6, v7
	v_cvt_pk_bf16_f32 v7, v8, v9
	v_pk_mul_f32 v[4:5], v[4:5], s[60:61] op_sel_hi:[1,0]
	v_cvt_pk_bf16_f32 v2, v2, v3
	s_mov_b64 s[0:1], -1
	v_cvt_pk_bf16_f32 v3, v4, v5
	global_store_dwordx2 v[22:23], v[6:7], off offset:256
	global_store_dwordx2 v[22:23], v[2:3], off offset:288
	s_and_b64 vcc, exec, s[6:7]
	s_cbranch_vccnz .LBB0_419
	s_andn2_b64 vcc, exec, s[10:11]
	s_cbranch_vccnz .LBB0_418
	s_barrier
	s_branch .LBB0_418

.LBB0_461:
	s_mov_b64 s[2:3], s[94:95]
	v_mov_b32_e32 v0, v1
	s_nop 0
	v_mbcnt_lo_u32_b32 v0, -1, v0
	v_mbcnt_hi_u32_b32 v0, -1, v0
	v_add_u32_e32 v0, s93, v0
	s_nop 0
	v_readfirstlane_b32 s0, v0
	s_ashr_i32 s0, s0, 6
	s_add_i32 s0, s0, s96
	s_cmp_lt_i32 s0, 0x10000
	s_cbranch_scc0 .LBB0_464
	s_load_dwordx2 s[4:5], s[2:3], 0xc0
	s_nop 0
	s_load_dwordx2 s[2:3], s[2:3], 0x48
	v_and_b32_e32 v4, 63, v0
	v_lshlrev_b32_e32 v0, 4, v4
	v_and_b32_e32 v5, 64, v197
	s_waitcnt lgkmcnt(0)
	v_lshl_add_u64 v[2:3], s[4:5], 0, v[0:1]
	s_mov_b64 s[4:5], 0x26000000
	v_lshl_add_u64 v[66:67], v[2:3], 0, s[4:5]
	v_add_u32_e32 v0, 64, v5
	v_xor_b32_e32 v2, 1, v197
	v_cmp_lt_i32_e32 vcc, v2, v0
	v_readlane_b32 s1, v254, 26
	s_lshl_b32 s62, s1, 10
	v_cndmask_b32_e32 v2, v197, v2, vcc
	v_lshlrev_b32_e32 v86, 2, v2
	v_xor_b32_e32 v2, 2, v197
	v_cmp_lt_i32_e32 vcc, v2, v0
	s_lshl_b64 s[4:5], s[62:63], 2
	s_add_u32 s2, s2, s4
	v_cndmask_b32_e32 v2, v197, v2, vcc
	v_lshlrev_b32_e32 v87, 2, v2
	v_xor_b32_e32 v2, 4, v197
	v_cmp_lt_i32_e32 vcc, v2, v0
	s_addc_u32 s3, s3, s5
	s_nop 0
	v_cndmask_b32_e32 v2, v197, v2, vcc
	v_lshlrev_b32_e32 v88, 2, v2
	v_xor_b32_e32 v2, 8, v197
	v_cmp_lt_i32_e32 vcc, v2, v0
	s_nop 1
	v_cndmask_b32_e32 v2, v197, v2, vcc
	v_lshlrev_b32_e32 v89, 2, v2
	v_xor_b32_e32 v2, 16, v197
	v_cmp_lt_i32_e32 vcc, v2, v0
	s_nop 1
	v_cndmask_b32_e32 v2, v197, v2, vcc
	v_lshlrev_b32_e32 v90, 2, v2
	v_xor_b32_e32 v2, 32, v197
	v_cmp_lt_i32_e32 vcc, v2, v0
	s_nop 1
	v_cndmask_b32_e32 v0, v197, v2, vcc
	v_lshlrev_b32_e32 v91, 2, v0
	v_lshlrev_b32_e32 v0, 5, v4
	v_lshl_add_u64 v[68:69], s[2:3], 0, v[0:1]
	global_load_dwordx4 v[204:207], v[68:69], off offset:16
	global_load_dwordx4 v[208:211], v[68:69], off
	global_load_dwordx4 v[212:215], v[68:69], off offset:2064
	global_load_dwordx4 v[216:219], v[68:69], off offset:2048
.LBB0_463:
	s_ashr_i32 s1, s0, 31
	s_lshl_b64 s[2:3], s[0:1], 12
	v_lshl_add_u64 v[84:85], v[66:67], 0, s[2:3]
	global_load_dwordx4 v[62:65], v[84:85], off
	global_load_dwordx4 v[58:61], v[84:85], off offset:1024
	s_add_i32 s2, s0, s97
	s_ashr_i32 s3, s2, 31
	s_lshl_b64 s[4:5], s[2:3], 12
	v_lshl_add_u64 v[82:83], v[66:67], 0, s[4:5]
	global_load_dwordx4 v[46:49], v[82:83], off
	global_load_dwordx4 v[42:45], v[82:83], off offset:1024
	s_add_i32 s1, s2, s97
	s_add_i32 s2, s88, s0
	s_ashr_i32 s3, s2, 31
	s_lshl_b64 s[2:3], s[2:3], 12
	v_lshl_add_u64 v[80:81], v[66:67], 0, s[2:3]
	global_load_dwordx4 v[38:41], v[80:81], off
	global_load_dwordx4 v[34:37], v[80:81], off offset:1024
	s_add_i32 s2, s75, s0
	s_ashr_i32 s3, s2, 31
	s_lshl_b64 s[2:3], s[2:3], 12
	v_lshl_add_u64 v[78:79], v[66:67], 0, s[2:3]
	global_load_dwordx4 v[30:33], v[78:79], off
	global_load_dwordx4 v[26:29], v[78:79], off offset:1024
	s_add_i32 s2, s89, s0
	s_ashr_i32 s3, s2, 31
	s_lshl_b64 s[2:3], s[2:3], 12
	v_lshl_add_u64 v[76:77], v[66:67], 0, s[2:3]
	global_load_dwordx4 v[22:25], v[76:77], off
	global_load_dwordx4 v[18:21], v[76:77], off offset:1024
	s_add_i32 s2, s77, s0
	s_ashr_i32 s3, s2, 31
	s_lshl_b64 s[2:3], s[2:3], 12
	v_lshl_add_u64 v[74:75], v[66:67], 0, s[2:3]
	global_load_dwordx4 v[14:17], v[74:75], off
	global_load_dwordx4 v[10:13], v[74:75], off offset:1024
	s_add_i32 s2, s78, s0
	s_ashr_i32 s3, s2, 31
	s_lshl_b64 s[2:3], s[2:3], 12
	v_lshl_add_u64 v[72:73], v[66:67], 0, s[2:3]
	global_load_dwordx4 v[6:9], v[72:73], off
	global_load_dwordx4 v[2:5], v[72:73], off offset:1024
	s_add_i32 s1, s1, s97
	s_add_i32 s1, s1, s97
	s_add_i32 s1, s1, s97
	s_add_i32 s1, s1, s97
	s_add_i32 s0, s79, s0
	s_add_i32 s2, s1, s97
	s_ashr_i32 s1, s0, 31
	s_lshl_b64 s[0:1], s[0:1], 12
	v_lshl_add_u64 v[70:71], v[66:67], 0, s[0:1]
	global_load_dwordx4 v[54:57], v[70:71], off
	global_load_dwordx4 v[50:53], v[70:71], off offset:1024
	s_waitcnt vmcnt(0)
	v_and_b32_e32 v152, 0xffff0000, v62
	v_and_b32_e32 v156, 0xffff0000, v63
	v_lshlrev_b32_e32 v154, 16, v62
	v_lshlrev_b32_e32 v145, 16, v58
	v_and_b32_e32 v144, 0xffff0000, v58
	v_mul_f32_e32 v0, v152, v152
	v_lshlrev_b32_e32 v157, 16, v63
	v_mul_f32_e32 v58, v156, v156
	v_fmac_f32_e32 v0, v154, v154
	v_lshlrev_b32_e32 v155, 16, v59
	v_fmac_f32_e32 v58, v157, v157
	v_fmac_f32_e32 v0, v145, v145
	v_and_b32_e32 v153, 0xffff0000, v59
	v_fmac_f32_e32 v58, v155, v155
	v_fmac_f32_e32 v0, v144, v144
	v_fmac_f32_e32 v58, v153, v153
	v_and_b32_e32 v170, 0xffff0000, v64
	v_add_f32_e32 v0, v0, v58
	v_lshlrev_b32_e32 v171, 16, v64
	v_mul_f32_e32 v58, v170, v170
	v_lshlrev_b32_e32 v159, 16, v60
	v_fmac_f32_e32 v58, v171, v171
	v_and_b32_e32 v158, 0xffff0000, v60
	v_fmac_f32_e32 v58, v159, v159
	v_fmac_f32_e32 v58, v158, v158
	v_and_b32_e32 v180, 0xffff0000, v65
	v_add_f32_e32 v0, v58, v0
	v_lshlrev_b32_e32 v182, 16, v65
	v_mul_f32_e32 v58, v180, v180
	v_lshlrev_b32_e32 v174, 16, v61
	v_fmac_f32_e32 v58, v182, v182
	v_and_b32_e32 v172, 0xffff0000, v61
	v_fmac_f32_e32 v58, v174, v174
	v_fmac_f32_e32 v58, v172, v172
	v_and_b32_e32 v150, 0xffff0000, v46
	v_and_b32_e32 v176, 0xffff0000, v47
	v_add_f32_e32 v164, v58, v0
	v_lshlrev_b32_e32 v151, 16, v46
	v_lshlrev_b32_e32 v142, 16, v42
	v_and_b32_e32 v160, 0xffff0000, v42
	v_mul_f32_e32 v0, v150, v150
	v_lshlrev_b32_e32 v177, 16, v47
	v_mul_f32_e32 v42, v176, v176
	v_fmac_f32_e32 v0, v151, v151
	v_lshlrev_b32_e32 v163, 16, v43
	v_fmac_f32_e32 v42, v177, v177
	v_fmac_f32_e32 v0, v142, v142
	v_and_b32_e32 v161, 0xffff0000, v43
	v_fmac_f32_e32 v42, v163, v163
	v_fmac_f32_e32 v0, v160, v160
	v_fmac_f32_e32 v42, v161, v161
	v_and_b32_e32 v178, 0xffff0000, v48
	v_add_f32_e32 v0, v0, v42
	v_lshlrev_b32_e32 v179, 16, v48
	v_mul_f32_e32 v42, v178, v178
	v_lshlrev_b32_e32 v169, 16, v44
	v_fmac_f32_e32 v42, v179, v179
	v_and_b32_e32 v168, 0xffff0000, v44
	v_fmac_f32_e32 v42, v169, v169
	v_fmac_f32_e32 v42, v168, v168
	v_and_b32_e32 v181, 0xffff0000, v49
	v_add_f32_e32 v0, v42, v0
	v_lshlrev_b32_e32 v183, 16, v49
	v_mul_f32_e32 v42, v181, v181
	v_lshlrev_b32_e32 v175, 16, v45
	v_fmac_f32_e32 v42, v183, v183
	v_and_b32_e32 v173, 0xffff0000, v45
	v_fmac_f32_e32 v42, v175, v175
	v_fmac_f32_e32 v42, v173, v173
	v_and_b32_e32 v139, 0xffff0000, v38
	v_and_b32_e32 v141, 0xffff0000, v39
	v_add_f32_e32 v165, v42, v0
	v_lshlrev_b32_e32 v140, 16, v38
	v_lshlrev_b32_e32 v132, 16, v34
	v_and_b32_e32 v131, 0xffff0000, v34
	v_mul_f32_e32 v0, v139, v139
	v_lshlrev_b32_e32 v143, 16, v39
	v_mul_f32_e32 v34, v141, v141
	v_fmac_f32_e32 v0, v140, v140
	v_lshlrev_b32_e32 v134, 16, v35
	v_fmac_f32_e32 v34, v143, v143
	v_fmac_f32_e32 v0, v132, v132
	v_and_b32_e32 v133, 0xffff0000, v35
	v_fmac_f32_e32 v34, v134, v134
	v_fmac_f32_e32 v0, v131, v131
	v_fmac_f32_e32 v34, v133, v133
	v_and_b32_e32 v146, 0xffff0000, v40
	v_add_f32_e32 v0, v0, v34
	v_lshlrev_b32_e32 v147, 16, v40
	v_mul_f32_e32 v34, v146, v146
	v_lshlrev_b32_e32 v136, 16, v36
	v_fmac_f32_e32 v34, v147, v147
	v_and_b32_e32 v135, 0xffff0000, v36
	v_fmac_f32_e32 v34, v136, v136
	v_fmac_f32_e32 v34, v135, v135
	v_and_b32_e32 v148, 0xffff0000, v41
	v_add_f32_e32 v0, v34, v0
	v_lshlrev_b32_e32 v149, 16, v41
	v_mul_f32_e32 v34, v148, v148
	v_lshlrev_b32_e32 v138, 16, v37
	v_fmac_f32_e32 v34, v149, v149
	v_and_b32_e32 v137, 0xffff0000, v37
	v_fmac_f32_e32 v34, v138, v138
	v_fmac_f32_e32 v34, v137, v137
	v_and_b32_e32 v123, 0xffff0000, v30
	v_and_b32_e32 v125, 0xffff0000, v31
	v_add_f32_e32 v166, v34, v0
	v_lshlrev_b32_e32 v124, 16, v30
	v_lshlrev_b32_e32 v116, 16, v26
	v_and_b32_e32 v115, 0xffff0000, v26
	v_mul_f32_e32 v0, v123, v123
	v_lshlrev_b32_e32 v126, 16, v31
	v_mul_f32_e32 v26, v125, v125
	v_fmac_f32_e32 v0, v124, v124
	v_lshlrev_b32_e32 v118, 16, v27
	v_fmac_f32_e32 v26, v126, v126
	v_fmac_f32_e32 v0, v116, v116
	v_and_b32_e32 v117, 0xffff0000, v27
	v_fmac_f32_e32 v26, v118, v118
	v_fmac_f32_e32 v0, v115, v115
	v_fmac_f32_e32 v26, v117, v117
	v_and_b32_e32 v127, 0xffff0000, v32
	v_add_f32_e32 v0, v0, v26
	v_lshlrev_b32_e32 v128, 16, v32
	v_mul_f32_e32 v26, v127, v127
	v_lshlrev_b32_e32 v120, 16, v28
	v_fmac_f32_e32 v26, v128, v128
	v_and_b32_e32 v119, 0xffff0000, v28
	v_fmac_f32_e32 v26, v120, v120
	v_fmac_f32_e32 v26, v119, v119
	v_and_b32_e32 v129, 0xffff0000, v33
	v_add_f32_e32 v0, v26, v0
	v_lshlrev_b32_e32 v130, 16, v33
	v_mul_f32_e32 v26, v129, v129
	v_lshlrev_b32_e32 v122, 16, v29
	v_fmac_f32_e32 v26, v130, v130
	v_and_b32_e32 v121, 0xffff0000, v29
	v_fmac_f32_e32 v26, v122, v122
	v_fmac_f32_e32 v26, v121, v121
	v_and_b32_e32 v107, 0xffff0000, v22
	v_and_b32_e32 v109, 0xffff0000, v23
	v_add_f32_e32 v167, v26, v0
	v_lshlrev_b32_e32 v108, 16, v22
	v_lshlrev_b32_e32 v100, 16, v18
	v_and_b32_e32 v99, 0xffff0000, v18
	v_mul_f32_e32 v0, v107, v107
	v_lshlrev_b32_e32 v110, 16, v23
	v_mul_f32_e32 v18, v109, v109
	v_fmac_f32_e32 v0, v108, v108
	v_lshlrev_b32_e32 v102, 16, v19
	v_fmac_f32_e32 v18, v110, v110
	v_fmac_f32_e32 v0, v100, v100
	v_and_b32_e32 v101, 0xffff0000, v19
	v_fmac_f32_e32 v18, v102, v102
	v_fmac_f32_e32 v0, v99, v99
	v_fmac_f32_e32 v18, v101, v101
	v_and_b32_e32 v111, 0xffff0000, v24
	v_add_f32_e32 v0, v0, v18
	v_lshlrev_b32_e32 v112, 16, v24
	v_mul_f32_e32 v18, v111, v111
	v_lshlrev_b32_e32 v104, 16, v20
	v_fmac_f32_e32 v18, v112, v112
	v_and_b32_e32 v103, 0xffff0000, v20
	v_fmac_f32_e32 v18, v104, v104
	v_fmac_f32_e32 v18, v103, v103
	v_and_b32_e32 v113, 0xffff0000, v25
	v_add_f32_e32 v0, v18, v0
	v_lshlrev_b32_e32 v114, 16, v25
	v_mul_f32_e32 v18, v113, v113
	v_lshlrev_b32_e32 v106, 16, v21
	v_fmac_f32_e32 v18, v114, v114
	v_and_b32_e32 v105, 0xffff0000, v21
	v_fmac_f32_e32 v18, v106, v106
	v_fmac_f32_e32 v18, v105, v105
	v_and_b32_e32 v65, 0xffff0000, v14
	v_and_b32_e32 v93, 0xffff0000, v15
	v_add_f32_e32 v184, v18, v0
	v_lshlrev_b32_e32 v92, 16, v14
	v_lshlrev_b32_e32 v58, 16, v10
	v_and_b32_e32 v49, 0xffff0000, v10
	v_mul_f32_e32 v0, v65, v65
	v_lshlrev_b32_e32 v94, 16, v15
	v_mul_f32_e32 v10, v93, v93
	v_fmac_f32_e32 v0, v92, v92
	v_lshlrev_b32_e32 v60, 16, v11
	v_fmac_f32_e32 v10, v94, v94
	v_fmac_f32_e32 v0, v58, v58
	v_and_b32_e32 v59, 0xffff0000, v11
	v_fmac_f32_e32 v10, v60, v60
	v_fmac_f32_e32 v0, v49, v49
	v_fmac_f32_e32 v10, v59, v59
	v_and_b32_e32 v95, 0xffff0000, v16
	v_add_f32_e32 v0, v0, v10
	v_lshlrev_b32_e32 v96, 16, v16
	v_mul_f32_e32 v10, v95, v95
	v_lshlrev_b32_e32 v62, 16, v12
	v_fmac_f32_e32 v10, v96, v96
	v_and_b32_e32 v61, 0xffff0000, v12
	v_fmac_f32_e32 v10, v62, v62
	v_fmac_f32_e32 v10, v61, v61
	v_and_b32_e32 v97, 0xffff0000, v17
	v_add_f32_e32 v0, v10, v0
	v_lshlrev_b32_e32 v98, 16, v17
	v_mul_f32_e32 v10, v97, v97
	v_lshlrev_b32_e32 v64, 16, v13
	v_fmac_f32_e32 v10, v98, v98
	v_and_b32_e32 v63, 0xffff0000, v13
	v_fmac_f32_e32 v10, v64, v64
	v_fmac_f32_e32 v10, v63, v63
	v_and_b32_e32 v41, 0xffff0000, v6
	v_and_b32_e32 v43, 0xffff0000, v7
	v_add_f32_e32 v10, v10, v0
	v_lshlrev_b32_e32 v42, 16, v6
	v_lshlrev_b32_e32 v34, 16, v2
	v_and_b32_e32 v33, 0xffff0000, v2
	v_mul_f32_e32 v0, v41, v41
	v_lshlrev_b32_e32 v44, 16, v7
	v_mul_f32_e32 v2, v43, v43
	v_fmac_f32_e32 v0, v42, v42
	v_lshlrev_b32_e32 v36, 16, v3
	v_fmac_f32_e32 v2, v44, v44
	v_fmac_f32_e32 v0, v34, v34
	v_and_b32_e32 v35, 0xffff0000, v3
	v_fmac_f32_e32 v2, v36, v36
	v_fmac_f32_e32 v0, v33, v33
	v_fmac_f32_e32 v2, v35, v35
	v_and_b32_e32 v45, 0xffff0000, v8
	v_add_f32_e32 v0, v0, v2
	v_lshlrev_b32_e32 v46, 16, v8
	v_mul_f32_e32 v2, v45, v45
	v_lshlrev_b32_e32 v38, 16, v4
	v_fmac_f32_e32 v2, v46, v46
	v_and_b32_e32 v37, 0xffff0000, v4
	v_fmac_f32_e32 v2, v38, v38
	v_fmac_f32_e32 v2, v37, v37
	v_and_b32_e32 v47, 0xffff0000, v9
	v_add_f32_e32 v0, v2, v0
	v_lshlrev_b32_e32 v48, 16, v9
	v_mul_f32_e32 v2, v47, v47
	v_lshlrev_b32_e32 v40, 16, v5
	v_fmac_f32_e32 v2, v48, v48
	v_and_b32_e32 v25, 0xffff0000, v54
	v_and_b32_e32 v27, 0xffff0000, v55
	v_and_b32_e32 v39, 0xffff0000, v5
	v_fmac_f32_e32 v2, v40, v40
	v_lshlrev_b32_e32 v26, 16, v54
	v_mul_f32_e32 v3, v25, v25
	v_lshlrev_b32_e32 v28, 16, v55
	v_mul_f32_e32 v4, v27, v27
	v_fmac_f32_e32 v2, v39, v39
	v_lshlrev_b32_e32 v18, 16, v50
	v_fmac_f32_e32 v3, v26, v26
	v_lshlrev_b32_e32 v20, 16, v51
	v_fmac_f32_e32 v4, v28, v28
	v_add_f32_e32 v2, v2, v0
	v_and_b32_e32 v0, 0xffff0000, v50
	v_fmac_f32_e32 v3, v18, v18
	v_and_b32_e32 v19, 0xffff0000, v51
	v_fmac_f32_e32 v4, v20, v20
	v_fmac_f32_e32 v3, v0, v0
	v_fmac_f32_e32 v4, v19, v19
	v_and_b32_e32 v29, 0xffff0000, v56
	ds_bpermute_b32 v9, v86, v10
	v_add_f32_e32 v3, v3, v4
	v_lshlrev_b32_e32 v30, 16, v56
	v_mul_f32_e32 v4, v29, v29
	v_lshlrev_b32_e32 v22, 16, v52
	v_fmac_f32_e32 v4, v30, v30
	v_and_b32_e32 v21, 0xffff0000, v52
	v_fmac_f32_e32 v4, v22, v22
	v_fmac_f32_e32 v4, v21, v21
	v_and_b32_e32 v31, 0xffff0000, v57
	v_add_f32_e32 v3, v4, v3
	v_lshlrev_b32_e32 v32, 16, v57
	v_mul_f32_e32 v4, v31, v31
	s_waitcnt lgkmcnt(0)
	v_add_f32_e32 v9, v10, v9
	ds_bpermute_b32 v10, v86, v2
	v_lshlrev_b32_e32 v24, 16, v53
	v_fmac_f32_e32 v4, v32, v32
	v_and_b32_e32 v23, 0xffff0000, v53
	v_fmac_f32_e32 v4, v24, v24
	v_fmac_f32_e32 v4, v23, v23
	v_add_f32_e32 v3, v4, v3
	ds_bpermute_b32 v4, v86, v164
	s_waitcnt lgkmcnt(1)
	v_add_f32_e32 v2, v2, v10
	ds_bpermute_b32 v10, v86, v3
	ds_bpermute_b32 v5, v86, v165
	ds_bpermute_b32 v6, v86, v166
	s_waitcnt lgkmcnt(3)
	v_add_f32_e32 v4, v164, v4
	ds_bpermute_b32 v7, v86, v167
	s_waitcnt lgkmcnt(3)
	v_add_f32_e32 v3, v3, v10
	ds_bpermute_b32 v10, v87, v4
	s_waitcnt lgkmcnt(3)
	v_add_f32_e32 v5, v165, v5
	s_waitcnt lgkmcnt(2)
	v_add_f32_e32 v6, v166, v6
	s_waitcnt lgkmcnt(1)
	v_add_f32_e32 v7, v167, v7
	ds_bpermute_b32 v8, v86, v184
	s_waitcnt lgkmcnt(1)
	v_add_f32_e32 v4, v4, v10
	ds_bpermute_b32 v10, v87, v5
	s_waitcnt lgkmcnt(1)
	v_add_f32_e32 v8, v184, v8
	s_waitcnt lgkmcnt(0)
	v_add_f32_e32 v5, v5, v10
	ds_bpermute_b32 v10, v87, v6
	ds_bpermute_b32 v200, v87, v7
	ds_bpermute_b32 v201, v87, v8
	ds_bpermute_b32 v202, v87, v9
	ds_bpermute_b32 v196, v87, v2
	ds_bpermute_b32 v162, v87, v3
	s_waitcnt lgkmcnt(0)
	v_add_f32_e32 v6, v6, v10
	v_add_f32_e32 v7, v7, v200
	v_add_f32_e32 v8, v8, v201
	v_add_f32_e32 v9, v9, v202
	v_add_f32_e32 v2, v2, v196
	v_add_f32_e32 v3, v3, v162
	ds_bpermute_b32 v10, v88, v4
	ds_bpermute_b32 v200, v88, v5
	ds_bpermute_b32 v201, v88, v6
	ds_bpermute_b32 v202, v88, v7
	ds_bpermute_b32 v196, v88, v8
	ds_bpermute_b32 v162, v88, v9
	ds_bpermute_b32 v250, v88, v2
	ds_bpermute_b32 v251, v88, v3
	s_waitcnt lgkmcnt(0)
	v_add_f32_e32 v4, v4, v10
	v_add_f32_e32 v5, v5, v200
	v_add_f32_e32 v6, v6, v201
	v_add_f32_e32 v7, v7, v202
	v_add_f32_e32 v8, v8, v196
	v_add_f32_e32 v9, v9, v162
	v_add_f32_e32 v2, v2, v250
	v_add_f32_e32 v3, v3, v251
	ds_bpermute_b32 v10, v89, v4
	ds_bpermute_b32 v200, v89, v5
	ds_bpermute_b32 v201, v89, v6
	ds_bpermute_b32 v202, v89, v7
	ds_bpermute_b32 v196, v89, v8
	ds_bpermute_b32 v162, v89, v9
	ds_bpermute_b32 v250, v89, v2
	ds_bpermute_b32 v251, v89, v3
	s_waitcnt lgkmcnt(0)
	v_add_f32_e32 v4, v4, v10
	v_add_f32_e32 v5, v5, v200
	v_add_f32_e32 v6, v6, v201
	v_add_f32_e32 v7, v7, v202
	v_add_f32_e32 v8, v8, v196
	v_add_f32_e32 v9, v9, v162
	v_add_f32_e32 v2, v2, v250
	v_add_f32_e32 v3, v3, v251
	ds_bpermute_b32 v10, v90, v4
	ds_bpermute_b32 v200, v90, v5
	ds_bpermute_b32 v201, v90, v6
	ds_bpermute_b32 v202, v90, v7
	ds_bpermute_b32 v196, v90, v8
	ds_bpermute_b32 v162, v90, v9
	ds_bpermute_b32 v250, v90, v2
	ds_bpermute_b32 v251, v90, v3
	s_waitcnt lgkmcnt(0)
	v_add_f32_e32 v4, v4, v10
	v_add_f32_e32 v5, v5, v200
	v_add_f32_e32 v6, v6, v201
	v_add_f32_e32 v7, v7, v202
	v_add_f32_e32 v8, v8, v196
	v_add_f32_e32 v9, v9, v162
	v_add_f32_e32 v2, v2, v250
	v_add_f32_e32 v3, v3, v251
	ds_bpermute_b32 v220, v91, v4
	ds_bpermute_b32 v221, v91, v5
	ds_bpermute_b32 v222, v91, v6
	ds_bpermute_b32 v223, v91, v7
	ds_bpermute_b32 v224, v91, v8
	ds_bpermute_b32 v225, v91, v9
	ds_bpermute_b32 v226, v91, v2
	ds_bpermute_b32 v227, v91, v3
	s_waitcnt lgkmcnt(0)
	v_add_f32_e32 v56, v4, v220
	v_add_f32_e32 v57, v5, v221
	v_add_f32_e32 v55, v6, v222
	v_add_f32_e32 v54, v7, v223
	v_add_f32_e32 v53, v8, v224
	v_add_f32_e32 v52, v9, v225
	v_add_f32_e32 v51, v2, v226
	v_add_f32_e32 v50, v3, v227
	s_nop 0
	s_nop 0
	s_nop 0
	s_nop 0
	v_fmamk_f32 v56, v56, 0x3a800000, v194
	v_cmp_gt_f32_e32 vcc, s61, v56
	v_mul_f32_e32 v164, 0x4f800000, v56
	s_nop 0
	s_nop 0
	s_nop 0
	v_cndmask_b32_e32 v56, v56, v164, vcc
	v_sqrt_f32_e32 v164, v56
	s_nop 0
	s_nop 0
	s_nop 0
	v_add_u32_e32 v165, -1, v164
	v_fma_f32 v166, -v165, v164, v56
	v_cmp_ge_f32_e64 s[0:1], 0, v166
	v_add_u32_e32 v166, 1, v164
	s_nop 0
	s_nop 0
	s_nop 0
	v_cndmask_b32_e64 v165, v164, v165, s[0:1]
	v_fma_f32 v164, -v166, v164, v56
	v_cmp_lt_f32_e64 s[0:1], 0, v164
	v_fmamk_f32 v55, v55, 0x3a800000, v194
	s_nop 0
	s_nop 0
	s_nop 0
	v_cndmask_b32_e64 v164, v165, v166, s[0:1]
	v_mul_f32_e32 v165, 0x37800000, v164
	v_cndmask_b32_e32 v164, v164, v165, vcc
	v_cmp_class_f32_e32 vcc, v56, v195
	s_nop 0
	s_nop 0
	s_nop 0
	v_cndmask_b32_e32 v56, v164, v56, vcc
	v_div_scale_f32 v164, s[0:1], v56, v56, 1.0
	v_rcp_f32_e32 v165, v164
	s_nop 0
	s_nop 0
	s_nop 0
	v_fmamk_f32 v54, v54, 0x3a800000, v194
	v_fma_f32 v166, -v164, v165, 1.0
	v_fmac_f32_e32 v165, v166, v165
	v_div_scale_f32 v166, vcc, 1.0, v56, 1.0
	s_nop 0
	s_nop 0
	s_nop 0
	s_nop 0
	s_nop 0
	s_nop 0
	v_mul_f32_e32 v167, v166, v165
	v_fma_f32 v184, -v164, v167, v166
	v_fmac_f32_e32 v167, v184, v165
	v_fma_f32 v164, -v164, v167, v166
	v_div_fmas_f32 v164, v164, v165, v167
	v_div_fixup_f32 v56, v164, v56, 1.0
	v_mul_f32_e32 v152, v56, v152
	v_mul_f32_e32 v154, v56, v154
	v_mul_f32_e32 v144, v56, v144
	v_mul_f32_e32 v145, v56, v145
	v_fmamk_f32 v53, v53, 0x3a800000, v194
	v_fmamk_f32 v52, v52, 0x3a800000, v194
	s_nop 0
	v_mul_f32_e32 v152, v152, v209
	v_mul_f32_e32 v154, v154, v208
	v_cvt_pk_bf16_f32 v164, v154, v152
	v_mul_f32_e32 v152, v56, v157
	v_mul_f32_e32 v152, v152, v210
	v_mul_f32_e32 v154, v56, v156
	v_mul_f32_e32 v154, v154, v211
	v_cvt_pk_bf16_f32 v165, v152, v154
	v_mul_f32_e32 v152, v56, v171
	v_mul_f32_e32 v152, v152, v204
	v_mul_f32_e32 v154, v56, v170
	v_mul_f32_e32 v154, v154, v205
	v_cvt_pk_bf16_f32 v166, v152, v154
	v_mul_f32_e32 v152, v56, v182
	v_mul_f32_e32 v152, v152, v206
	v_mul_f32_e32 v154, v56, v180
	s_nop 0
	v_mul_f32_e32 v144, v144, v217
	v_mul_f32_e32 v154, v154, v207
	v_cvt_pk_bf16_f32 v167, v152, v154
	v_mul_f32_e32 v145, v145, v216
	v_cvt_pk_bf16_f32 v152, v145, v144
	v_mul_f32_e32 v144, v56, v155
	v_mul_f32_e32 v144, v144, v218
	v_mul_f32_e32 v145, v56, v153
	v_mul_f32_e32 v145, v145, v219
	v_cvt_pk_bf16_f32 v153, v144, v145
	v_mul_f32_e32 v144, v56, v159
	v_mul_f32_e32 v144, v144, v212
	v_mul_f32_e32 v145, v56, v158
	v_mul_f32_e32 v145, v145, v213
	v_cvt_pk_bf16_f32 v154, v144, v145
	v_mul_f32_e32 v144, v56, v174
	v_mul_f32_e32 v56, v56, v172
	v_mul_f32_e32 v56, v56, v215
	v_mul_f32_e32 v144, v144, v214
	v_cvt_pk_bf16_f32 v155, v144, v56
	v_fmamk_f32 v56, v57, 0x3a800000, v194
	v_cmp_gt_f32_e32 vcc, s61, v56
	v_mul_f32_e32 v57, 0x4f800000, v56
	global_store_dwordx4 v[84:85], v[164:167], off
	global_store_dwordx4 v[84:85], v[152:155], off offset:1024
	v_cndmask_b32_e32 v56, v56, v57, vcc
	v_sqrt_f32_e32 v57, v56
	s_nop 0
	v_add_u32_e32 v84, -1, v57
	v_fma_f32 v85, -v84, v57, v56
	v_cmp_ge_f32_e64 s[0:1], 0, v85
	v_add_u32_e32 v85, 1, v57
	s_nop 0
	v_cndmask_b32_e64 v84, v57, v84, s[0:1]
	v_fma_f32 v57, -v85, v57, v56
	v_cmp_lt_f32_e64 s[0:1], 0, v57
	s_nop 1
	v_cndmask_b32_e64 v57, v84, v85, s[0:1]
	v_mul_f32_e32 v84, 0x37800000, v57
	v_cndmask_b32_e32 v57, v57, v84, vcc
	v_cmp_class_f32_e32 vcc, v56, v195
	s_nop 1
	v_cndmask_b32_e32 v56, v57, v56, vcc
	v_div_scale_f32 v57, s[0:1], v56, v56, 1.0
	v_rcp_f32_e32 v84, v57
	s_nop 0
	v_fma_f32 v85, -v57, v84, 1.0
	v_fmac_f32_e32 v84, v85, v84
	v_div_scale_f32 v85, vcc, 1.0, v56, 1.0
	v_mul_f32_e32 v144, v85, v84
	v_fma_f32 v145, -v57, v144, v85
	v_fmac_f32_e32 v144, v145, v84
	v_fma_f32 v57, -v57, v144, v85
	v_div_fmas_f32 v57, v57, v84, v144
	v_div_fixup_f32 v56, v57, v56, 1.0
	v_mul_f32_e32 v57, v56, v151
	v_mul_f32_e32 v57, v57, v208
	v_mul_f32_e32 v84, v56, v150
	v_mul_f32_e32 v84, v84, v209
	v_cvt_pk_bf16_f32 v150, v57, v84
	v_mul_f32_e32 v57, v56, v177
	v_mul_f32_e32 v57, v57, v210
	v_mul_f32_e32 v84, v56, v176
	v_mul_f32_e32 v84, v84, v211
	v_cvt_pk_bf16_f32 v151, v57, v84
	v_mul_f32_e32 v57, v56, v179
	v_mul_f32_e32 v57, v57, v204
	v_mul_f32_e32 v84, v56, v178
	v_mul_f32_e32 v84, v84, v205
	v_cvt_pk_bf16_f32 v152, v57, v84
	v_mul_f32_e32 v57, v56, v183
	v_mul_f32_e32 v57, v57, v206
	v_mul_f32_e32 v84, v56, v181
	v_mul_f32_e32 v84, v84, v207
	v_cvt_pk_bf16_f32 v153, v57, v84
	v_mul_f32_e32 v57, v56, v142
	v_mul_f32_e32 v57, v57, v216
	v_mul_f32_e32 v84, v56, v160
	v_mul_f32_e32 v84, v84, v217
	v_cvt_pk_bf16_f32 v154, v57, v84
	v_mul_f32_e32 v57, v56, v163
	v_mul_f32_e32 v57, v57, v218
	v_mul_f32_e32 v84, v56, v161
	v_mul_f32_e32 v84, v84, v219
	v_cvt_pk_bf16_f32 v155, v57, v84
	v_mul_f32_e32 v57, v56, v169
	v_mul_f32_e32 v57, v57, v212
	v_mul_f32_e32 v84, v56, v168
	v_mul_f32_e32 v84, v84, v213
	v_cvt_pk_bf16_f32 v156, v57, v84
	v_mul_f32_e32 v57, v56, v175
	v_mul_f32_e32 v56, v56, v173
	v_mul_f32_e32 v56, v56, v215
	v_mul_f32_e32 v57, v57, v214
	v_cvt_pk_bf16_f32 v157, v57, v56
	v_cmp_gt_f32_e32 vcc, s61, v55
	v_mul_f32_e32 v56, 0x4f800000, v55
	global_store_dwordx4 v[82:83], v[150:153], off
	global_store_dwordx4 v[82:83], v[154:157], off offset:1024
	v_cndmask_b32_e32 v55, v55, v56, vcc
	v_sqrt_f32_e32 v56, v55
	s_nop 0
	v_add_u32_e32 v57, -1, v56
	v_fma_f32 v82, -v57, v56, v55
	v_cmp_ge_f32_e64 s[0:1], 0, v82
	v_add_u32_e32 v82, 1, v56
	s_nop 0
	v_cndmask_b32_e64 v57, v56, v57, s[0:1]
	v_fma_f32 v56, -v82, v56, v55
	v_cmp_lt_f32_e64 s[0:1], 0, v56
	s_nop 1
	v_cndmask_b32_e64 v56, v57, v82, s[0:1]
	v_mul_f32_e32 v57, 0x37800000, v56
	v_cndmask_b32_e32 v56, v56, v57, vcc
	v_cmp_class_f32_e32 vcc, v55, v195
	s_nop 1
	v_cndmask_b32_e32 v55, v56, v55, vcc
	v_div_scale_f32 v56, s[0:1], v55, v55, 1.0
	v_rcp_f32_e32 v57, v56
	s_nop 0
	v_fma_f32 v82, -v56, v57, 1.0
	v_fmac_f32_e32 v57, v82, v57
	v_div_scale_f32 v82, vcc, 1.0, v55, 1.0
	v_mul_f32_e32 v83, v82, v57
	v_fma_f32 v84, -v56, v83, v82
	v_fmac_f32_e32 v83, v84, v57
	v_fma_f32 v56, -v56, v83, v82
	v_div_fmas_f32 v56, v56, v57, v83
	v_div_fixup_f32 v55, v56, v55, 1.0
	v_mul_f32_e32 v56, v55, v140
	v_mul_f32_e32 v56, v208, v56
	v_mul_f32_e32 v57, v55, v139
	v_mul_f32_e32 v57, v209, v57
	v_cvt_pk_bf16_f32 v82, v56, v57
	v_mul_f32_e32 v56, v55, v143
	v_mul_f32_e32 v56, v210, v56
	v_mul_f32_e32 v57, v55, v141
	v_mul_f32_e32 v57, v211, v57
	v_cvt_pk_bf16_f32 v83, v56, v57
	v_mul_f32_e32 v56, v55, v147
	v_mul_f32_e32 v56, v56, v204
	v_mul_f32_e32 v57, v55, v146
	v_mul_f32_e32 v57, v57, v205
	v_cvt_pk_bf16_f32 v84, v56, v57
	v_mul_f32_e32 v56, v55, v149
	v_mul_f32_e32 v56, v56, v206
	v_mul_f32_e32 v57, v55, v148
	v_mul_f32_e32 v57, v57, v207
	v_cvt_pk_bf16_f32 v85, v56, v57
	v_mul_f32_e32 v56, v55, v132
	v_mul_f32_e32 v56, v56, v216
	v_mul_f32_e32 v57, v55, v131
	v_mul_f32_e32 v57, v57, v217
	v_cvt_pk_bf16_f32 v132, v56, v57
	v_mul_f32_e32 v56, v55, v134
	v_mul_f32_e32 v56, v56, v218
	v_mul_f32_e32 v57, v55, v133
	v_mul_f32_e32 v57, v57, v219
	v_cvt_pk_bf16_f32 v133, v56, v57
	v_mul_f32_e32 v56, v55, v136
	v_mul_f32_e32 v56, v56, v212
	v_mul_f32_e32 v57, v55, v135
	v_mul_f32_e32 v57, v57, v213
	v_cvt_pk_bf16_f32 v134, v56, v57
	v_mul_f32_e32 v56, v55, v138
	v_mul_f32_e32 v55, v55, v137
	v_mul_f32_e32 v55, v55, v215
	v_mul_f32_e32 v56, v56, v214
	v_cvt_pk_bf16_f32 v135, v56, v55
	v_cmp_gt_f32_e32 vcc, s61, v54
	v_mul_f32_e32 v55, 0x4f800000, v54
	global_store_dwordx4 v[80:81], v[82:85], off
	global_store_dwordx4 v[80:81], v[132:135], off offset:1024
	v_cndmask_b32_e32 v54, v54, v55, vcc
	v_sqrt_f32_e32 v55, v54
	s_nop 0
	v_add_u32_e32 v56, -1, v55
	v_fma_f32 v57, -v56, v55, v54
	v_cmp_ge_f32_e64 s[0:1], 0, v57
	v_add_u32_e32 v57, 1, v55
	s_nop 0
	v_cndmask_b32_e64 v56, v55, v56, s[0:1]
	v_fma_f32 v55, -v57, v55, v54
	v_cmp_lt_f32_e64 s[0:1], 0, v55
	s_nop 1
	v_cndmask_b32_e64 v55, v56, v57, s[0:1]
	v_mul_f32_e32 v56, 0x37800000, v55
	v_cndmask_b32_e32 v55, v55, v56, vcc
	v_cmp_class_f32_e32 vcc, v54, v195
	s_nop 1
	v_cndmask_b32_e32 v54, v55, v54, vcc
	v_div_scale_f32 v55, s[0:1], v54, v54, 1.0
	v_rcp_f32_e32 v56, v55
	s_nop 0
	v_fma_f32 v57, -v55, v56, 1.0
	v_fmac_f32_e32 v56, v57, v56
	v_div_scale_f32 v57, vcc, 1.0, v54, 1.0
	v_mul_f32_e32 v80, v57, v56
	v_fma_f32 v81, -v55, v80, v57
	v_fmac_f32_e32 v80, v81, v56
	v_fma_f32 v55, -v55, v80, v57
	v_div_fmas_f32 v55, v55, v56, v80
	v_div_fixup_f32 v83, v55, v54, 1.0
	v_mul_f32_e32 v54, v83, v124
	v_mul_f32_e32 v55, v83, v123
	v_mul_f32_e32 v54, v208, v54
	v_mul_f32_e32 v55, v209, v55
	v_cvt_pk_bf16_f32 v54, v54, v55
	v_mul_f32_e32 v55, v83, v126
	v_mul_f32_e32 v56, v83, v125
	v_mul_f32_e32 v55, v210, v55
	v_mul_f32_e32 v56, v211, v56
	v_cvt_pk_bf16_f32 v55, v55, v56
	v_mul_f32_e32 v56, v83, v128
	v_mul_f32_e32 v57, v83, v127
	v_mul_f32_e32 v56, v204, v56
	v_mul_f32_e32 v57, v205, v57
	v_cvt_pk_bf16_f32 v56, v56, v57
	v_mul_f32_e32 v57, v83, v130
	v_mul_f32_e32 v80, v83, v129
	v_mul_f32_e32 v57, v206, v57
	v_mul_f32_e32 v80, v207, v80
	v_cvt_pk_bf16_f32 v57, v57, v80
	v_mul_f32_e32 v80, v83, v116
	v_mul_f32_e32 v81, v83, v115
	v_mul_f32_e32 v80, v80, v216
	v_mul_f32_e32 v81, v81, v217
	v_cvt_pk_bf16_f32 v80, v80, v81
	v_mul_f32_e32 v81, v83, v118
	v_mul_f32_e32 v82, v83, v117
	v_mul_f32_e32 v81, v81, v218
	v_mul_f32_e32 v82, v82, v219
	v_cvt_pk_bf16_f32 v81, v81, v82
	v_mul_f32_e32 v82, v83, v120
	v_mul_f32_e32 v84, v83, v119
	v_mul_f32_e32 v82, v82, v212
	v_mul_f32_e32 v84, v84, v213
	v_cvt_pk_bf16_f32 v82, v82, v84
	v_mul_f32_e32 v84, v83, v122
	v_mul_f32_e32 v83, v83, v121
	v_mul_f32_e32 v83, v83, v215
	v_mul_f32_e32 v84, v84, v214
	v_cvt_pk_bf16_f32 v83, v84, v83
	global_store_dwordx4 v[78:79], v[54:57], off
	global_store_dwordx4 v[78:79], v[80:83], off offset:1024
	v_cmp_gt_f32_e32 vcc, s61, v53
	v_mul_f32_e32 v54, 0x4f800000, v53
	s_nop 0
	v_cndmask_b32_e32 v53, v53, v54, vcc
	v_sqrt_f32_e32 v54, v53
	s_nop 0
	v_add_u32_e32 v55, -1, v54
	v_fma_f32 v56, -v55, v54, v53
	v_cmp_ge_f32_e64 s[0:1], 0, v56
	v_add_u32_e32 v56, 1, v54
	s_nop 0
	v_cndmask_b32_e64 v55, v54, v55, s[0:1]
	v_fma_f32 v54, -v56, v54, v53
	v_cmp_lt_f32_e64 s[0:1], 0, v54
	s_nop 1
	v_cndmask_b32_e64 v54, v55, v56, s[0:1]
	v_mul_f32_e32 v55, 0x37800000, v54
	v_cndmask_b32_e32 v54, v54, v55, vcc
	v_cmp_class_f32_e32 vcc, v53, v195
	s_nop 1
	v_cndmask_b32_e32 v53, v54, v53, vcc
	v_div_scale_f32 v54, s[0:1], v53, v53, 1.0
	v_rcp_f32_e32 v55, v54
	s_nop 0
	v_fma_f32 v56, -v54, v55, 1.0
	v_fmac_f32_e32 v55, v56, v55
	v_div_scale_f32 v56, vcc, 1.0, v53, 1.0
	v_mul_f32_e32 v57, v56, v55
	v_fma_f32 v78, -v54, v57, v56
	v_fmac_f32_e32 v57, v78, v55
	v_fma_f32 v54, -v54, v57, v56
	v_div_fmas_f32 v54, v54, v55, v57
	v_div_fixup_f32 v53, v54, v53, 1.0
	v_mul_f32_e32 v54, v53, v108
	v_mul_f32_e32 v55, v53, v107
	v_mul_f32_e32 v54, v208, v54
	v_mul_f32_e32 v55, v209, v55
	v_cvt_pk_bf16_f32 v54, v54, v55
	v_mul_f32_e32 v55, v53, v110
	v_mul_f32_e32 v56, v53, v109
	v_mul_f32_e32 v55, v210, v55
	v_mul_f32_e32 v56, v211, v56
	v_cvt_pk_bf16_f32 v55, v55, v56
	v_mul_f32_e32 v56, v53, v112
	v_mul_f32_e32 v57, v53, v111
	v_mul_f32_e32 v56, v204, v56
	v_mul_f32_e32 v57, v205, v57
	v_cvt_pk_bf16_f32 v56, v56, v57
	v_mul_f32_e32 v57, v53, v114
	v_mul_f32_e32 v78, v53, v113
	v_mul_f32_e32 v57, v206, v57
	v_mul_f32_e32 v78, v207, v78
	v_cvt_pk_bf16_f32 v57, v57, v78
	v_mul_f32_e32 v78, v53, v100
	v_mul_f32_e32 v79, v53, v99
	v_mul_f32_e32 v78, v216, v78
	v_mul_f32_e32 v79, v217, v79
	v_cvt_pk_bf16_f32 v78, v78, v79
	v_mul_f32_e32 v79, v53, v102
	v_mul_f32_e32 v80, v53, v101
	v_mul_f32_e32 v79, v218, v79
	v_mul_f32_e32 v80, v219, v80
	v_cvt_pk_bf16_f32 v79, v79, v80
	v_mul_f32_e32 v80, v53, v104
	v_mul_f32_e32 v81, v53, v103
	v_mul_f32_e32 v80, v80, v212
	v_mul_f32_e32 v81, v81, v213
	v_cvt_pk_bf16_f32 v80, v80, v81
	v_mul_f32_e32 v81, v53, v106
	v_mul_f32_e32 v53, v53, v105
	v_mul_f32_e32 v81, v81, v214
	v_mul_f32_e32 v53, v53, v215
	v_cvt_pk_bf16_f32 v81, v81, v53
	v_cmp_gt_f32_e32 vcc, s61, v52
	v_mul_f32_e32 v53, 0x4f800000, v52
	global_store_dwordx4 v[76:77], v[54:57], off
	global_store_dwordx4 v[76:77], v[78:81], off offset:1024
	v_cndmask_b32_e32 v52, v52, v53, vcc
	v_sqrt_f32_e32 v53, v52
	s_nop 0
	v_add_u32_e32 v54, -1, v53
	v_fma_f32 v55, -v54, v53, v52
	v_cmp_ge_f32_e64 s[0:1], 0, v55
	v_add_u32_e32 v55, 1, v53
	s_nop 0
	v_cndmask_b32_e64 v54, v53, v54, s[0:1]
	v_fma_f32 v53, -v55, v53, v52
	v_cmp_lt_f32_e64 s[0:1], 0, v53
	s_nop 1
	v_cndmask_b32_e64 v53, v54, v55, s[0:1]
	v_mul_f32_e32 v54, 0x37800000, v53
	v_cndmask_b32_e32 v53, v53, v54, vcc
	v_cmp_class_f32_e32 vcc, v52, v195
	s_nop 1
	v_cndmask_b32_e32 v52, v53, v52, vcc
	v_div_scale_f32 v53, s[0:1], v52, v52, 1.0
	v_rcp_f32_e32 v54, v53
	s_nop 0
	v_fma_f32 v55, -v53, v54, 1.0
	v_fmac_f32_e32 v54, v55, v54
	v_div_scale_f32 v55, vcc, 1.0, v52, 1.0
	v_mul_f32_e32 v56, v55, v54
	v_fma_f32 v57, -v53, v56, v55
	v_fmac_f32_e32 v56, v57, v54
	v_fma_f32 v53, -v53, v56, v55
	v_div_fmas_f32 v53, v53, v54, v56
	v_div_fixup_f32 v76, v53, v52, 1.0
	v_mul_f32_e32 v52, v76, v92
	v_mul_f32_e32 v53, v76, v65
	v_mul_f32_e32 v52, v208, v52
	v_mul_f32_e32 v53, v209, v53
	v_cvt_pk_bf16_f32 v52, v52, v53
	v_mul_f32_e32 v53, v76, v94
	v_mul_f32_e32 v54, v76, v93
	v_mul_f32_e32 v53, v210, v53
	v_mul_f32_e32 v54, v211, v54
	v_cvt_pk_bf16_f32 v53, v53, v54
	v_mul_f32_e32 v54, v76, v96
	v_mul_f32_e32 v55, v76, v95
	v_mul_f32_e32 v54, v204, v54
	v_mul_f32_e32 v55, v205, v55
	v_cvt_pk_bf16_f32 v54, v54, v55
	v_mul_f32_e32 v55, v76, v98
	v_mul_f32_e32 v56, v76, v97
	v_mul_f32_e32 v55, v206, v55
	v_mul_f32_e32 v56, v207, v56
	v_cvt_pk_bf16_f32 v55, v55, v56
	v_mul_f32_e32 v56, v76, v58
	v_mul_f32_e32 v49, v76, v49
	v_mul_f32_e32 v56, v216, v56
	v_mul_f32_e32 v49, v217, v49
	v_cvt_pk_bf16_f32 v56, v56, v49
	v_mul_f32_e32 v49, v76, v60
	v_mul_f32_e32 v57, v76, v59
	v_mul_f32_e32 v49, v218, v49
	v_mul_f32_e32 v57, v219, v57
	v_cvt_pk_bf16_f32 v57, v49, v57
	v_mul_f32_e32 v49, v76, v62
	v_mul_f32_e32 v58, v76, v61
	v_mul_f32_e32 v49, v212, v49
	v_mul_f32_e32 v58, v213, v58
	v_cvt_pk_bf16_f32 v58, v49, v58
	v_mul_f32_e32 v49, v76, v64
	v_mul_f32_e32 v59, v76, v63
	v_mul_f32_e32 v49, v214, v49
	v_mul_f32_e32 v59, v215, v59
	v_cvt_pk_bf16_f32 v59, v49, v59
	v_fmamk_f32 v49, v51, 0x3a800000, v194
	v_cmp_gt_f32_e32 vcc, s61, v49
	v_mul_f32_e32 v51, 0x4f800000, v49
	global_store_dwordx4 v[74:75], v[52:55], off
	global_store_dwordx4 v[74:75], v[56:59], off offset:1024
	v_cndmask_b32_e32 v49, v49, v51, vcc
	v_sqrt_f32_e32 v51, v49
	s_nop 0
	v_add_u32_e32 v52, -1, v51
	v_fma_f32 v53, -v52, v51, v49
	v_cmp_ge_f32_e64 s[0:1], 0, v53
	v_add_u32_e32 v53, 1, v51
	s_nop 0
	v_cndmask_b32_e64 v52, v51, v52, s[0:1]
	v_fma_f32 v51, -v53, v51, v49
	v_cmp_lt_f32_e64 s[0:1], 0, v51
	s_nop 1
	v_cndmask_b32_e64 v51, v52, v53, s[0:1]
	v_mul_f32_e32 v52, 0x37800000, v51
	v_cndmask_b32_e32 v51, v51, v52, vcc
	v_cmp_class_f32_e32 vcc, v49, v195
	s_nop 1
	v_cndmask_b32_e32 v49, v51, v49, vcc
	v_div_scale_f32 v51, s[0:1], v49, v49, 1.0
	v_rcp_f32_e32 v52, v51
	s_nop 0
	v_fma_f32 v53, -v51, v52, 1.0
	v_fmac_f32_e32 v52, v53, v52
	v_div_scale_f32 v53, vcc, 1.0, v49, 1.0
	v_mul_f32_e32 v54, v53, v52
	v_fma_f32 v55, -v51, v54, v53
	v_fmac_f32_e32 v54, v55, v52
	v_fma_f32 v51, -v51, v54, v53
	v_div_fmas_f32 v51, v51, v52, v54
	v_div_fixup_f32 v49, v51, v49, 1.0
	v_mul_f32_e32 v34, v49, v34
	v_mul_f32_e32 v33, v49, v33
	v_mul_f32_e32 v42, v49, v42
	v_mul_f32_e32 v41, v49, v41
	v_mul_f32_e32 v34, v216, v34
	v_mul_f32_e32 v33, v217, v33
	v_mul_f32_e32 v42, v208, v42
	v_mul_f32_e32 v41, v209, v41
	v_cvt_pk_bf16_f32 v34, v34, v33
	v_mul_f32_e32 v33, v49, v36
	v_mul_f32_e32 v35, v49, v35
	v_cvt_pk_bf16_f32 v42, v42, v41
	v_mul_f32_e32 v41, v49, v44
	v_mul_f32_e32 v43, v49, v43
	v_mul_f32_e32 v33, v218, v33
	v_mul_f32_e32 v35, v219, v35
	v_mul_f32_e32 v41, v210, v41
	v_mul_f32_e32 v43, v211, v43
	v_cvt_pk_bf16_f32 v35, v33, v35
	v_mul_f32_e32 v33, v49, v38
	v_mul_f32_e32 v36, v49, v37
	v_cvt_pk_bf16_f32 v43, v41, v43
	v_mul_f32_e32 v41, v49, v46
	v_mul_f32_e32 v44, v49, v45
	v_mul_f32_e32 v33, v212, v33
	v_mul_f32_e32 v36, v213, v36
	v_mul_f32_e32 v41, v204, v41
	v_mul_f32_e32 v44, v205, v44
	v_mul_f32_e32 v45, v49, v47
	v_cvt_pk_bf16_f32 v36, v33, v36
	v_mul_f32_e32 v33, v49, v40
	v_mul_f32_e32 v37, v49, v39
	v_cvt_pk_bf16_f32 v44, v41, v44
	v_mul_f32_e32 v41, v49, v48
	v_mul_f32_e32 v45, v207, v45
	v_mul_f32_e32 v33, v214, v33
	v_mul_f32_e32 v37, v215, v37
	v_mul_f32_e32 v41, v206, v41
	v_cvt_pk_bf16_f32 v45, v41, v45
	v_cvt_pk_bf16_f32 v37, v33, v37
	v_fmamk_f32 v33, v50, 0x3a800000, v194
	global_store_dwordx4 v[72:73], v[42:45], off
	global_store_dwordx4 v[72:73], v[34:37], off offset:1024
	v_cmp_gt_f32_e32 vcc, s61, v33
	s_nop 0
	v_mul_f32_e32 v34, 0x4f800000, v33
	v_cndmask_b32_e32 v33, v33, v34, vcc
	v_sqrt_f32_e32 v34, v33
	s_nop 0
	v_add_u32_e32 v35, -1, v34
	v_fma_f32 v36, -v35, v34, v33
	v_cmp_ge_f32_e64 s[0:1], 0, v36
	v_add_u32_e32 v36, 1, v34
	s_nop 0
	v_cndmask_b32_e64 v35, v34, v35, s[0:1]
	v_fma_f32 v34, -v36, v34, v33
	v_cmp_lt_f32_e64 s[0:1], 0, v34
	s_nop 1
	v_cndmask_b32_e64 v34, v35, v36, s[0:1]
	v_mul_f32_e32 v35, 0x37800000, v34
	v_cndmask_b32_e32 v34, v34, v35, vcc
	v_cmp_class_f32_e32 vcc, v33, v195
	s_nop 1
	v_cndmask_b32_e32 v33, v34, v33, vcc
	v_div_scale_f32 v34, s[0:1], v33, v33, 1.0
	v_rcp_f32_e32 v35, v34
	s_add_i32 s0, s2, s97
	s_cmp_gt_i32 s0, 0xffff
	v_fma_f32 v36, -v34, v35, 1.0
	v_fmac_f32_e32 v35, v36, v35
	v_div_scale_f32 v36, vcc, 1.0, v33, 1.0
	v_mul_f32_e32 v37, v36, v35
	v_fma_f32 v38, -v34, v37, v36
	v_fmac_f32_e32 v37, v38, v35
	v_fma_f32 v34, -v34, v37, v36
	v_div_fmas_f32 v34, v34, v35, v37
	v_div_fixup_f32 v33, v34, v33, 1.0
	v_mul_f32_e32 v26, v33, v26
	v_mul_f32_e32 v25, v33, v25
	v_mul_f32_e32 v6, v208, v26
	v_mul_f32_e32 v7, v209, v25
	v_cvt_pk_bf16_f32 v6, v6, v7
	v_mul_f32_e32 v7, v33, v28
	v_mul_f32_e32 v7, v210, v7
	v_mul_f32_e32 v8, v33, v27
	v_mul_f32_e32 v8, v211, v8
	v_cvt_pk_bf16_f32 v7, v7, v8
	v_mul_f32_e32 v8, v33, v30
	v_mul_f32_e32 v2, v204, v8
	v_mul_f32_e32 v8, v33, v29
	v_mul_f32_e32 v3, v205, v8
	v_cvt_pk_bf16_f32 v8, v2, v3
	v_mul_f32_e32 v2, v33, v32
	v_mul_f32_e32 v2, v206, v2
	v_mul_f32_e32 v3, v33, v31
	v_mul_f32_e32 v3, v207, v3
	v_cvt_pk_bf16_f32 v9, v2, v3
	v_mul_f32_e32 v2, v33, v18
	v_mul_f32_e32 v0, v33, v0
	v_mul_f32_e32 v2, v216, v2
	v_mul_f32_e32 v0, v217, v0
	v_cvt_pk_bf16_f32 v2, v2, v0
	v_mul_f32_e32 v0, v33, v20
	v_mul_f32_e32 v3, v33, v19
	v_mul_f32_e32 v0, v218, v0
	v_mul_f32_e32 v3, v219, v3
	v_cvt_pk_bf16_f32 v3, v0, v3
	v_mul_f32_e32 v0, v33, v22
	v_mul_f32_e32 v4, v33, v21
	v_mul_f32_e32 v0, v212, v0
	v_mul_f32_e32 v4, v213, v4
	v_mul_f32_e32 v5, v33, v23
	v_cvt_pk_bf16_f32 v4, v0, v4
	v_mul_f32_e32 v0, v33, v24
	v_mul_f32_e32 v5, v215, v5
	v_mul_f32_e32 v0, v214, v0
	v_cvt_pk_bf16_f32 v5, v0, v5
	global_store_dwordx4 v[70:71], v[6:9], off
	global_store_dwordx4 v[70:71], v[2:5], off offset:1024
	s_cbranch_scc0 .LBB0_463

.LBB0_670:
	s_or_b64 exec, exec, s[0:1]
	s_mov_b64 s[4:5], s[94:95]
	v_mov_b32_e32 v0, v1
	s_waitcnt lgkmcnt(0)
	s_barrier
	s_nop 0
	v_mbcnt_lo_u32_b32 v0, -1, v0
	v_mbcnt_hi_u32_b32 v0, -1, v0
	v_add_u32_e32 v0, s93, v0
	s_nop 0
	v_readfirstlane_b32 s0, v0
	s_ashr_i32 s0, s0, 6
	s_add_i32 s16, s0, s96
	s_cmp_lt_i32 s16, 0x10000
	s_cbranch_scc0 .LBB0_673
	v_and_b32_e32 v3, 64, v197
	v_add_u32_e32 v3, 64, v3
	v_xor_b32_e32 v4, 1, v197
	v_cmp_lt_i32_e32 vcc, v4, v3
	s_load_dwordx2 s[6:7], s[4:5], 0x88
	s_load_dwordx4 s[0:3], s[4:5], 0xb8
	v_cndmask_b32_e32 v4, v197, v4, vcc
	v_lshlrev_b32_e32 v152, 2, v4
	v_xor_b32_e32 v4, 2, v197
	v_cmp_lt_i32_e32 vcc, v4, v3
	v_readlane_b32 s4, v254, 26
	s_lshl_b32 s62, s4, 10
	v_cndmask_b32_e32 v4, v197, v4, vcc
	v_lshlrev_b32_e32 v153, 2, v4
	v_xor_b32_e32 v4, 4, v197
	v_cmp_lt_i32_e32 vcc, v4, v3
	s_lshl_b64 s[4:5], s[62:63], 2
	v_and_b32_e32 v2, 63, v0
	v_cndmask_b32_e32 v4, v197, v4, vcc
	v_lshlrev_b32_e32 v154, 2, v4
	v_xor_b32_e32 v4, 8, v197
	v_cmp_lt_i32_e32 vcc, v4, v3
	s_waitcnt lgkmcnt(0)
	s_add_u32 s4, s6, s4
	s_addc_u32 s5, s7, s5
	v_cndmask_b32_e32 v4, v197, v4, vcc
	v_lshlrev_b32_e32 v155, 2, v4
	v_xor_b32_e32 v4, 16, v197
	v_cmp_lt_i32_e32 vcc, v4, v3
	v_lshlrev_b32_e32 v0, 4, v2
	v_lshl_add_u64 v[146:147], s[0:1], 0, v[0:1]
	v_cndmask_b32_e32 v4, v197, v4, vcc
	v_lshlrev_b32_e32 v156, 2, v4
	v_xor_b32_e32 v4, 32, v197
	v_cmp_lt_i32_e32 vcc, v4, v3
	v_lshl_add_u64 v[148:149], s[4:5], 0, v[0:1]
	v_lshlrev_b32_e32 v0, 3, v2
	v_cndmask_b32_e32 v3, v197, v4, vcc
	v_lshlrev_b32_e32 v157, 2, v3
	v_lshl_add_u64 v[150:151], s[2:3], 0, v[0:1]
	global_load_dwordx4 v[204:207], v[148:149], off
	global_load_dwordx4 v[208:211], v[148:149], off offset:1024
	global_load_dwordx4 v[212:215], v[148:149], off offset:2048
	global_load_dwordx4 v[216:219], v[148:149], off offset:3072
.LBB0_672:
	s_ashr_i32 s17, s16, 31
	s_lshl_b64 s[0:1], s[16:17], 12
	v_lshl_add_u64 v[2:3], v[146:147], 0, s[0:1]
	global_load_dwordx4 v[126:129], v[2:3], off
	global_load_dwordx4 v[122:125], v[2:3], off offset:1024
	global_load_dwordx4 v[118:121], v[2:3], off offset:2048
	global_load_dwordx4 v[114:117], v[2:3], off offset:3072
	s_add_i32 s14, s16, s97
	s_ashr_i32 s15, s14, 31
	s_lshl_b64 s[0:1], s[14:15], 12
	v_lshl_add_u64 v[2:3], v[146:147], 0, s[0:1]
	global_load_dwordx4 v[110:113], v[2:3], off
	global_load_dwordx4 v[106:109], v[2:3], off offset:1024
	global_load_dwordx4 v[102:105], v[2:3], off offset:2048
	global_load_dwordx4 v[98:101], v[2:3], off offset:3072
	s_add_i32 s12, s88, s16
	s_ashr_i32 s13, s12, 31
	s_lshl_b64 s[0:1], s[12:13], 12
	v_lshl_add_u64 v[2:3], v[146:147], 0, s[0:1]
	global_load_dwordx4 v[94:97], v[2:3], off
	global_load_dwordx4 v[90:93], v[2:3], off offset:1024
	global_load_dwordx4 v[86:89], v[2:3], off offset:2048
	global_load_dwordx4 v[82:85], v[2:3], off offset:3072
	s_add_i32 s10, s75, s16
	s_ashr_i32 s11, s10, 31
	s_lshl_b64 s[0:1], s[10:11], 12
	v_lshl_add_u64 v[2:3], v[146:147], 0, s[0:1]
	global_load_dwordx4 v[78:81], v[2:3], off
	global_load_dwordx4 v[74:77], v[2:3], off offset:1024
	global_load_dwordx4 v[70:73], v[2:3], off offset:2048
	global_load_dwordx4 v[66:69], v[2:3], off offset:3072
	s_add_i32 s8, s89, s16
	s_ashr_i32 s9, s8, 31
	s_lshl_b64 s[0:1], s[8:9], 12
	v_lshl_add_u64 v[2:3], v[146:147], 0, s[0:1]
	global_load_dwordx4 v[62:65], v[2:3], off
	global_load_dwordx4 v[58:61], v[2:3], off offset:1024
	global_load_dwordx4 v[54:57], v[2:3], off offset:2048
	global_load_dwordx4 v[50:53], v[2:3], off offset:3072
	s_add_i32 s6, s77, s16
	s_ashr_i32 s7, s6, 31
	s_lshl_b64 s[0:1], s[6:7], 12
	v_lshl_add_u64 v[2:3], v[146:147], 0, s[0:1]
	global_load_dwordx4 v[46:49], v[2:3], off
	global_load_dwordx4 v[42:45], v[2:3], off offset:1024
	global_load_dwordx4 v[34:37], v[2:3], off offset:2048
	global_load_dwordx4 v[26:29], v[2:3], off offset:3072
	s_add_i32 s4, s78, s16
	s_ashr_i32 s5, s4, 31
	s_lshl_b64 s[0:1], s[4:5], 12
	v_lshl_add_u64 v[2:3], v[146:147], 0, s[0:1]
	global_load_dwordx4 v[14:17], v[2:3], off
	global_load_dwordx4 v[10:13], v[2:3], off offset:1024
	global_load_dwordx4 v[6:9], v[2:3], off offset:2048
	s_nop 0
	global_load_dwordx4 v[2:5], v[2:3], off offset:3072
	s_add_i32 s2, s14, s97
	s_add_i32 s2, s2, s97
	s_add_i32 s2, s2, s97
	s_add_i32 s2, s2, s97
	s_add_i32 s18, s2, s97
	s_add_i32 s2, s79, s16
	s_ashr_i32 s3, s2, 31
	s_lshl_b64 s[0:1], s[2:3], 12
	v_lshl_add_u64 v[18:19], v[146:147], 0, s[0:1]
	global_load_dwordx4 v[38:41], v[18:19], off
	global_load_dwordx4 v[30:33], v[18:19], off offset:1024
	global_load_dwordx4 v[22:25], v[18:19], off offset:2048
	s_nop 0
	global_load_dwordx4 v[18:21], v[18:19], off offset:3072
	s_add_i32 s18, s18, s97
	s_waitcnt vmcnt(31)
	v_mul_f32_e32 v0, v127, v127
	v_mul_f32_e32 v130, v129, v129
	v_fmac_f32_e32 v0, v126, v126
	v_fmac_f32_e32 v130, v128, v128
	v_add_f32_e32 v0, v0, v130
	s_waitcnt vmcnt(30)
	v_mul_f32_e32 v130, v123, v123
	v_mul_f32_e32 v131, v125, v125
	v_fmac_f32_e32 v130, v122, v122
	v_fmac_f32_e32 v131, v124, v124
	v_add_f32_e32 v130, v130, v131
	v_add_f32_e32 v0, v0, v130
	s_waitcnt vmcnt(29)
	v_mul_f32_e32 v130, v119, v119
	v_mul_f32_e32 v131, v121, v121
	v_fmac_f32_e32 v130, v118, v118
	v_fmac_f32_e32 v131, v120, v120
	v_add_f32_e32 v130, v130, v131
	v_add_f32_e32 v0, v0, v130
	s_waitcnt vmcnt(28)
	v_mul_f32_e32 v130, v115, v115
	v_mul_f32_e32 v131, v117, v117
	v_fmac_f32_e32 v130, v114, v114
	v_fmac_f32_e32 v131, v116, v116
	v_add_f32_e32 v130, v130, v131
	v_add_f32_e32 v0, v0, v130
	s_waitcnt vmcnt(27)
	v_mul_f32_e32 v130, v111, v111
	v_mul_f32_e32 v131, v113, v113
	v_fmac_f32_e32 v130, v110, v110
	v_fmac_f32_e32 v131, v112, v112
	v_add_f32_e32 v130, v130, v131
	s_waitcnt vmcnt(26)
	v_mul_f32_e32 v131, v107, v107
	v_mul_f32_e32 v132, v109, v109
	v_fmac_f32_e32 v131, v106, v106
	v_fmac_f32_e32 v132, v108, v108
	v_add_f32_e32 v131, v131, v132
	v_add_f32_e32 v130, v130, v131
	s_waitcnt vmcnt(25)
	v_mul_f32_e32 v131, v103, v103
	v_mul_f32_e32 v132, v105, v105
	v_fmac_f32_e32 v131, v102, v102
	v_fmac_f32_e32 v132, v104, v104
	v_add_f32_e32 v131, v131, v132
	v_add_f32_e32 v130, v130, v131
	s_waitcnt vmcnt(24)
	v_mul_f32_e32 v131, v99, v99
	v_mul_f32_e32 v132, v101, v101
	v_fmac_f32_e32 v131, v98, v98
	v_fmac_f32_e32 v132, v100, v100
	v_add_f32_e32 v131, v131, v132
	v_add_f32_e32 v130, v130, v131
	s_waitcnt vmcnt(23)
	v_mul_f32_e32 v131, v95, v95
	v_mul_f32_e32 v132, v97, v97
	v_fmac_f32_e32 v131, v94, v94
	v_fmac_f32_e32 v132, v96, v96
	v_add_f32_e32 v131, v131, v132
	s_waitcnt vmcnt(22)
	v_mul_f32_e32 v132, v91, v91
	v_mul_f32_e32 v133, v93, v93
	v_fmac_f32_e32 v132, v90, v90
	v_fmac_f32_e32 v133, v92, v92
	v_add_f32_e32 v132, v132, v133
	v_add_f32_e32 v131, v131, v132
	s_waitcnt vmcnt(21)
	v_mul_f32_e32 v132, v87, v87
	v_mul_f32_e32 v133, v89, v89
	v_fmac_f32_e32 v132, v86, v86
	v_fmac_f32_e32 v133, v88, v88
	v_add_f32_e32 v132, v132, v133
	v_add_f32_e32 v131, v131, v132
	s_waitcnt vmcnt(20)
	v_mul_f32_e32 v132, v83, v83
	v_mul_f32_e32 v133, v85, v85
	v_fmac_f32_e32 v132, v82, v82
	v_fmac_f32_e32 v133, v84, v84
	v_add_f32_e32 v132, v132, v133
	v_add_f32_e32 v131, v131, v132
	s_waitcnt vmcnt(19)
	v_mul_f32_e32 v132, v79, v79
	v_mul_f32_e32 v133, v81, v81
	v_fmac_f32_e32 v132, v78, v78
	v_fmac_f32_e32 v133, v80, v80
	v_add_f32_e32 v132, v132, v133
	s_waitcnt vmcnt(18)
	v_mul_f32_e32 v133, v75, v75
	v_mul_f32_e32 v134, v77, v77
	v_fmac_f32_e32 v133, v74, v74
	v_fmac_f32_e32 v134, v76, v76
	v_add_f32_e32 v133, v133, v134
	v_add_f32_e32 v132, v132, v133
	s_waitcnt vmcnt(17)
	v_mul_f32_e32 v133, v71, v71
	v_mul_f32_e32 v134, v73, v73
	v_fmac_f32_e32 v133, v70, v70
	v_fmac_f32_e32 v134, v72, v72
	v_add_f32_e32 v133, v133, v134
	v_add_f32_e32 v132, v132, v133
	s_waitcnt vmcnt(16)
	v_mul_f32_e32 v133, v67, v67
	v_mul_f32_e32 v134, v69, v69
	v_fmac_f32_e32 v133, v66, v66
	v_fmac_f32_e32 v134, v68, v68
	v_add_f32_e32 v133, v133, v134
	v_add_f32_e32 v132, v132, v133
	s_waitcnt vmcnt(15)
	v_mul_f32_e32 v133, v63, v63
	v_mul_f32_e32 v134, v65, v65
	v_fmac_f32_e32 v133, v62, v62
	v_fmac_f32_e32 v134, v64, v64
	v_add_f32_e32 v133, v133, v134
	s_waitcnt vmcnt(14)
	v_mul_f32_e32 v134, v59, v59
	v_mul_f32_e32 v135, v61, v61
	v_fmac_f32_e32 v134, v58, v58
	v_fmac_f32_e32 v135, v60, v60
	v_add_f32_e32 v134, v134, v135
	v_add_f32_e32 v133, v133, v134
	s_waitcnt vmcnt(13)
	v_mul_f32_e32 v134, v55, v55
	v_mul_f32_e32 v135, v57, v57
	v_fmac_f32_e32 v134, v54, v54
	v_fmac_f32_e32 v135, v56, v56
	v_add_f32_e32 v134, v134, v135
	v_add_f32_e32 v133, v133, v134
	s_waitcnt vmcnt(12)
	v_mul_f32_e32 v134, v51, v51
	v_mul_f32_e32 v135, v53, v53
	v_fmac_f32_e32 v134, v50, v50
	v_fmac_f32_e32 v135, v52, v52
	v_add_f32_e32 v134, v134, v135
	v_add_f32_e32 v133, v133, v134
	s_waitcnt vmcnt(11)
	v_mul_f32_e32 v134, v47, v47
	v_mul_f32_e32 v135, v49, v49
	v_fmac_f32_e32 v134, v46, v46
	v_fmac_f32_e32 v135, v48, v48
	v_add_f32_e32 v134, v134, v135
	s_waitcnt vmcnt(10)
	v_mul_f32_e32 v135, v43, v43
	v_mul_f32_e32 v136, v45, v45
	v_fmac_f32_e32 v135, v42, v42
	v_fmac_f32_e32 v136, v44, v44
	v_add_f32_e32 v135, v135, v136
	v_add_f32_e32 v134, v134, v135
	s_waitcnt vmcnt(9)
	v_mul_f32_e32 v135, v35, v35
	v_mul_f32_e32 v136, v37, v37
	v_fmac_f32_e32 v135, v34, v34
	v_fmac_f32_e32 v136, v36, v36
	v_add_f32_e32 v135, v135, v136
	v_add_f32_e32 v134, v134, v135
	s_waitcnt vmcnt(8)
	v_mul_f32_e32 v135, v27, v27
	v_mul_f32_e32 v136, v29, v29
	v_fmac_f32_e32 v135, v26, v26
	v_fmac_f32_e32 v136, v28, v28
	v_add_f32_e32 v135, v135, v136
	v_add_f32_e32 v134, v134, v135
	s_waitcnt vmcnt(7)
	v_mul_f32_e32 v135, v15, v15
	v_mul_f32_e32 v136, v17, v17
	v_fmac_f32_e32 v135, v14, v14
	v_fmac_f32_e32 v136, v16, v16
	v_add_f32_e32 v135, v135, v136
	s_waitcnt vmcnt(6)
	v_mul_f32_e32 v136, v11, v11
	v_mul_f32_e32 v137, v13, v13
	v_fmac_f32_e32 v136, v10, v10
	v_fmac_f32_e32 v137, v12, v12
	v_add_f32_e32 v136, v136, v137
	v_add_f32_e32 v135, v135, v136
	s_waitcnt vmcnt(5)
	v_mul_f32_e32 v136, v7, v7
	v_mul_f32_e32 v137, v9, v9
	v_fmac_f32_e32 v136, v6, v6
	v_fmac_f32_e32 v137, v8, v8
	v_add_f32_e32 v136, v136, v137
	v_add_f32_e32 v135, v135, v136
	s_waitcnt vmcnt(4)
	v_mul_f32_e32 v136, v3, v3
	v_mul_f32_e32 v137, v5, v5
	v_fmac_f32_e32 v136, v2, v2
	v_fmac_f32_e32 v137, v4, v4
	v_add_f32_e32 v136, v136, v137
	v_add_f32_e32 v135, v135, v136
	s_waitcnt vmcnt(3)
	v_mul_f32_e32 v136, v39, v39
	v_mul_f32_e32 v137, v41, v41
	v_fmac_f32_e32 v136, v38, v38
	v_fmac_f32_e32 v137, v40, v40
	v_add_f32_e32 v136, v136, v137
	s_waitcnt vmcnt(2)
	v_mul_f32_e32 v137, v31, v31
	v_mul_f32_e32 v138, v33, v33
	v_fmac_f32_e32 v137, v30, v30
	v_fmac_f32_e32 v138, v32, v32
	v_add_f32_e32 v137, v137, v138
	v_add_f32_e32 v136, v136, v137
	s_waitcnt vmcnt(1)
	v_mul_f32_e32 v137, v23, v23
	v_mul_f32_e32 v138, v25, v25
	v_fmac_f32_e32 v137, v22, v22
	v_fmac_f32_e32 v138, v24, v24
	v_add_f32_e32 v137, v137, v138
	v_add_f32_e32 v136, v136, v137
	s_waitcnt vmcnt(0)
	v_mul_f32_e32 v137, v19, v19
	v_mul_f32_e32 v138, v21, v21
	v_fmac_f32_e32 v137, v18, v18
	v_fmac_f32_e32 v138, v20, v20
	v_add_f32_e32 v137, v137, v138
	v_add_f32_e32 v136, v136, v137
	ds_bpermute_b32 v137, v152, v0
	ds_bpermute_b32 v200, v152, v130
	ds_bpermute_b32 v201, v152, v131
	ds_bpermute_b32 v202, v152, v132
	ds_bpermute_b32 v196, v152, v133
	ds_bpermute_b32 v162, v152, v134
	ds_bpermute_b32 v250, v152, v135
	ds_bpermute_b32 v251, v152, v136
	s_waitcnt lgkmcnt(0)
	v_add_f32_e32 v0, v0, v137
	v_add_f32_e32 v130, v130, v200
	v_add_f32_e32 v131, v131, v201
	v_add_f32_e32 v132, v132, v202
	v_add_f32_e32 v133, v133, v196
	v_add_f32_e32 v134, v134, v162
	v_add_f32_e32 v135, v135, v250
	v_add_f32_e32 v136, v136, v251
	ds_bpermute_b32 v137, v153, v0
	ds_bpermute_b32 v200, v153, v130
	ds_bpermute_b32 v201, v153, v131
	ds_bpermute_b32 v202, v153, v132
	ds_bpermute_b32 v196, v153, v133
	ds_bpermute_b32 v162, v153, v134
	ds_bpermute_b32 v250, v153, v135
	ds_bpermute_b32 v251, v153, v136
	s_waitcnt lgkmcnt(0)
	v_add_f32_e32 v0, v0, v137
	v_add_f32_e32 v130, v130, v200
	v_add_f32_e32 v131, v131, v201
	v_add_f32_e32 v132, v132, v202
	v_add_f32_e32 v133, v133, v196
	v_add_f32_e32 v134, v134, v162
	v_add_f32_e32 v135, v135, v250
	v_add_f32_e32 v136, v136, v251
	ds_bpermute_b32 v137, v154, v0
	ds_bpermute_b32 v200, v154, v130
	ds_bpermute_b32 v201, v154, v131
	ds_bpermute_b32 v202, v154, v132
	ds_bpermute_b32 v196, v154, v133
	ds_bpermute_b32 v162, v154, v134
	ds_bpermute_b32 v250, v154, v135
	ds_bpermute_b32 v251, v154, v136
	s_waitcnt lgkmcnt(0)
	v_add_f32_e32 v0, v0, v137
	v_add_f32_e32 v130, v130, v200
	v_add_f32_e32 v131, v131, v201
	v_add_f32_e32 v132, v132, v202
	v_add_f32_e32 v133, v133, v196
	v_add_f32_e32 v134, v134, v162
	v_add_f32_e32 v135, v135, v250
	v_add_f32_e32 v136, v136, v251
	ds_bpermute_b32 v137, v155, v0
	ds_bpermute_b32 v200, v155, v130
	ds_bpermute_b32 v201, v155, v131
	ds_bpermute_b32 v202, v155, v132
	ds_bpermute_b32 v196, v155, v133
	ds_bpermute_b32 v162, v155, v134
	ds_bpermute_b32 v250, v155, v135
	ds_bpermute_b32 v251, v155, v136
	s_waitcnt lgkmcnt(0)
	v_add_f32_e32 v0, v0, v137
	v_add_f32_e32 v130, v130, v200
	v_add_f32_e32 v131, v131, v201
	v_add_f32_e32 v132, v132, v202
	v_add_f32_e32 v133, v133, v196
	v_add_f32_e32 v134, v134, v162
	v_add_f32_e32 v135, v135, v250
	v_add_f32_e32 v136, v136, v251
	ds_bpermute_b32 v137, v156, v0
	ds_bpermute_b32 v200, v156, v130
	ds_bpermute_b32 v201, v156, v131
	ds_bpermute_b32 v202, v156, v132
	ds_bpermute_b32 v196, v156, v133
	ds_bpermute_b32 v162, v156, v134
	ds_bpermute_b32 v250, v156, v135
	ds_bpermute_b32 v251, v156, v136
	s_waitcnt lgkmcnt(0)
	v_add_f32_e32 v0, v0, v137
	v_add_f32_e32 v130, v130, v200
	v_add_f32_e32 v131, v131, v201
	v_add_f32_e32 v132, v132, v202
	v_add_f32_e32 v133, v133, v196
	v_add_f32_e32 v134, v134, v162
	v_add_f32_e32 v135, v135, v250
	v_add_f32_e32 v136, v136, v251
	ds_bpermute_b32 v220, v157, v0
	ds_bpermute_b32 v221, v157, v130
	ds_bpermute_b32 v222, v157, v131
	ds_bpermute_b32 v223, v157, v132
	ds_bpermute_b32 v224, v157, v133
	ds_bpermute_b32 v225, v157, v134
	ds_bpermute_b32 v226, v157, v135
	ds_bpermute_b32 v227, v157, v136
	s_waitcnt lgkmcnt(0)
	v_add_f32_e32 v164, v0, v220
	v_add_f32_e32 v166, v130, v221
	v_add_f32_e32 v163, v131, v222
	v_add_f32_e32 v161, v132, v223
	v_add_f32_e32 v160, v133, v224
	v_add_f32_e32 v159, v134, v225
	v_add_f32_e32 v158, v135, v226
	v_add_f32_e32 v0, v136, v227
	s_nop 0
	s_nop 0
	s_nop 0
	s_nop 0
	v_fmamk_f32 v164, v164, 0x3a800000, v194
	v_cmp_gt_f32_e32 vcc, s61, v164
	v_mul_f32_e32 v165, 0x4f800000, v164
	s_nop 0
	s_nop 0
	s_nop 0
	v_cndmask_b32_e32 v164, v164, v165, vcc
	v_sqrt_f32_e32 v165, v164
	s_nop 0
	s_nop 0
	s_nop 0
	v_add_u32_e32 v167, -1, v165
	v_fma_f32 v168, -v167, v165, v164
	v_cmp_ge_f32_e64 s[0:1], 0, v168
	v_add_u32_e32 v168, 1, v165
	s_nop 0
	s_nop 0
	s_nop 0
	v_cndmask_b32_e64 v167, v165, v167, s[0:1]
	v_fma_f32 v165, -v168, v165, v164
	v_cmp_lt_f32_e64 s[0:1], 0, v165
	s_nop 0
	s_nop 0
	s_nop 0
	v_cndmask_b32_e64 v165, v167, v168, s[0:1]
	v_mul_f32_e32 v167, 0x37800000, v165
	v_cndmask_b32_e32 v165, v165, v167, vcc
	v_cmp_class_f32_e32 vcc, v164, v195
	s_nop 0
	s_nop 0
	s_nop 0
	v_cndmask_b32_e32 v164, v165, v164, vcc
	v_div_scale_f32 v165, s[0:1], v164, v164, 1.0
	v_rcp_f32_e32 v167, v165
	s_nop 0
	s_nop 0
	s_nop 0
	s_lshl_b64 s[0:1], s[16:17], 11
	v_fma_f32 v168, -v165, v167, 1.0
	v_fmac_f32_e32 v167, v168, v167
	v_div_scale_f32 v168, vcc, 1.0, v164, 1.0
	s_nop 0
	s_nop 0
	s_nop 0
	s_nop 0
	s_nop 0
	s_nop 0
	v_mul_f32_e32 v169, v168, v167
	v_fma_f32 v170, -v165, v169, v168
	v_fmac_f32_e32 v169, v170, v167
	v_fma_f32 v165, -v165, v169, v168
	v_div_fmas_f32 v165, v165, v167, v169
	v_div_fixup_f32 v167, v165, v164, 1.0
	v_mul_f32_e32 v114, v114, v167
	v_mul_f32_e32 v115, v115, v167
	v_lshl_add_u64 v[164:165], v[150:151], 0, s[0:1]
	v_mul_f32_e32 v118, v118, v167
	v_mul_f32_e32 v119, v119, v167
	v_fmamk_f32 v0, v0, 0x3a800000, v194
	v_mul_f32_e32 v126, v126, v167
	v_mul_f32_e32 v127, v127, v167
	v_mul_f32_e32 v122, v122, v167
	v_mul_f32_e32 v123, v123, v167
	s_add_i32 s16, s18, s97
	s_nop 0
	v_mul_f32_e32 v126, v126, v204
	v_mul_f32_e32 v127, v127, v205
	s_nop 0
	v_mul_f32_e32 v118, v118, v212
	s_nop 0
	v_mul_f32_e32 v114, v114, v216
	v_mul_f32_e32 v115, v115, v217
	v_cvt_pk_bf16_f32 v114, v114, v115
	v_mul_f32_e32 v115, v116, v167
	v_mul_f32_e32 v115, v115, v218
	v_mul_f32_e32 v116, v117, v167
	v_mul_f32_e32 v116, v116, v219
	v_cvt_pk_bf16_f32 v115, v115, v116
	global_store_dwordx2 v[164:165], v[114:115], off offset:1536
	v_fmamk_f32 v114, v166, 0x3a800000, v194
	v_cmp_gt_f32_e32 vcc, s61, v114
	v_mul_f32_e32 v115, 0x4f800000, v114
	v_mul_f32_e32 v119, v119, v213
	v_cndmask_b32_e32 v114, v114, v115, vcc
	v_sqrt_f32_e32 v115, v114
	v_cvt_pk_bf16_f32 v118, v118, v119
	v_mul_f32_e32 v119, v120, v167
	v_mul_f32_e32 v119, v119, v214
	v_add_u32_e32 v116, -1, v115
	v_fma_f32 v117, -v116, v115, v114
	v_cmp_ge_f32_e64 s[0:1], 0, v117
	v_add_u32_e32 v117, 1, v115
	v_mul_f32_e32 v120, v121, v167
	v_cndmask_b32_e64 v116, v115, v116, s[0:1]
	v_fma_f32 v115, -v117, v115, v114
	v_cmp_lt_f32_e64 s[0:1], 0, v115
	v_mul_f32_e32 v120, v120, v215
	v_cvt_pk_bf16_f32 v119, v119, v120
	global_store_dwordx2 v[164:165], v[118:119], off offset:1024
	v_cndmask_b32_e64 v115, v116, v117, s[0:1]
	v_mul_f32_e32 v116, 0x37800000, v115
	v_cndmask_b32_e32 v115, v115, v116, vcc
	v_cmp_class_f32_e32 vcc, v114, v195
	v_cvt_pk_bf16_f32 v126, v126, v127
	v_mul_f32_e32 v127, v128, v167
	v_mul_f32_e32 v127, v127, v206
	v_cndmask_b32_e32 v114, v115, v114, vcc
	v_div_scale_f32 v115, s[0:1], v114, v114, 1.0
	v_rcp_f32_e32 v116, v115
	s_lshl_b64 s[0:1], s[14:15], 11
	v_mul_f32_e32 v128, v129, v167
	v_mul_f32_e32 v128, v128, v207
	v_fma_f32 v117, -v115, v116, 1.0
	v_fmac_f32_e32 v116, v117, v116
	v_div_scale_f32 v117, vcc, 1.0, v114, 1.0
	v_mul_f32_e32 v118, v117, v116
	v_fma_f32 v119, -v115, v118, v117
	v_fmac_f32_e32 v118, v119, v116
	v_fma_f32 v115, -v115, v118, v117
	v_div_fmas_f32 v115, v115, v116, v118
	v_div_fixup_f32 v116, v115, v114, 1.0
	v_mul_f32_e32 v98, v98, v116
	v_mul_f32_e32 v99, v99, v116
	v_mul_f32_e32 v98, v98, v216
	v_mul_f32_e32 v99, v99, v217
	v_cvt_pk_bf16_f32 v98, v98, v99
	v_mul_f32_e32 v99, v100, v116
	v_lshl_add_u64 v[114:115], v[150:151], 0, s[0:1]
	v_mul_f32_e32 v99, v99, v218
	v_mul_f32_e32 v100, v101, v116
	v_mul_f32_e32 v100, v100, v219
	v_cvt_pk_bf16_f32 v99, v99, v100
	global_store_dwordx2 v[114:115], v[98:99], off offset:1536
	v_fmamk_f32 v98, v163, 0x3a800000, v194
	v_cmp_gt_f32_e32 vcc, s61, v98
	v_mul_f32_e32 v99, 0x4f800000, v98
	v_mul_f32_e32 v102, v102, v116
	v_cndmask_b32_e32 v98, v98, v99, vcc
	v_sqrt_f32_e32 v99, v98
	v_mul_f32_e32 v103, v103, v116
	v_mul_f32_e32 v102, v102, v212
	v_mul_f32_e32 v103, v103, v213
	v_add_u32_e32 v100, -1, v99
	v_fma_f32 v101, -v100, v99, v98
	v_cmp_ge_f32_e64 s[0:1], 0, v101
	v_add_u32_e32 v101, 1, v99
	v_cvt_pk_bf16_f32 v102, v102, v103
	v_mul_f32_e32 v103, v104, v116
	v_cndmask_b32_e64 v100, v99, v100, s[0:1]
	v_fma_f32 v99, -v101, v99, v98
	v_cmp_lt_f32_e64 s[0:1], 0, v99
	v_mul_f32_e32 v103, v103, v214
	v_mul_f32_e32 v104, v105, v116
	v_cndmask_b32_e64 v99, v100, v101, s[0:1]
	v_mul_f32_e32 v100, 0x37800000, v99
	v_cndmask_b32_e32 v99, v99, v100, vcc
	v_cmp_class_f32_e32 vcc, v98, v195
	v_mul_f32_e32 v104, v104, v215
	v_cvt_pk_bf16_f32 v103, v103, v104
	global_store_dwordx2 v[114:115], v[102:103], off offset:1024
	v_cndmask_b32_e32 v98, v99, v98, vcc
	v_div_scale_f32 v99, s[0:1], v98, v98, 1.0
	v_rcp_f32_e32 v100, v99
	s_lshl_b64 s[0:1], s[12:13], 11
	v_mul_f32_e32 v110, v110, v116
	v_mul_f32_e32 v111, v111, v116
	v_fma_f32 v101, -v99, v100, 1.0
	v_fmac_f32_e32 v100, v101, v100
	v_div_scale_f32 v101, vcc, 1.0, v98, 1.0
	v_mul_f32_e32 v102, v101, v100
	v_fma_f32 v103, -v99, v102, v101
	v_fmac_f32_e32 v102, v103, v100
	v_fma_f32 v99, -v99, v102, v101
	v_div_fmas_f32 v99, v99, v100, v102
	v_div_fixup_f32 v100, v99, v98, 1.0
	v_mul_f32_e32 v82, v82, v100
	v_mul_f32_e32 v83, v83, v100
	v_mul_f32_e32 v82, v82, v216
	v_mul_f32_e32 v83, v83, v217
	v_cvt_pk_bf16_f32 v82, v82, v83
	v_mul_f32_e32 v83, v84, v100
	v_lshl_add_u64 v[98:99], v[150:151], 0, s[0:1]
	v_mul_f32_e32 v83, v83, v218
	v_mul_f32_e32 v84, v85, v100
	v_mul_f32_e32 v84, v84, v219
	v_cvt_pk_bf16_f32 v83, v83, v84
	global_store_dwordx2 v[98:99], v[82:83], off offset:1536
	v_fmamk_f32 v82, v161, 0x3a800000, v194
	v_cmp_gt_f32_e32 vcc, s61, v82
	v_mul_f32_e32 v83, 0x4f800000, v82
	v_mul_f32_e32 v86, v86, v100
	v_cndmask_b32_e32 v82, v82, v83, vcc
	v_sqrt_f32_e32 v83, v82
	v_mul_f32_e32 v87, v87, v100
	v_mul_f32_e32 v86, v86, v212
	v_mul_f32_e32 v87, v87, v213
	v_add_u32_e32 v84, -1, v83
	v_fma_f32 v85, -v84, v83, v82
	v_cmp_ge_f32_e64 s[0:1], 0, v85
	v_add_u32_e32 v85, 1, v83
	v_cvt_pk_bf16_f32 v86, v86, v87
	v_mul_f32_e32 v87, v88, v100
	v_cndmask_b32_e64 v84, v83, v84, s[0:1]
	v_fma_f32 v83, -v85, v83, v82
	v_cmp_lt_f32_e64 s[0:1], 0, v83
	v_mul_f32_e32 v87, v87, v214
	v_mul_f32_e32 v88, v89, v100
	v_cndmask_b32_e64 v83, v84, v85, s[0:1]
	v_mul_f32_e32 v84, 0x37800000, v83
	v_cndmask_b32_e32 v83, v83, v84, vcc
	v_cmp_class_f32_e32 vcc, v82, v195
	v_mul_f32_e32 v88, v88, v215
	v_cvt_pk_bf16_f32 v87, v87, v88
	global_store_dwordx2 v[98:99], v[86:87], off offset:1024
	v_cndmask_b32_e32 v82, v83, v82, vcc
	v_div_scale_f32 v83, s[0:1], v82, v82, 1.0
	v_rcp_f32_e32 v84, v83
	s_lshl_b64 s[0:1], s[10:11], 11
	v_mul_f32_e32 v94, v94, v100
	v_mul_f32_e32 v95, v95, v100
	v_fma_f32 v85, -v83, v84, 1.0
	v_fmac_f32_e32 v84, v85, v84
	v_div_scale_f32 v85, vcc, 1.0, v82, 1.0
	v_mul_f32_e32 v86, v85, v84
	v_fma_f32 v87, -v83, v86, v85
	v_fmac_f32_e32 v86, v87, v84
	v_fma_f32 v83, -v83, v86, v85
	v_div_fmas_f32 v83, v83, v84, v86
	v_div_fixup_f32 v84, v83, v82, 1.0
	v_mul_f32_e32 v66, v66, v84
	v_mul_f32_e32 v67, v67, v84
	v_mul_f32_e32 v66, v66, v216
	v_mul_f32_e32 v67, v67, v217
	v_cvt_pk_bf16_f32 v66, v66, v67
	v_mul_f32_e32 v67, v68, v84
	v_lshl_add_u64 v[82:83], v[150:151], 0, s[0:1]
	v_mul_f32_e32 v67, v67, v218
	v_mul_f32_e32 v68, v69, v84
	v_mul_f32_e32 v68, v68, v219
	v_cvt_pk_bf16_f32 v67, v67, v68
	global_store_dwordx2 v[82:83], v[66:67], off offset:1536
	v_fmamk_f32 v66, v160, 0x3a800000, v194
	v_cmp_gt_f32_e32 vcc, s61, v66
	v_mul_f32_e32 v67, 0x4f800000, v66
	v_mul_f32_e32 v70, v70, v84
	v_cndmask_b32_e32 v66, v66, v67, vcc
	v_sqrt_f32_e32 v67, v66
	v_mul_f32_e32 v71, v71, v84
	v_mul_f32_e32 v70, v70, v212
	v_mul_f32_e32 v71, v71, v213
	v_add_u32_e32 v68, -1, v67
	v_fma_f32 v69, -v68, v67, v66
	v_cmp_ge_f32_e64 s[0:1], 0, v69
	v_add_u32_e32 v69, 1, v67
	v_cvt_pk_bf16_f32 v70, v70, v71
	v_mul_f32_e32 v71, v72, v84
	v_cndmask_b32_e64 v68, v67, v68, s[0:1]
	v_fma_f32 v67, -v69, v67, v66
	v_cmp_lt_f32_e64 s[0:1], 0, v67
	v_mul_f32_e32 v71, v71, v214
	v_mul_f32_e32 v72, v73, v84
	v_cndmask_b32_e64 v67, v68, v69, s[0:1]
	v_mul_f32_e32 v68, 0x37800000, v67
	v_cndmask_b32_e32 v67, v67, v68, vcc
	v_cmp_class_f32_e32 vcc, v66, v195
	v_mul_f32_e32 v72, v72, v215
	v_cvt_pk_bf16_f32 v71, v71, v72
	global_store_dwordx2 v[82:83], v[70:71], off offset:1024
	v_cndmask_b32_e32 v66, v67, v66, vcc
	v_div_scale_f32 v67, s[0:1], v66, v66, 1.0
	v_rcp_f32_e32 v68, v67
	s_lshl_b64 s[0:1], s[8:9], 11
	v_mul_f32_e32 v78, v78, v84
	v_mul_f32_e32 v79, v79, v84
	v_fma_f32 v69, -v67, v68, 1.0
	v_fmac_f32_e32 v68, v69, v68
	v_div_scale_f32 v69, vcc, 1.0, v66, 1.0
	v_mul_f32_e32 v70, v69, v68
	v_fma_f32 v71, -v67, v70, v69
	v_fmac_f32_e32 v70, v71, v68
	v_fma_f32 v67, -v67, v70, v69
	v_div_fmas_f32 v67, v67, v68, v70
	v_div_fixup_f32 v68, v67, v66, 1.0
	v_mul_f32_e32 v50, v50, v68
	v_mul_f32_e32 v51, v51, v68
	v_mul_f32_e32 v50, v50, v216
	v_mul_f32_e32 v51, v51, v217
	v_cvt_pk_bf16_f32 v50, v50, v51
	v_mul_f32_e32 v51, v52, v68
	v_lshl_add_u64 v[66:67], v[150:151], 0, s[0:1]
	v_mul_f32_e32 v51, v51, v218
	v_mul_f32_e32 v52, v53, v68
	v_mul_f32_e32 v52, v52, v219
	v_cvt_pk_bf16_f32 v51, v51, v52
	global_store_dwordx2 v[66:67], v[50:51], off offset:1536
	v_fmamk_f32 v50, v159, 0x3a800000, v194
	v_cmp_gt_f32_e32 vcc, s61, v50
	v_mul_f32_e32 v51, 0x4f800000, v50
	v_mul_f32_e32 v54, v54, v68
	v_cndmask_b32_e32 v50, v50, v51, vcc
	v_sqrt_f32_e32 v51, v50
	v_mul_f32_e32 v55, v55, v68
	v_mul_f32_e32 v54, v54, v212
	v_mul_f32_e32 v55, v55, v213
	v_add_u32_e32 v52, -1, v51
	v_fma_f32 v53, -v52, v51, v50
	v_cmp_ge_f32_e64 s[0:1], 0, v53
	v_add_u32_e32 v53, 1, v51
	v_cvt_pk_bf16_f32 v54, v54, v55
	v_mul_f32_e32 v55, v56, v68
	v_cndmask_b32_e64 v52, v51, v52, s[0:1]
	v_fma_f32 v51, -v53, v51, v50
	v_cmp_lt_f32_e64 s[0:1], 0, v51
	v_mul_f32_e32 v55, v55, v214
	v_mul_f32_e32 v56, v57, v68
	v_cndmask_b32_e64 v51, v52, v53, s[0:1]
	v_mul_f32_e32 v52, 0x37800000, v51
	v_cndmask_b32_e32 v51, v51, v52, vcc
	v_cmp_class_f32_e32 vcc, v50, v195
	v_mul_f32_e32 v56, v56, v215
	v_cvt_pk_bf16_f32 v55, v55, v56
	global_store_dwordx2 v[66:67], v[54:55], off offset:1024
	v_cndmask_b32_e32 v50, v51, v50, vcc
	v_div_scale_f32 v51, s[0:1], v50, v50, 1.0
	v_rcp_f32_e32 v52, v51
	s_lshl_b64 s[0:1], s[6:7], 11
	v_mul_f32_e32 v62, v62, v68
	v_mul_f32_e32 v63, v63, v68
	v_fma_f32 v53, -v51, v52, 1.0
	v_fmac_f32_e32 v52, v53, v52
	v_div_scale_f32 v53, vcc, 1.0, v50, 1.0
	v_mul_f32_e32 v54, v53, v52
	v_fma_f32 v55, -v51, v54, v53
	v_fmac_f32_e32 v54, v55, v52
	v_fma_f32 v51, -v51, v54, v53
	v_div_fmas_f32 v51, v51, v52, v54
	v_div_fixup_f32 v52, v51, v50, 1.0
	v_mul_f32_e32 v26, v26, v52
	v_mul_f32_e32 v27, v27, v52
	v_mul_f32_e32 v26, v26, v216
	v_mul_f32_e32 v27, v27, v217
	v_cvt_pk_bf16_f32 v26, v26, v27
	v_mul_f32_e32 v27, v28, v52
	v_lshl_add_u64 v[50:51], v[150:151], 0, s[0:1]
	v_mul_f32_e32 v27, v27, v218
	v_mul_f32_e32 v28, v29, v52
	v_mul_f32_e32 v28, v28, v219
	v_cvt_pk_bf16_f32 v27, v27, v28
	global_store_dwordx2 v[50:51], v[26:27], off offset:1536
	v_fmamk_f32 v26, v158, 0x3a800000, v194
	v_cmp_gt_f32_e32 vcc, s61, v26
	v_mul_f32_e32 v27, 0x4f800000, v26
	v_mul_f32_e32 v34, v34, v52
	v_cndmask_b32_e32 v26, v26, v27, vcc
	v_sqrt_f32_e32 v27, v26
	v_mul_f32_e32 v35, v35, v52
	v_mul_f32_e32 v34, v212, v34
	v_mul_f32_e32 v35, v213, v35
	v_add_u32_e32 v28, -1, v27
	v_fma_f32 v29, -v28, v27, v26
	v_cmp_ge_f32_e64 s[0:1], 0, v29
	v_add_u32_e32 v29, 1, v27
	v_cvt_pk_bf16_f32 v34, v34, v35
	v_mul_f32_e32 v35, v36, v52
	v_cndmask_b32_e64 v28, v27, v28, s[0:1]
	v_fma_f32 v27, -v29, v27, v26
	v_cmp_lt_f32_e64 s[0:1], 0, v27
	v_mul_f32_e32 v35, v214, v35
	v_mul_f32_e32 v36, v37, v52
	v_cndmask_b32_e64 v27, v28, v29, s[0:1]
	v_mul_f32_e32 v28, 0x37800000, v27
	v_cndmask_b32_e32 v27, v27, v28, vcc
	v_cmp_class_f32_e32 vcc, v26, v195
	v_mul_f32_e32 v36, v215, v36
	v_cvt_pk_bf16_f32 v35, v35, v36
	global_store_dwordx2 v[50:51], v[34:35], off offset:1024
	v_cndmask_b32_e32 v26, v27, v26, vcc
	v_div_scale_f32 v27, s[0:1], v26, v26, 1.0
	v_rcp_f32_e32 v28, v27
	s_lshl_b64 s[0:1], s[4:5], 11
	v_mul_f32_e32 v46, v46, v52
	v_mul_f32_e32 v47, v47, v52
	v_fma_f32 v29, -v27, v28, 1.0
	v_fmac_f32_e32 v28, v29, v28
	v_div_scale_f32 v29, vcc, 1.0, v26, 1.0
	v_mul_f32_e32 v34, v29, v28
	v_fma_f32 v35, -v27, v34, v29
	v_fmac_f32_e32 v34, v35, v28
	v_fma_f32 v27, -v27, v34, v29
	v_div_fmas_f32 v27, v27, v28, v34
	v_div_fixup_f32 v28, v27, v26, 1.0
	v_mul_f32_e32 v2, v2, v28
	v_mul_f32_e32 v3, v3, v28
	v_mul_f32_e32 v2, v216, v2
	v_mul_f32_e32 v3, v217, v3
	v_cvt_pk_bf16_f32 v2, v2, v3
	v_mul_f32_e32 v3, v4, v28
	v_lshl_add_u64 v[26:27], v[150:151], 0, s[0:1]
	v_mul_f32_e32 v3, v218, v3
	v_mul_f32_e32 v4, v5, v28
	v_mul_f32_e32 v4, v219, v4
	v_cvt_pk_bf16_f32 v3, v3, v4
	global_store_dwordx2 v[26:27], v[2:3], off offset:1536
	v_cmp_gt_f32_e32 vcc, s61, v0
	v_mul_f32_e32 v2, 0x4f800000, v0
	v_mul_f32_e32 v6, v6, v28
	v_cndmask_b32_e32 v0, v0, v2, vcc
	v_sqrt_f32_e32 v2, v0
	v_mul_f32_e32 v7, v7, v28
	v_mul_f32_e32 v6, v212, v6
	v_mul_f32_e32 v7, v213, v7
	v_add_u32_e32 v3, -1, v2
	v_fma_f32 v4, -v3, v2, v0
	v_cmp_ge_f32_e64 s[0:1], 0, v4
	v_add_u32_e32 v4, 1, v2
	v_cvt_pk_bf16_f32 v6, v6, v7
	v_mul_f32_e32 v7, v8, v28
	v_cndmask_b32_e64 v3, v2, v3, s[0:1]
	v_fma_f32 v2, -v4, v2, v0
	v_cmp_lt_f32_e64 s[0:1], 0, v2
	v_mul_f32_e32 v7, v214, v7
	v_mul_f32_e32 v8, v9, v28
	v_cndmask_b32_e64 v2, v3, v4, s[0:1]
	v_mul_f32_e32 v3, 0x37800000, v2
	v_cndmask_b32_e32 v2, v2, v3, vcc
	v_cmp_class_f32_e32 vcc, v0, v195
	v_mul_f32_e32 v8, v215, v8
	v_cvt_pk_bf16_f32 v7, v7, v8
	global_store_dwordx2 v[26:27], v[6:7], off offset:1024
	v_cndmask_b32_e32 v0, v2, v0, vcc
	v_div_scale_f32 v2, s[0:1], v0, v0, 1.0
	v_rcp_f32_e32 v3, v2
	v_mul_f32_e32 v14, v14, v28
	v_mul_f32_e32 v15, v15, v28
	v_mul_f32_e32 v110, v110, v204
	v_fma_f32 v4, -v2, v3, 1.0
	v_fmac_f32_e32 v3, v4, v3
	v_div_scale_f32 v4, vcc, 1.0, v0, 1.0
	v_mul_f32_e32 v5, v4, v3
	v_fma_f32 v6, -v2, v5, v4
	v_fmac_f32_e32 v5, v6, v3
	v_fma_f32 v2, -v2, v5, v4
	v_div_fmas_f32 v2, v2, v3, v5
	v_div_fixup_f32 v0, v2, v0, 1.0
	v_mul_f32_e32 v4, v38, v0
	v_mul_f32_e32 v5, v39, v0
	v_mul_f32_e32 v4, v204, v4
	v_mul_f32_e32 v5, v205, v5
	v_mul_f32_e32 v111, v111, v205
	v_mul_f32_e32 v94, v94, v204
	v_mul_f32_e32 v95, v95, v205
	v_mul_f32_e32 v78, v204, v78
	v_mul_f32_e32 v79, v205, v79
	v_mul_f32_e32 v62, v204, v62
	v_mul_f32_e32 v63, v205, v63
	v_mul_f32_e32 v46, v204, v46
	v_mul_f32_e32 v47, v205, v47
	v_mul_f32_e32 v14, v204, v14
	v_mul_f32_e32 v15, v205, v15
	v_cvt_pk_bf16_f32 v4, v4, v5
	v_mul_f32_e32 v5, v40, v0
	v_cvt_pk_bf16_f32 v110, v110, v111
	v_mul_f32_e32 v111, v112, v116
	v_cvt_pk_bf16_f32 v94, v94, v95
	v_mul_f32_e32 v95, v96, v100
	v_cvt_pk_bf16_f32 v78, v78, v79
	v_mul_f32_e32 v79, v80, v84
	v_cvt_pk_bf16_f32 v62, v62, v63
	v_mul_f32_e32 v63, v64, v68
	v_cvt_pk_bf16_f32 v46, v46, v47
	v_mul_f32_e32 v47, v48, v52
	v_cvt_pk_bf16_f32 v14, v14, v15
	v_mul_f32_e32 v15, v16, v28
	s_lshl_b64 s[0:1], s[2:3], 11
	v_mul_f32_e32 v5, v206, v5
	v_mul_f32_e32 v6, v41, v0
	v_mul_f32_e32 v111, v111, v206
	v_mul_f32_e32 v112, v113, v116
	v_mul_f32_e32 v95, v95, v206
	v_mul_f32_e32 v96, v97, v100
	v_mul_f32_e32 v79, v206, v79
	v_mul_f32_e32 v80, v81, v84
	v_mul_f32_e32 v63, v206, v63
	v_mul_f32_e32 v64, v65, v68
	v_mul_f32_e32 v47, v206, v47
	v_mul_f32_e32 v48, v49, v52
	v_mul_f32_e32 v15, v206, v15
	v_mul_f32_e32 v16, v17, v28
	v_lshl_add_u64 v[2:3], v[150:151], 0, s[0:1]
	v_mul_f32_e32 v6, v207, v6
	v_cvt_pk_bf16_f32 v5, v5, v6
	v_cvt_pk_bf16_f32 v127, v127, v128
	global_store_dwordx2 v[164:165], v[126:127], off
	v_mul_f32_e32 v112, v112, v207
	v_cvt_pk_bf16_f32 v111, v111, v112
	global_store_dwordx2 v[114:115], v[110:111], off
	v_mul_f32_e32 v96, v96, v207
	v_cvt_pk_bf16_f32 v95, v95, v96
	global_store_dwordx2 v[98:99], v[94:95], off
	v_mul_f32_e32 v80, v207, v80
	v_cvt_pk_bf16_f32 v79, v79, v80
	global_store_dwordx2 v[82:83], v[78:79], off
	v_mul_f32_e32 v64, v207, v64
	v_cvt_pk_bf16_f32 v63, v63, v64
	global_store_dwordx2 v[66:67], v[62:63], off
	v_mul_f32_e32 v48, v207, v48
	v_cvt_pk_bf16_f32 v47, v47, v48
	global_store_dwordx2 v[50:51], v[46:47], off
	v_mul_f32_e32 v16, v207, v16
	v_cvt_pk_bf16_f32 v15, v15, v16
	global_store_dwordx2 v[26:27], v[14:15], off
	global_store_dwordx2 v[2:3], v[4:5], off
	v_mul_f32_e32 v4, v30, v0
	v_mul_f32_e32 v5, v31, v0
	v_mul_f32_e32 v106, v106, v116
	v_mul_f32_e32 v107, v107, v116
	v_mul_f32_e32 v90, v90, v100
	v_mul_f32_e32 v91, v91, v100
	v_mul_f32_e32 v74, v74, v84
	v_mul_f32_e32 v75, v75, v84
	v_mul_f32_e32 v58, v58, v68
	v_mul_f32_e32 v59, v59, v68
	v_mul_f32_e32 v42, v42, v52
	v_mul_f32_e32 v43, v43, v52
	v_mul_f32_e32 v10, v10, v28
	v_mul_f32_e32 v11, v11, v28
	v_mul_f32_e32 v4, v208, v4
	v_mul_f32_e32 v5, v209, v5
	v_mul_f32_e32 v122, v122, v208
	v_mul_f32_e32 v123, v123, v209
	v_mul_f32_e32 v106, v106, v208
	v_mul_f32_e32 v107, v107, v209
	v_mul_f32_e32 v90, v90, v208
	v_mul_f32_e32 v91, v91, v209
	v_mul_f32_e32 v74, v74, v208
	v_mul_f32_e32 v75, v75, v209
	v_mul_f32_e32 v58, v208, v58
	v_mul_f32_e32 v59, v209, v59
	v_mul_f32_e32 v42, v208, v42
	v_mul_f32_e32 v43, v209, v43
	v_mul_f32_e32 v10, v208, v10
	v_mul_f32_e32 v11, v209, v11
	v_cvt_pk_bf16_f32 v4, v4, v5
	v_mul_f32_e32 v5, v32, v0
	v_cvt_pk_bf16_f32 v122, v122, v123
	v_mul_f32_e32 v123, v124, v167
	v_cvt_pk_bf16_f32 v106, v106, v107
	v_mul_f32_e32 v107, v108, v116
	v_cvt_pk_bf16_f32 v90, v90, v91
	v_mul_f32_e32 v91, v92, v100
	v_cvt_pk_bf16_f32 v74, v74, v75
	v_mul_f32_e32 v75, v76, v84
	v_cvt_pk_bf16_f32 v58, v58, v59
	v_mul_f32_e32 v59, v60, v68
	v_cvt_pk_bf16_f32 v42, v42, v43
	v_mul_f32_e32 v43, v44, v52
	v_cvt_pk_bf16_f32 v10, v10, v11
	v_mul_f32_e32 v11, v12, v28
	v_mul_f32_e32 v5, v210, v5
	v_mul_f32_e32 v6, v33, v0
	v_mul_f32_e32 v123, v123, v210
	v_mul_f32_e32 v124, v125, v167
	v_mul_f32_e32 v107, v107, v210
	v_mul_f32_e32 v108, v109, v116
	v_mul_f32_e32 v91, v91, v210
	v_mul_f32_e32 v92, v93, v100
	v_mul_f32_e32 v75, v75, v210
	v_mul_f32_e32 v76, v77, v84
	v_mul_f32_e32 v59, v210, v59
	v_mul_f32_e32 v60, v61, v68
	v_mul_f32_e32 v43, v210, v43
	v_mul_f32_e32 v44, v45, v52
	v_mul_f32_e32 v11, v210, v11
	v_mul_f32_e32 v12, v13, v28
	v_mul_f32_e32 v6, v211, v6
	v_cvt_pk_bf16_f32 v5, v5, v6
	v_mul_f32_e32 v124, v124, v211
	v_cvt_pk_bf16_f32 v123, v123, v124
	global_store_dwordx2 v[164:165], v[122:123], off offset:512
	v_mul_f32_e32 v108, v108, v211
	v_cvt_pk_bf16_f32 v107, v107, v108
	global_store_dwordx2 v[114:115], v[106:107], off offset:512
	v_mul_f32_e32 v92, v92, v211
	v_cvt_pk_bf16_f32 v91, v91, v92
	global_store_dwordx2 v[98:99], v[90:91], off offset:512
	v_mul_f32_e32 v76, v76, v211
	v_cvt_pk_bf16_f32 v75, v75, v76
	global_store_dwordx2 v[82:83], v[74:75], off offset:512
	v_mul_f32_e32 v60, v211, v60
	v_cvt_pk_bf16_f32 v59, v59, v60
	global_store_dwordx2 v[66:67], v[58:59], off offset:512
	v_mul_f32_e32 v44, v211, v44
	v_cvt_pk_bf16_f32 v43, v43, v44
	global_store_dwordx2 v[50:51], v[42:43], off offset:512
	v_mul_f32_e32 v12, v211, v12
	v_cvt_pk_bf16_f32 v11, v11, v12
	global_store_dwordx2 v[26:27], v[10:11], off offset:512
	global_store_dwordx2 v[2:3], v[4:5], off offset:512
	v_mul_f32_e32 v4, v22, v0
	v_mul_f32_e32 v5, v23, v0
	v_mul_f32_e32 v4, v212, v4
	v_mul_f32_e32 v5, v213, v5
	v_cvt_pk_bf16_f32 v4, v4, v5
	v_mul_f32_e32 v5, v24, v0
	v_mul_f32_e32 v5, v214, v5
	v_mul_f32_e32 v6, v25, v0
	v_mul_f32_e32 v6, v215, v6
	v_cvt_pk_bf16_f32 v5, v5, v6
	global_store_dwordx2 v[2:3], v[4:5], off offset:1024
	v_mul_f32_e32 v4, v18, v0
	v_mul_f32_e32 v5, v19, v0
	v_mul_f32_e32 v4, v216, v4
	v_mul_f32_e32 v5, v217, v5
	v_cvt_pk_bf16_f32 v4, v4, v5
	v_mul_f32_e32 v5, v20, v0
	v_mul_f32_e32 v5, v218, v5
	v_mul_f32_e32 v0, v21, v0
	s_cmp_gt_i32 s16, 0xffff
	v_mul_f32_e32 v0, v219, v0
	v_cvt_pk_bf16_f32 v5, v5, v0
	global_store_dwordx2 v[2:3], v[4:5], off offset:1536
	s_cbranch_scc0 .LBB0_672

.LBB0_948:
	s_or_b64 exec, exec, s[0:1]
	s_mov_b64 s[12:13], s[94:95]
	s_waitcnt lgkmcnt(0)
	s_barrier
	v_mov_b32_e32 v0, v1
	s_load_dwordx4 s[4:7], s[12:13], 0xb0
	s_load_dwordx2 s[10:11], s[12:13], 0xc0
	v_readlane_b32 s14, v254, 18
	v_mbcnt_lo_u32_b32 v0, -1, v0
	v_mbcnt_hi_u32_b32 v0, -1, v0
	v_add_u32_e32 v0, s93, v0
	v_readlane_b32 s15, v254, 19
	v_readfirstlane_b32 s0, v0
	s_ashr_i32 s0, s0, 6
	s_add_i32 s8, s0, s96
	s_cmp_lt_i32 s8, 0x10000
	s_cselect_b64 s[0:1], -1, 0
	v_and_b32_e32 v163, 63, v0
	v_cndmask_b32_e64 v0, 0, 1, s[0:1]
	s_mov_b64 s[2:3], -1
	s_andn2_b64 vcc, exec, s[14:15]
	v_cmp_ne_u32_e64 s[0:1], 1, v0
	s_cbranch_vccnz .LBB0_953
	s_and_b64 vcc, exec, s[0:1]
	s_cbranch_vccnz .LBB0_952
	v_and_b32_e32 v2, 64, v197
	v_add_u32_e32 v2, 64, v2
	v_xor_b32_e32 v3, 1, v197
	v_cmp_lt_i32_e32 vcc, v3, v2
	v_lshlrev_b32_e32 v0, 4, v163
	s_waitcnt lgkmcnt(0)
	v_lshl_add_u64 v[146:147], s[6:7], 0, v[0:1]
	v_cndmask_b32_e32 v3, v197, v3, vcc
	v_lshlrev_b32_e32 v172, 2, v3
	v_xor_b32_e32 v3, 2, v197
	v_cmp_lt_i32_e32 vcc, v3, v2
	v_lshl_add_u64 v[148:149], s[4:5], 0, v[0:1]
	s_mov_b32 s2, s8
	v_cndmask_b32_e32 v3, v197, v3, vcc
	v_lshlrev_b32_e32 v173, 2, v3
	v_xor_b32_e32 v3, 4, v197
	v_cmp_lt_i32_e32 vcc, v3, v2
	s_nop 1
	v_cndmask_b32_e32 v3, v197, v3, vcc
	v_lshlrev_b32_e32 v174, 2, v3
	v_xor_b32_e32 v3, 8, v197
	v_cmp_lt_i32_e32 vcc, v3, v2
	s_nop 1
	v_cndmask_b32_e32 v3, v197, v3, vcc
	v_lshlrev_b32_e32 v175, 2, v3
	v_xor_b32_e32 v3, 16, v197
	v_cmp_lt_i32_e32 vcc, v3, v2
	s_nop 1
	v_cndmask_b32_e32 v3, v197, v3, vcc
	v_lshlrev_b32_e32 v176, 2, v3
	v_xor_b32_e32 v3, 32, v197
	v_cmp_lt_i32_e32 vcc, v3, v2
	s_nop 1
	v_cndmask_b32_e32 v2, v197, v3, vcc
	v_lshlrev_b32_e32 v177, 2, v2
	global_load_dwordx4 v[204:207], v[148:149], off
	global_load_dwordx4 v[208:211], v[148:149], off offset:1024
	global_load_dwordx4 v[212:215], v[148:149], off offset:2048
	global_load_dwordx4 v[216:219], v[148:149], off offset:3072
.LBB0_951:
	s_ashr_i32 s3, s2, 31
	s_lshl_b64 s[4:5], s[2:3], 12
	v_lshl_add_u64 v[170:171], v[146:147], 0, s[4:5]
	global_load_dwordx4 v[126:129], v[170:171], off
	global_load_dwordx4 v[122:125], v[170:171], off offset:1024
	global_load_dwordx4 v[118:121], v[170:171], off offset:2048
	global_load_dwordx4 v[114:117], v[170:171], off offset:3072
	s_add_i32 s4, s2, s97
	s_ashr_i32 s5, s4, 31
	s_lshl_b64 s[14:15], s[4:5], 12
	v_lshl_add_u64 v[168:169], v[146:147], 0, s[14:15]
	global_load_dwordx4 v[110:113], v[168:169], off
	global_load_dwordx4 v[106:109], v[168:169], off offset:1024
	global_load_dwordx4 v[102:105], v[168:169], off offset:2048
	global_load_dwordx4 v[98:101], v[168:169], off offset:3072
	s_add_i32 s3, s4, s97
	s_add_i32 s4, s88, s2
	s_ashr_i32 s5, s4, 31
	s_lshl_b64 s[4:5], s[4:5], 12
	v_lshl_add_u64 v[160:161], v[146:147], 0, s[4:5]
	global_load_dwordx4 v[94:97], v[160:161], off
	global_load_dwordx4 v[90:93], v[160:161], off offset:1024
	global_load_dwordx4 v[86:89], v[160:161], off offset:2048
	global_load_dwordx4 v[82:85], v[160:161], off offset:3072
	s_add_i32 s4, s75, s2
	s_ashr_i32 s5, s4, 31
	s_lshl_b64 s[4:5], s[4:5], 12
	v_lshl_add_u64 v[158:159], v[146:147], 0, s[4:5]
	global_load_dwordx4 v[78:81], v[158:159], off
	global_load_dwordx4 v[74:77], v[158:159], off offset:1024
	global_load_dwordx4 v[70:73], v[158:159], off offset:2048
	global_load_dwordx4 v[66:69], v[158:159], off offset:3072
	s_add_i32 s4, s89, s2
	s_ashr_i32 s5, s4, 31
	s_lshl_b64 s[4:5], s[4:5], 12
	v_lshl_add_u64 v[156:157], v[146:147], 0, s[4:5]
	global_load_dwordx4 v[62:65], v[156:157], off
	global_load_dwordx4 v[58:61], v[156:157], off offset:1024
	global_load_dwordx4 v[54:57], v[156:157], off offset:2048
	global_load_dwordx4 v[50:53], v[156:157], off offset:3072
	s_add_i32 s4, s77, s2
	s_ashr_i32 s5, s4, 31
	s_lshl_b64 s[4:5], s[4:5], 12
	v_lshl_add_u64 v[154:155], v[146:147], 0, s[4:5]
	global_load_dwordx4 v[34:37], v[154:155], off
	global_load_dwordx4 v[26:29], v[154:155], off offset:1024
	global_load_dwordx4 v[22:25], v[154:155], off offset:2048
	global_load_dwordx4 v[18:21], v[154:155], off offset:3072
	s_add_i32 s4, s78, s2
	s_ashr_i32 s5, s4, 31
	s_lshl_b64 s[4:5], s[4:5], 12
	v_lshl_add_u64 v[150:151], v[146:147], 0, s[4:5]
	global_load_dwordx4 v[14:17], v[150:151], off
	global_load_dwordx4 v[10:13], v[150:151], off offset:1024
	global_load_dwordx4 v[6:9], v[150:151], off offset:2048
	global_load_dwordx4 v[2:5], v[150:151], off offset:3072
	s_add_i32 s3, s3, s97
	s_add_i32 s3, s3, s97
	s_add_i32 s3, s3, s97
	s_add_i32 s3, s3, s97
	s_add_i32 s2, s79, s2
	s_add_i32 s4, s3, s97
	s_ashr_i32 s3, s2, 31
	s_lshl_b64 s[2:3], s[2:3], 12
	v_lshl_add_u64 v[152:153], v[146:147], 0, s[2:3]
	global_load_dwordx4 v[46:49], v[152:153], off
	global_load_dwordx4 v[42:45], v[152:153], off offset:1024
	global_load_dwordx4 v[38:41], v[152:153], off offset:2048
	global_load_dwordx4 v[30:33], v[152:153], off offset:3072
	s_waitcnt vmcnt(31)
	v_pk_mul_f32 v[130:131], v[128:129], v[128:129]
	v_pk_mul_f32 v[132:133], v[126:127], v[126:127]
	s_waitcnt vmcnt(28)
	v_mul_f32_e32 v0, v114, v114
	v_pk_mov_b32 v[134:135], v[132:133], v[130:131] op_sel:[1,0]
	v_mov_b32_e32 v133, v131
	v_pk_add_f32 v[130:131], v[134:135], v[132:133]
	v_pk_mul_f32 v[132:133], v[124:125], v[124:125]
	v_pk_mul_f32 v[134:135], v[122:123], v[122:123]
	v_pk_add_f32 v[130:131], v[130:131], v[130:131] op_sel:[0,1] op_sel_hi:[1,0]
	v_pk_mov_b32 v[136:137], v[134:135], v[132:133] op_sel:[1,0]
	v_mov_b32_e32 v135, v133
	v_pk_add_f32 v[132:133], v[136:137], v[134:135]
	v_mul_f32_e32 v134, v115, v115
	v_pk_add_f32 v[132:133], v[132:133], v[132:133] op_sel:[0,1] op_sel_hi:[1,0]
	v_mov_b32_e32 v131, v0
	v_mov_b32_e32 v133, v134
	v_mul_f32_e32 v0, v119, v119
	v_mul_f32_e32 v135, v116, v116
	v_pk_add_f32 v[130:131], v[130:131], v[132:133]
	v_pk_fma_f32 v[132:133], v[118:119], v[118:119], v[0:1] op_sel_hi:[1,1,0]
	v_mul_f32_e32 v0, v121, v121
	v_mul_f32_e32 v136, v117, v117
	v_mov_b32_e32 v133, v135
	v_pk_fma_f32 v[134:135], v[120:121], v[120:121], v[0:1] op_sel_hi:[1,1,0]
	s_waitcnt vmcnt(24)
	v_mul_f32_e32 v0, v98, v98
	v_mov_b32_e32 v135, v136
	v_pk_add_f32 v[132:133], v[132:133], v[134:135]
	s_nop 0
	v_pk_add_f32 v[130:131], v[130:131], v[132:133]
	v_pk_mul_f32 v[132:133], v[110:111], v[110:111]
	v_add_f32_e32 v138, v130, v131
	v_pk_mul_f32 v[130:131], v[112:113], v[112:113]
	s_nop 0
	v_pk_mov_b32 v[134:135], v[132:133], v[130:131] op_sel:[1,0]
	v_mov_b32_e32 v133, v131
	v_pk_add_f32 v[130:131], v[134:135], v[132:133]
	v_pk_mul_f32 v[132:133], v[108:109], v[108:109]
	v_pk_mul_f32 v[134:135], v[106:107], v[106:107]
	v_pk_add_f32 v[130:131], v[130:131], v[130:131] op_sel:[0,1] op_sel_hi:[1,0]
	v_pk_mov_b32 v[136:137], v[134:135], v[132:133] op_sel:[1,0]
	v_mov_b32_e32 v135, v133
	v_pk_add_f32 v[132:133], v[136:137], v[134:135]
	v_mul_f32_e32 v134, v99, v99
	v_pk_add_f32 v[132:133], v[132:133], v[132:133] op_sel:[0,1] op_sel_hi:[1,0]
	v_mov_b32_e32 v131, v0
	v_mov_b32_e32 v133, v134
	v_mul_f32_e32 v0, v103, v103
	v_mul_f32_e32 v135, v100, v100
	v_pk_add_f32 v[130:131], v[130:131], v[132:133]
	v_pk_fma_f32 v[132:133], v[102:103], v[102:103], v[0:1] op_sel_hi:[1,1,0]
	v_mul_f32_e32 v0, v105, v105
	v_mul_f32_e32 v136, v101, v101
	v_mov_b32_e32 v133, v135
	v_pk_fma_f32 v[134:135], v[104:105], v[104:105], v[0:1] op_sel_hi:[1,1,0]
	s_waitcnt vmcnt(20)
	v_mul_f32_e32 v0, v82, v82
	v_mov_b32_e32 v135, v136
	v_pk_add_f32 v[132:133], v[132:133], v[134:135]
	s_nop 0
	v_pk_add_f32 v[130:131], v[130:131], v[132:133]
	v_pk_mul_f32 v[132:133], v[94:95], v[94:95]
	v_add_f32_e32 v139, v130, v131
	v_pk_mul_f32 v[130:131], v[96:97], v[96:97]
	s_nop 0
	v_pk_mov_b32 v[134:135], v[132:133], v[130:131] op_sel:[1,0]
	v_mov_b32_e32 v133, v131
	v_pk_add_f32 v[130:131], v[134:135], v[132:133]
	v_pk_mul_f32 v[132:133], v[92:93], v[92:93]
	v_pk_mul_f32 v[134:135], v[90:91], v[90:91]
	v_pk_add_f32 v[130:131], v[130:131], v[130:131] op_sel:[0,1] op_sel_hi:[1,0]
	v_pk_mov_b32 v[136:137], v[134:135], v[132:133] op_sel:[1,0]
	v_mov_b32_e32 v135, v133
	v_pk_add_f32 v[132:133], v[136:137], v[134:135]
	v_mul_f32_e32 v134, v83, v83
	v_pk_add_f32 v[132:133], v[132:133], v[132:133] op_sel:[0,1] op_sel_hi:[1,0]
	v_mov_b32_e32 v131, v0
	v_mov_b32_e32 v133, v134
	v_mul_f32_e32 v0, v87, v87
	v_mul_f32_e32 v135, v84, v84
	v_pk_add_f32 v[130:131], v[130:131], v[132:133]
	v_pk_fma_f32 v[132:133], v[86:87], v[86:87], v[0:1] op_sel_hi:[1,1,0]
	v_mul_f32_e32 v0, v89, v89
	v_mul_f32_e32 v136, v85, v85
	v_mov_b32_e32 v133, v135
	v_pk_fma_f32 v[134:135], v[88:89], v[88:89], v[0:1] op_sel_hi:[1,1,0]
	s_waitcnt vmcnt(16)
	v_mul_f32_e32 v0, v66, v66
	v_mov_b32_e32 v135, v136
	v_pk_add_f32 v[132:133], v[132:133], v[134:135]
	s_nop 0
	v_pk_add_f32 v[130:131], v[130:131], v[132:133]
	v_pk_mul_f32 v[132:133], v[78:79], v[78:79]
	v_add_f32_e32 v140, v130, v131
	v_pk_mul_f32 v[130:131], v[80:81], v[80:81]
	s_nop 0
	v_pk_mov_b32 v[134:135], v[132:133], v[130:131] op_sel:[1,0]
	v_mov_b32_e32 v133, v131
	v_pk_add_f32 v[130:131], v[134:135], v[132:133]
	v_pk_mul_f32 v[132:133], v[76:77], v[76:77]
	v_pk_mul_f32 v[134:135], v[74:75], v[74:75]
	v_pk_add_f32 v[130:131], v[130:131], v[130:131] op_sel:[0,1] op_sel_hi:[1,0]
	v_pk_mov_b32 v[136:137], v[134:135], v[132:133] op_sel:[1,0]
	v_mov_b32_e32 v135, v133
	v_pk_add_f32 v[132:133], v[136:137], v[134:135]
	v_mul_f32_e32 v134, v67, v67
	v_pk_add_f32 v[132:133], v[132:133], v[132:133] op_sel:[0,1] op_sel_hi:[1,0]
	v_mov_b32_e32 v131, v0
	v_mov_b32_e32 v133, v134
	v_mul_f32_e32 v0, v71, v71
	v_mul_f32_e32 v135, v68, v68
	v_pk_add_f32 v[130:131], v[130:131], v[132:133]
	v_pk_fma_f32 v[132:133], v[70:71], v[70:71], v[0:1] op_sel_hi:[1,1,0]
	v_mul_f32_e32 v0, v73, v73
	v_mul_f32_e32 v136, v69, v69
	v_mov_b32_e32 v133, v135
	v_pk_fma_f32 v[134:135], v[72:73], v[72:73], v[0:1] op_sel_hi:[1,1,0]
	s_waitcnt vmcnt(12)
	v_mul_f32_e32 v0, v50, v50
	v_mov_b32_e32 v135, v136
	v_pk_add_f32 v[132:133], v[132:133], v[134:135]
	s_nop 0
	v_pk_add_f32 v[130:131], v[130:131], v[132:133]
	v_pk_mul_f32 v[132:133], v[62:63], v[62:63]
	v_add_f32_e32 v141, v130, v131
	v_pk_mul_f32 v[130:131], v[64:65], v[64:65]
	s_nop 0
	v_pk_mov_b32 v[134:135], v[132:133], v[130:131] op_sel:[1,0]
	v_mov_b32_e32 v133, v131
	v_pk_add_f32 v[130:131], v[134:135], v[132:133]
	v_pk_mul_f32 v[132:133], v[60:61], v[60:61]
	v_pk_mul_f32 v[134:135], v[58:59], v[58:59]
	v_pk_add_f32 v[130:131], v[130:131], v[130:131] op_sel:[0,1] op_sel_hi:[1,0]
	v_pk_mov_b32 v[136:137], v[134:135], v[132:133] op_sel:[1,0]
	v_mov_b32_e32 v135, v133
	v_pk_add_f32 v[132:133], v[136:137], v[134:135]
	v_mul_f32_e32 v134, v51, v51
	v_pk_add_f32 v[132:133], v[132:133], v[132:133] op_sel:[0,1] op_sel_hi:[1,0]
	v_mov_b32_e32 v131, v0
	v_mov_b32_e32 v133, v134
	v_mul_f32_e32 v0, v55, v55
	v_mul_f32_e32 v135, v52, v52
	v_pk_add_f32 v[130:131], v[130:131], v[132:133]
	v_pk_fma_f32 v[132:133], v[54:55], v[54:55], v[0:1] op_sel_hi:[1,1,0]
	v_mul_f32_e32 v0, v57, v57
	v_mul_f32_e32 v136, v53, v53
	v_mov_b32_e32 v133, v135
	v_pk_fma_f32 v[134:135], v[56:57], v[56:57], v[0:1] op_sel_hi:[1,1,0]
	s_waitcnt vmcnt(8)
	v_mul_f32_e32 v0, v18, v18
	v_mov_b32_e32 v135, v136
	v_pk_add_f32 v[132:133], v[132:133], v[134:135]
	s_nop 0
	v_pk_add_f32 v[130:131], v[130:131], v[132:133]
	v_pk_mul_f32 v[132:133], v[34:35], v[34:35]
	v_add_f32_e32 v142, v130, v131
	v_pk_mul_f32 v[130:131], v[36:37], v[36:37]
	s_nop 0
	v_pk_mov_b32 v[134:135], v[132:133], v[130:131] op_sel:[1,0]
	v_mov_b32_e32 v133, v131
	v_pk_add_f32 v[130:131], v[134:135], v[132:133]
	v_pk_mul_f32 v[132:133], v[28:29], v[28:29]
	v_pk_mul_f32 v[134:135], v[26:27], v[26:27]
	v_pk_add_f32 v[130:131], v[130:131], v[130:131] op_sel:[0,1] op_sel_hi:[1,0]
	v_pk_mov_b32 v[136:137], v[134:135], v[132:133] op_sel:[1,0]
	v_mov_b32_e32 v135, v133
	v_pk_add_f32 v[132:133], v[136:137], v[134:135]
	v_mul_f32_e32 v134, v19, v19
	v_pk_add_f32 v[132:133], v[132:133], v[132:133] op_sel:[0,1] op_sel_hi:[1,0]
	v_mov_b32_e32 v131, v0
	v_mov_b32_e32 v133, v134
	v_mul_f32_e32 v0, v23, v23
	v_mul_f32_e32 v135, v20, v20
	v_pk_add_f32 v[130:131], v[130:131], v[132:133]
	v_pk_fma_f32 v[132:133], v[22:23], v[22:23], v[0:1] op_sel_hi:[1,1,0]
	v_mul_f32_e32 v0, v25, v25
	v_mul_f32_e32 v136, v21, v21
	v_mov_b32_e32 v133, v135
	v_pk_fma_f32 v[134:135], v[24:25], v[24:25], v[0:1] op_sel_hi:[1,1,0]
	s_waitcnt vmcnt(4)
	v_mul_f32_e32 v0, v2, v2
	v_mov_b32_e32 v135, v136
	v_pk_add_f32 v[132:133], v[132:133], v[134:135]
	s_nop 0
	v_pk_add_f32 v[130:131], v[130:131], v[132:133]
	v_pk_mul_f32 v[132:133], v[14:15], v[14:15]
	v_add_f32_e32 v143, v130, v131
	v_pk_mul_f32 v[130:131], v[16:17], v[16:17]
	s_nop 0
	v_pk_mov_b32 v[134:135], v[132:133], v[130:131] op_sel:[1,0]
	v_mov_b32_e32 v133, v131
	v_pk_add_f32 v[130:131], v[134:135], v[132:133]
	v_pk_mul_f32 v[132:133], v[12:13], v[12:13]
	v_pk_mul_f32 v[134:135], v[10:11], v[10:11]
	v_pk_add_f32 v[130:131], v[130:131], v[130:131] op_sel:[0,1] op_sel_hi:[1,0]
	v_pk_mov_b32 v[136:137], v[134:135], v[132:133] op_sel:[1,0]
	v_mov_b32_e32 v135, v133
	v_pk_add_f32 v[132:133], v[136:137], v[134:135]
	v_mul_f32_e32 v134, v3, v3
	v_pk_add_f32 v[132:133], v[132:133], v[132:133] op_sel:[0,1] op_sel_hi:[1,0]
	v_mov_b32_e32 v131, v0
	v_mov_b32_e32 v133, v134
	v_mul_f32_e32 v0, v7, v7
	v_mul_f32_e32 v135, v4, v4
	v_pk_add_f32 v[130:131], v[130:131], v[132:133]
	v_pk_fma_f32 v[132:133], v[6:7], v[6:7], v[0:1] op_sel_hi:[1,1,0]
	v_mul_f32_e32 v0, v9, v9
	v_mul_f32_e32 v136, v5, v5
	v_mov_b32_e32 v133, v135
	v_pk_fma_f32 v[134:135], v[8:9], v[8:9], v[0:1] op_sel_hi:[1,1,0]
	s_waitcnt vmcnt(0)
	v_mul_f32_e32 v0, v30, v30
	v_mov_b32_e32 v135, v136
	v_pk_add_f32 v[132:133], v[132:133], v[134:135]
	s_nop 0
	v_pk_add_f32 v[130:131], v[130:131], v[132:133]
	v_pk_mul_f32 v[132:133], v[46:47], v[46:47]
	v_add_f32_e32 v144, v130, v131
	v_pk_mul_f32 v[130:131], v[48:49], v[48:49]
	s_nop 0
	v_pk_mov_b32 v[134:135], v[132:133], v[130:131] op_sel:[1,0]
	v_mov_b32_e32 v133, v131
	v_pk_add_f32 v[130:131], v[134:135], v[132:133]
	v_pk_mul_f32 v[132:133], v[44:45], v[44:45]
	v_pk_mul_f32 v[134:135], v[42:43], v[42:43]
	v_pk_add_f32 v[130:131], v[130:131], v[130:131] op_sel:[0,1] op_sel_hi:[1,0]
	v_pk_mov_b32 v[136:137], v[134:135], v[132:133] op_sel:[1,0]
	v_mov_b32_e32 v135, v133
	v_pk_add_f32 v[132:133], v[136:137], v[134:135]
	v_mul_f32_e32 v134, v31, v31
	v_pk_add_f32 v[132:133], v[132:133], v[132:133] op_sel:[0,1] op_sel_hi:[1,0]
	v_mov_b32_e32 v131, v0
	v_mov_b32_e32 v133, v134
	v_mul_f32_e32 v0, v39, v39
	v_mul_f32_e32 v135, v32, v32
	v_pk_add_f32 v[130:131], v[130:131], v[132:133]
	v_pk_fma_f32 v[132:133], v[38:39], v[38:39], v[0:1] op_sel_hi:[1,1,0]
	v_mul_f32_e32 v0, v41, v41
	v_mul_f32_e32 v136, v33, v33
	v_mov_b32_e32 v133, v135
	v_pk_fma_f32 v[134:135], v[40:41], v[40:41], v[0:1] op_sel_hi:[1,1,0]
	s_nop 0
	v_mov_b32_e32 v135, v136
	v_pk_add_f32 v[132:133], v[132:133], v[134:135]
	ds_bpermute_b32 v134, v172, v142
	v_pk_add_f32 v[130:131], v[130:131], v[132:133]
	ds_bpermute_b32 v132, v172, v140
	v_add_f32_e32 v0, v130, v131
	ds_bpermute_b32 v130, v172, v138
	ds_bpermute_b32 v137, v172, v0
	ds_bpermute_b32 v131, v172, v139
	s_waitcnt lgkmcnt(3)
	v_add_f32_e32 v132, v140, v132
	ds_bpermute_b32 v133, v172, v141
	s_waitcnt lgkmcnt(3)
	v_add_f32_e32 v130, v138, v130
	s_waitcnt lgkmcnt(2)
	v_add_f32_e32 v0, v0, v137
	ds_bpermute_b32 v137, v173, v130
	s_waitcnt lgkmcnt(2)
	v_add_f32_e32 v131, v139, v131
	s_waitcnt lgkmcnt(1)
	v_add_f32_e32 v133, v141, v133
	v_add_f32_e32 v134, v142, v134
	ds_bpermute_b32 v135, v172, v143
	s_waitcnt lgkmcnt(1)
	v_add_f32_e32 v130, v130, v137
	ds_bpermute_b32 v137, v173, v131
	ds_bpermute_b32 v136, v172, v144
	s_waitcnt lgkmcnt(2)
	v_add_f32_e32 v135, v143, v135
	s_waitcnt lgkmcnt(1)
	v_add_f32_e32 v131, v131, v137
	ds_bpermute_b32 v137, v173, v132
	s_waitcnt lgkmcnt(1)
	v_add_f32_e32 v136, v144, v136
	s_waitcnt lgkmcnt(0)
	v_add_f32_e32 v132, v132, v137
	ds_bpermute_b32 v137, v173, v133
	ds_bpermute_b32 v200, v173, v134
	ds_bpermute_b32 v201, v173, v135
	ds_bpermute_b32 v202, v173, v136
	ds_bpermute_b32 v196, v173, v0
	s_waitcnt lgkmcnt(0)
	v_add_f32_e32 v133, v133, v137
	v_add_f32_e32 v134, v134, v200
	v_add_f32_e32 v135, v135, v201
	v_add_f32_e32 v136, v136, v202
	v_add_f32_e32 v0, v0, v196
	ds_bpermute_b32 v137, v174, v130
	ds_bpermute_b32 v200, v174, v131
	ds_bpermute_b32 v201, v174, v132
	ds_bpermute_b32 v202, v174, v133
	ds_bpermute_b32 v196, v174, v134
	ds_bpermute_b32 v162, v174, v135
	ds_bpermute_b32 v250, v174, v136
	ds_bpermute_b32 v251, v174, v0
	s_waitcnt lgkmcnt(0)
	v_add_f32_e32 v130, v130, v137
	v_add_f32_e32 v131, v131, v200
	v_add_f32_e32 v132, v132, v201
	v_add_f32_e32 v133, v133, v202
	v_add_f32_e32 v134, v134, v196
	v_add_f32_e32 v135, v135, v162
	v_add_f32_e32 v136, v136, v250
	v_add_f32_e32 v0, v0, v251
	ds_bpermute_b32 v137, v175, v130
	ds_bpermute_b32 v200, v175, v131
	ds_bpermute_b32 v201, v175, v132
	ds_bpermute_b32 v202, v175, v133
	ds_bpermute_b32 v196, v175, v134
	ds_bpermute_b32 v162, v175, v135
	ds_bpermute_b32 v250, v175, v136
	ds_bpermute_b32 v251, v175, v0
	s_waitcnt lgkmcnt(0)
	v_add_f32_e32 v130, v130, v137
	v_add_f32_e32 v131, v131, v200
	v_add_f32_e32 v132, v132, v201
	v_add_f32_e32 v133, v133, v202
	v_add_f32_e32 v134, v134, v196
	v_add_f32_e32 v135, v135, v162
	v_add_f32_e32 v136, v136, v250
	v_add_f32_e32 v0, v0, v251
	ds_bpermute_b32 v137, v176, v130
	ds_bpermute_b32 v200, v176, v131
	ds_bpermute_b32 v201, v176, v132
	ds_bpermute_b32 v202, v176, v133
	ds_bpermute_b32 v196, v176, v134
	ds_bpermute_b32 v162, v176, v135
	ds_bpermute_b32 v250, v176, v136
	ds_bpermute_b32 v251, v176, v0
	s_waitcnt lgkmcnt(0)
	v_add_f32_e32 v130, v130, v137
	v_add_f32_e32 v131, v131, v200
	v_add_f32_e32 v132, v132, v201
	v_add_f32_e32 v133, v133, v202
	v_add_f32_e32 v134, v134, v196
	v_add_f32_e32 v135, v135, v162
	v_add_f32_e32 v136, v136, v250
	v_add_f32_e32 v0, v0, v251
	ds_bpermute_b32 v220, v177, v130
	ds_bpermute_b32 v221, v177, v131
	ds_bpermute_b32 v222, v177, v132
	ds_bpermute_b32 v223, v177, v133
	ds_bpermute_b32 v224, v177, v134
	ds_bpermute_b32 v225, v177, v135
	ds_bpermute_b32 v226, v177, v136
	ds_bpermute_b32 v227, v177, v0
	s_waitcnt lgkmcnt(0)
	v_add_f32_e32 v164, v130, v220
	v_add_f32_e32 v165, v131, v221
	v_add_f32_e32 v182, v132, v222
	v_add_f32_e32 v181, v133, v223
	v_add_f32_e32 v180, v134, v224
	v_add_f32_e32 v179, v135, v225
	v_add_f32_e32 v178, v136, v226
	v_add_f32_e32 v0, v0, v227
	s_nop 0
	s_nop 0
	s_nop 0
	s_nop 0
	v_fmamk_f32 v164, v164, 0x3a800000, v194
	v_cmp_gt_f32_e32 vcc, s61, v164
	v_mul_f32_e32 v166, 0x4f800000, v164
	s_nop 0
	s_nop 0
	s_nop 0
	v_cndmask_b32_e32 v164, v164, v166, vcc
	v_sqrt_f32_e32 v166, v164
	s_nop 0
	s_nop 0
	s_nop 0
	v_add_u32_e32 v167, -1, v166
	v_fma_f32 v183, -v167, v166, v164
	v_cmp_ge_f32_e64 s[2:3], 0, v183
	v_add_u32_e32 v183, 1, v166
	s_nop 0
	s_nop 0
	s_nop 0
	v_cndmask_b32_e64 v167, v166, v167, s[2:3]
	v_fma_f32 v166, -v183, v166, v164
	v_cmp_lt_f32_e64 s[2:3], 0, v166
	s_nop 0
	s_nop 0
	s_nop 0
	v_cndmask_b32_e64 v166, v167, v183, s[2:3]
	v_mul_f32_e32 v167, 0x37800000, v166
	v_cndmask_b32_e32 v166, v166, v167, vcc
	v_cmp_class_f32_e32 vcc, v164, v195
	s_nop 0
	s_nop 0
	s_nop 0
	v_cndmask_b32_e32 v164, v166, v164, vcc
	v_div_scale_f32 v166, s[2:3], v164, v164, 1.0
	v_rcp_f32_e32 v167, v166
	s_nop 0
	s_nop 0
	s_nop 0
	v_fma_f32 v183, -v166, v167, 1.0
	v_fmac_f32_e32 v167, v183, v167
	v_div_scale_f32 v183, vcc, 1.0, v164, 1.0
	s_nop 0
	s_nop 0
	s_nop 0
	s_nop 0
	s_nop 0
	s_nop 0
	v_mul_f32_e32 v184, v183, v167
	v_fma_f32 v185, -v166, v184, v183
	v_fmac_f32_e32 v184, v185, v167
	v_fma_f32 v166, -v166, v184, v183
	v_div_fmas_f32 v166, v166, v167, v184
	v_div_fixup_f32 v164, v166, v164, 1.0
	v_pk_mul_f32 v[114:115], v[114:115], v[164:165] op_sel_hi:[1,0]
	v_pk_mul_f32 v[116:117], v[116:117], v[164:165] op_sel_hi:[1,0]
	v_pk_mul_f32 v[118:119], v[118:119], v[164:165] op_sel_hi:[1,0]
	v_pk_mul_f32 v[120:121], v[120:121], v[164:165] op_sel_hi:[1,0]
	v_fmamk_f32 v0, v0, 0x3a800000, v194
	v_pk_mul_f32 v[126:127], v[126:127], v[164:165] op_sel_hi:[1,0]
	v_pk_mul_f32 v[128:129], v[128:129], v[164:165] op_sel_hi:[1,0]
	v_pk_mul_f32 v[122:123], v[122:123], v[164:165] op_sel_hi:[1,0]
	v_pk_mul_f32 v[124:125], v[124:125], v[164:165] op_sel_hi:[1,0]
	s_nop 0
	v_pk_mul_f32 v[128:129], v[206:207], v[128:129]
	v_pk_mul_f32 v[126:127], v[204:205], v[126:127]
	s_nop 0
	v_pk_mul_f32 v[120:121], v[120:121], v[214:215]
	s_nop 0
	v_pk_mul_f32 v[116:117], v[116:117], v[218:219]
	v_pk_mul_f32 v[114:115], v[114:115], v[216:217]
	global_store_dwordx4 v[170:171], v[114:117], off offset:3072
	v_pk_mul_f32 v[118:119], v[118:119], v[212:213]
	global_store_dwordx4 v[170:171], v[118:121], off offset:2048
	v_fmamk_f32 v114, v165, 0x3a800000, v194
	v_cmp_gt_f32_e32 vcc, s61, v114
	v_mul_f32_e32 v115, 0x4f800000, v114
	global_store_dwordx4 v[170:171], v[126:129], off
	v_cndmask_b32_e32 v114, v114, v115, vcc
	v_sqrt_f32_e32 v115, v114
	v_pk_mul_f32 v[124:125], v[124:125], v[210:211]
	v_pk_mul_f32 v[122:123], v[122:123], v[208:209]
	global_store_dwordx4 v[170:171], v[122:125], off offset:1024
	v_add_u32_e32 v116, -1, v115
	v_fma_f32 v117, -v116, v115, v114
	v_cmp_ge_f32_e64 s[2:3], 0, v117
	v_add_u32_e32 v117, 1, v115
	s_nop 0
	v_cndmask_b32_e64 v116, v115, v116, s[2:3]
	v_fma_f32 v115, -v117, v115, v114
	v_cmp_lt_f32_e64 s[2:3], 0, v115
	s_nop 1
	v_cndmask_b32_e64 v115, v116, v117, s[2:3]
	v_mul_f32_e32 v116, 0x37800000, v115
	v_cndmask_b32_e32 v115, v115, v116, vcc
	v_cmp_class_f32_e32 vcc, v114, v195
	s_nop 1
	v_cndmask_b32_e32 v114, v115, v114, vcc
	v_div_scale_f32 v115, s[2:3], v114, v114, 1.0
	v_rcp_f32_e32 v116, v115
	s_nop 0
	v_fma_f32 v117, -v115, v116, 1.0
	v_fmac_f32_e32 v116, v117, v116
	v_div_scale_f32 v117, vcc, 1.0, v114, 1.0
	v_mul_f32_e32 v118, v117, v116
	v_fma_f32 v119, -v115, v118, v117
	v_fmac_f32_e32 v118, v119, v116
	v_fma_f32 v115, -v115, v118, v117
	v_div_fmas_f32 v115, v115, v116, v118
	v_div_fixup_f32 v114, v115, v114, 1.0
	v_pk_mul_f32 v[98:99], v[98:99], v[114:115] op_sel_hi:[1,0]
	v_pk_mul_f32 v[100:101], v[100:101], v[114:115] op_sel_hi:[1,0]
	v_pk_mul_f32 v[98:99], v[98:99], v[216:217]
	v_pk_mul_f32 v[100:101], v[100:101], v[218:219]
	global_store_dwordx4 v[168:169], v[98:101], off offset:3072
	v_pk_mul_f32 v[102:103], v[102:103], v[114:115] op_sel_hi:[1,0]
	v_pk_mul_f32 v[104:105], v[104:105], v[114:115] op_sel_hi:[1,0]
	v_fmamk_f32 v98, v182, 0x3a800000, v194
	v_cmp_gt_f32_e32 vcc, s61, v98
	v_mul_f32_e32 v99, 0x4f800000, v98
	v_pk_mul_f32 v[104:105], v[104:105], v[214:215]
	v_cndmask_b32_e32 v98, v98, v99, vcc
	v_sqrt_f32_e32 v99, v98
	v_pk_mul_f32 v[102:103], v[102:103], v[212:213]
	global_store_dwordx4 v[168:169], v[102:105], off offset:2048
	v_pk_mul_f32 v[110:111], v[110:111], v[114:115] op_sel_hi:[1,0]
	v_add_u32_e32 v100, -1, v99
	v_fma_f32 v101, -v100, v99, v98
	v_cmp_ge_f32_e64 s[2:3], 0, v101
	v_add_u32_e32 v101, 1, v99
	v_pk_mul_f32 v[112:113], v[112:113], v[114:115] op_sel_hi:[1,0]
	v_cndmask_b32_e64 v100, v99, v100, s[2:3]
	v_fma_f32 v99, -v101, v99, v98
	v_cmp_lt_f32_e64 s[2:3], 0, v99
	v_pk_mul_f32 v[112:113], v[206:207], v[112:113]
	v_pk_mul_f32 v[110:111], v[204:205], v[110:111]
	v_cndmask_b32_e64 v99, v100, v101, s[2:3]
	v_mul_f32_e32 v100, 0x37800000, v99
	v_cndmask_b32_e32 v99, v99, v100, vcc
	v_cmp_class_f32_e32 vcc, v98, v195
	global_store_dwordx4 v[168:169], v[110:113], off
	v_pk_mul_f32 v[106:107], v[106:107], v[114:115] op_sel_hi:[1,0]
	v_cndmask_b32_e32 v98, v99, v98, vcc
	v_div_scale_f32 v99, s[2:3], v98, v98, 1.0
	v_rcp_f32_e32 v100, v99
	v_pk_mul_f32 v[108:109], v[108:109], v[114:115] op_sel_hi:[1,0]
	v_pk_mul_f32 v[106:107], v[208:209], v[106:107]
	v_pk_mul_f32 v[108:109], v[210:211], v[108:109]
	v_fma_f32 v101, -v99, v100, 1.0
	v_fmac_f32_e32 v100, v101, v100
	v_div_scale_f32 v101, vcc, 1.0, v98, 1.0
	v_mul_f32_e32 v102, v101, v100
	v_fma_f32 v103, -v99, v102, v101
	v_fmac_f32_e32 v102, v103, v100
	v_fma_f32 v99, -v99, v102, v101
	v_div_fmas_f32 v99, v99, v100, v102
	v_div_fixup_f32 v98, v99, v98, 1.0
	v_pk_mul_f32 v[82:83], v[82:83], v[98:99] op_sel_hi:[1,0]
	v_pk_mul_f32 v[84:85], v[84:85], v[98:99] op_sel_hi:[1,0]
	v_pk_mul_f32 v[82:83], v[82:83], v[216:217]
	v_pk_mul_f32 v[84:85], v[84:85], v[218:219]
	global_store_dwordx4 v[160:161], v[82:85], off offset:3072
	v_pk_mul_f32 v[86:87], v[86:87], v[98:99] op_sel_hi:[1,0]
	v_pk_mul_f32 v[88:89], v[88:89], v[98:99] op_sel_hi:[1,0]
	v_fmamk_f32 v82, v181, 0x3a800000, v194
	v_cmp_gt_f32_e32 vcc, s61, v82
	v_mul_f32_e32 v83, 0x4f800000, v82
	v_pk_mul_f32 v[88:89], v[214:215], v[88:89]
	v_cndmask_b32_e32 v82, v82, v83, vcc
	v_sqrt_f32_e32 v83, v82
	v_pk_mul_f32 v[86:87], v[212:213], v[86:87]
	global_store_dwordx4 v[160:161], v[86:89], off offset:2048
	v_pk_mul_f32 v[94:95], v[94:95], v[98:99] op_sel_hi:[1,0]
	v_add_u32_e32 v84, -1, v83
	v_fma_f32 v85, -v84, v83, v82
	v_cmp_ge_f32_e64 s[2:3], 0, v85
	v_add_u32_e32 v85, 1, v83
	v_pk_mul_f32 v[96:97], v[96:97], v[98:99] op_sel_hi:[1,0]
	v_cndmask_b32_e64 v84, v83, v84, s[2:3]
	v_fma_f32 v83, -v85, v83, v82
	v_cmp_lt_f32_e64 s[2:3], 0, v83
	v_pk_mul_f32 v[96:97], v[206:207], v[96:97]
	v_pk_mul_f32 v[94:95], v[204:205], v[94:95]
	v_cndmask_b32_e64 v83, v84, v85, s[2:3]
	v_mul_f32_e32 v84, 0x37800000, v83
	v_cndmask_b32_e32 v83, v83, v84, vcc
	v_cmp_class_f32_e32 vcc, v82, v195
	global_store_dwordx4 v[160:161], v[94:97], off
	v_pk_mul_f32 v[90:91], v[90:91], v[98:99] op_sel_hi:[1,0]
	v_cndmask_b32_e32 v82, v83, v82, vcc
	v_div_scale_f32 v83, s[2:3], v82, v82, 1.0
	v_rcp_f32_e32 v84, v83
	v_pk_mul_f32 v[92:93], v[92:93], v[98:99] op_sel_hi:[1,0]
	v_pk_mul_f32 v[90:91], v[208:209], v[90:91]
	v_pk_mul_f32 v[92:93], v[210:211], v[92:93]
	v_fma_f32 v85, -v83, v84, 1.0
	v_fmac_f32_e32 v84, v85, v84
	v_div_scale_f32 v85, vcc, 1.0, v82, 1.0
	v_mul_f32_e32 v86, v85, v84
	v_fma_f32 v87, -v83, v86, v85
	v_fmac_f32_e32 v86, v87, v84
	v_fma_f32 v83, -v83, v86, v85
	v_div_fmas_f32 v83, v83, v84, v86
	v_div_fixup_f32 v82, v83, v82, 1.0
	v_pk_mul_f32 v[66:67], v[66:67], v[82:83] op_sel_hi:[1,0]
	v_pk_mul_f32 v[68:69], v[68:69], v[82:83] op_sel_hi:[1,0]
	v_pk_mul_f32 v[66:67], v[216:217], v[66:67]
	v_pk_mul_f32 v[68:69], v[218:219], v[68:69]
	global_store_dwordx4 v[158:159], v[66:69], off offset:3072
	v_pk_mul_f32 v[70:71], v[70:71], v[82:83] op_sel_hi:[1,0]
	v_pk_mul_f32 v[72:73], v[72:73], v[82:83] op_sel_hi:[1,0]
	v_fmamk_f32 v66, v180, 0x3a800000, v194
	v_cmp_gt_f32_e32 vcc, s61, v66
	v_mul_f32_e32 v67, 0x4f800000, v66
	v_pk_mul_f32 v[72:73], v[214:215], v[72:73]
	v_cndmask_b32_e32 v66, v66, v67, vcc
	v_sqrt_f32_e32 v67, v66
	v_pk_mul_f32 v[70:71], v[212:213], v[70:71]
	global_store_dwordx4 v[158:159], v[70:73], off offset:2048
	v_pk_mul_f32 v[78:79], v[78:79], v[82:83] op_sel_hi:[1,0]
	v_add_u32_e32 v68, -1, v67
	v_fma_f32 v69, -v68, v67, v66
	v_cmp_ge_f32_e64 s[2:3], 0, v69
	v_add_u32_e32 v69, 1, v67
	v_pk_mul_f32 v[80:81], v[80:81], v[82:83] op_sel_hi:[1,0]
	v_cndmask_b32_e64 v68, v67, v68, s[2:3]
	v_fma_f32 v67, -v69, v67, v66
	v_cmp_lt_f32_e64 s[2:3], 0, v67
	v_pk_mul_f32 v[80:81], v[206:207], v[80:81]
	v_pk_mul_f32 v[78:79], v[204:205], v[78:79]
	v_cndmask_b32_e64 v67, v68, v69, s[2:3]
	v_mul_f32_e32 v68, 0x37800000, v67
	v_cndmask_b32_e32 v67, v67, v68, vcc
	v_cmp_class_f32_e32 vcc, v66, v195
	global_store_dwordx4 v[158:159], v[78:81], off
	v_pk_mul_f32 v[74:75], v[74:75], v[82:83] op_sel_hi:[1,0]
	v_cndmask_b32_e32 v66, v67, v66, vcc
	v_div_scale_f32 v67, s[2:3], v66, v66, 1.0
	v_rcp_f32_e32 v68, v67
	v_pk_mul_f32 v[76:77], v[76:77], v[82:83] op_sel_hi:[1,0]
	v_pk_mul_f32 v[74:75], v[208:209], v[74:75]
	v_pk_mul_f32 v[76:77], v[210:211], v[76:77]
	v_fma_f32 v69, -v67, v68, 1.0
	v_fmac_f32_e32 v68, v69, v68
	v_div_scale_f32 v69, vcc, 1.0, v66, 1.0
	v_mul_f32_e32 v70, v69, v68
	v_fma_f32 v71, -v67, v70, v69
	v_fmac_f32_e32 v70, v71, v68
	v_fma_f32 v67, -v67, v70, v69
	v_div_fmas_f32 v67, v67, v68, v70
	v_div_fixup_f32 v66, v67, v66, 1.0
	v_pk_mul_f32 v[50:51], v[50:51], v[66:67] op_sel_hi:[1,0]
	v_pk_mul_f32 v[52:53], v[52:53], v[66:67] op_sel_hi:[1,0]
	v_pk_mul_f32 v[50:51], v[216:217], v[50:51]
	v_pk_mul_f32 v[52:53], v[218:219], v[52:53]
	global_store_dwordx4 v[156:157], v[50:53], off offset:3072
	v_pk_mul_f32 v[54:55], v[54:55], v[66:67] op_sel_hi:[1,0]
	v_pk_mul_f32 v[56:57], v[56:57], v[66:67] op_sel_hi:[1,0]
	v_fmamk_f32 v50, v179, 0x3a800000, v194
	v_cmp_gt_f32_e32 vcc, s61, v50
	v_mul_f32_e32 v51, 0x4f800000, v50
	v_pk_mul_f32 v[56:57], v[214:215], v[56:57]
	v_cndmask_b32_e32 v50, v50, v51, vcc
	v_sqrt_f32_e32 v51, v50
	v_pk_mul_f32 v[54:55], v[212:213], v[54:55]
	global_store_dwordx4 v[156:157], v[54:57], off offset:2048
	v_pk_mul_f32 v[62:63], v[62:63], v[66:67] op_sel_hi:[1,0]
	v_add_u32_e32 v52, -1, v51
	v_fma_f32 v53, -v52, v51, v50
	v_cmp_ge_f32_e64 s[2:3], 0, v53
	v_add_u32_e32 v53, 1, v51
	v_pk_mul_f32 v[64:65], v[64:65], v[66:67] op_sel_hi:[1,0]
	v_cndmask_b32_e64 v52, v51, v52, s[2:3]
	v_fma_f32 v51, -v53, v51, v50
	v_cmp_lt_f32_e64 s[2:3], 0, v51
	v_pk_mul_f32 v[64:65], v[206:207], v[64:65]
	v_pk_mul_f32 v[62:63], v[204:205], v[62:63]
	v_cndmask_b32_e64 v51, v52, v53, s[2:3]
	v_mul_f32_e32 v52, 0x37800000, v51
	v_cndmask_b32_e32 v51, v51, v52, vcc
	v_cmp_class_f32_e32 vcc, v50, v195
	global_store_dwordx4 v[156:157], v[62:65], off
	v_pk_mul_f32 v[58:59], v[58:59], v[66:67] op_sel_hi:[1,0]
	v_cndmask_b32_e32 v50, v51, v50, vcc
	v_div_scale_f32 v51, s[2:3], v50, v50, 1.0
	v_rcp_f32_e32 v52, v51
	v_pk_mul_f32 v[60:61], v[60:61], v[66:67] op_sel_hi:[1,0]
	v_pk_mul_f32 v[58:59], v[208:209], v[58:59]
	v_pk_mul_f32 v[60:61], v[210:211], v[60:61]
	v_fma_f32 v53, -v51, v52, 1.0
	v_fmac_f32_e32 v52, v53, v52
	v_div_scale_f32 v53, vcc, 1.0, v50, 1.0
	v_mul_f32_e32 v54, v53, v52
	v_fma_f32 v55, -v51, v54, v53
	v_fmac_f32_e32 v54, v55, v52
	v_fma_f32 v51, -v51, v54, v53
	v_div_fmas_f32 v51, v51, v52, v54
	v_div_fixup_f32 v50, v51, v50, 1.0
	v_pk_mul_f32 v[18:19], v[18:19], v[50:51] op_sel_hi:[1,0]
	v_pk_mul_f32 v[20:21], v[20:21], v[50:51] op_sel_hi:[1,0]
	v_pk_mul_f32 v[18:19], v[216:217], v[18:19]
	v_pk_mul_f32 v[20:21], v[218:219], v[20:21]
	global_store_dwordx4 v[154:155], v[18:21], off offset:3072
	v_pk_mul_f32 v[22:23], v[22:23], v[50:51] op_sel_hi:[1,0]
	v_pk_mul_f32 v[24:25], v[24:25], v[50:51] op_sel_hi:[1,0]
	v_fmamk_f32 v18, v178, 0x3a800000, v194
	v_cmp_gt_f32_e32 vcc, s61, v18
	v_mul_f32_e32 v19, 0x4f800000, v18
	v_pk_mul_f32 v[24:25], v[214:215], v[24:25]
	v_cndmask_b32_e32 v18, v18, v19, vcc
	v_sqrt_f32_e32 v19, v18
	v_pk_mul_f32 v[22:23], v[212:213], v[22:23]
	global_store_dwordx4 v[154:155], v[22:25], off offset:2048
	v_pk_mul_f32 v[34:35], v[34:35], v[50:51] op_sel_hi:[1,0]
	v_add_u32_e32 v20, -1, v19
	v_fma_f32 v21, -v20, v19, v18
	v_cmp_ge_f32_e64 s[2:3], 0, v21
	v_add_u32_e32 v21, 1, v19
	v_pk_mul_f32 v[36:37], v[36:37], v[50:51] op_sel_hi:[1,0]
	v_cndmask_b32_e64 v20, v19, v20, s[2:3]
	v_fma_f32 v19, -v21, v19, v18
	v_cmp_lt_f32_e64 s[2:3], 0, v19
	v_pk_mul_f32 v[36:37], v[206:207], v[36:37]
	v_pk_mul_f32 v[34:35], v[204:205], v[34:35]
	v_cndmask_b32_e64 v19, v20, v21, s[2:3]
	v_mul_f32_e32 v20, 0x37800000, v19
	v_cndmask_b32_e32 v19, v19, v20, vcc
	v_cmp_class_f32_e32 vcc, v18, v195
	global_store_dwordx4 v[154:155], v[34:37], off
	v_pk_mul_f32 v[26:27], v[26:27], v[50:51] op_sel_hi:[1,0]
	v_cndmask_b32_e32 v18, v19, v18, vcc
	v_div_scale_f32 v19, s[2:3], v18, v18, 1.0
	v_rcp_f32_e32 v20, v19
	v_pk_mul_f32 v[28:29], v[28:29], v[50:51] op_sel_hi:[1,0]
	v_pk_mul_f32 v[26:27], v[208:209], v[26:27]
	v_pk_mul_f32 v[28:29], v[210:211], v[28:29]
	v_fma_f32 v21, -v19, v20, 1.0
	v_fmac_f32_e32 v20, v21, v20
	v_div_scale_f32 v21, vcc, 1.0, v18, 1.0
	v_mul_f32_e32 v22, v21, v20
	v_fma_f32 v23, -v19, v22, v21
	v_fmac_f32_e32 v22, v23, v20
	v_fma_f32 v19, -v19, v22, v21
	v_div_fmas_f32 v19, v19, v20, v22
	v_div_fixup_f32 v18, v19, v18, 1.0
	v_pk_mul_f32 v[2:3], v[2:3], v[18:19] op_sel_hi:[1,0]
	v_pk_mul_f32 v[4:5], v[4:5], v[18:19] op_sel_hi:[1,0]
	v_pk_mul_f32 v[2:3], v[216:217], v[2:3]
	v_pk_mul_f32 v[4:5], v[218:219], v[4:5]
	global_store_dwordx4 v[150:151], v[2:5], off offset:3072
	v_cmp_gt_f32_e32 vcc, s61, v0
	v_pk_mul_f32 v[6:7], v[6:7], v[18:19] op_sel_hi:[1,0]
	v_mul_f32_e32 v2, 0x4f800000, v0
	v_cndmask_b32_e32 v0, v0, v2, vcc
	v_sqrt_f32_e32 v2, v0
	v_pk_mul_f32 v[8:9], v[8:9], v[18:19] op_sel_hi:[1,0]
	v_pk_mul_f32 v[6:7], v[212:213], v[6:7]
	v_pk_mul_f32 v[8:9], v[214:215], v[8:9]
	v_add_u32_e32 v3, -1, v2
	v_fma_f32 v4, -v3, v2, v0
	v_cmp_ge_f32_e64 s[2:3], 0, v4
	v_add_u32_e32 v4, 1, v2
	global_store_dwordx4 v[150:151], v[6:9], off offset:2048
	v_cndmask_b32_e64 v3, v2, v3, s[2:3]
	v_fma_f32 v2, -v4, v2, v0
	v_cmp_lt_f32_e64 s[2:3], 0, v2
	v_pk_mul_f32 v[14:15], v[14:15], v[18:19] op_sel_hi:[1,0]
	v_pk_mul_f32 v[16:17], v[16:17], v[18:19] op_sel_hi:[1,0]
	v_cndmask_b32_e64 v2, v3, v4, s[2:3]
	v_mul_f32_e32 v3, 0x37800000, v2
	v_cndmask_b32_e32 v2, v2, v3, vcc
	v_cmp_class_f32_e32 vcc, v0, v195
	v_pk_mul_f32 v[16:17], v[206:207], v[16:17]
	v_pk_mul_f32 v[14:15], v[204:205], v[14:15]
	v_cndmask_b32_e32 v0, v2, v0, vcc
	v_div_scale_f32 v2, s[2:3], v0, v0, 1.0
	v_rcp_f32_e32 v3, v2
	global_store_dwordx4 v[150:151], v[14:17], off
	v_pk_mul_f32 v[10:11], v[10:11], v[18:19] op_sel_hi:[1,0]
	v_pk_mul_f32 v[12:13], v[12:13], v[18:19] op_sel_hi:[1,0]
	v_fma_f32 v4, -v2, v3, 1.0
	v_fmac_f32_e32 v3, v4, v3
	v_div_scale_f32 v4, vcc, 1.0, v0, 1.0
	v_mul_f32_e32 v5, v4, v3
	v_fma_f32 v6, -v2, v5, v4
	v_fmac_f32_e32 v5, v6, v3
	v_fma_f32 v2, -v2, v5, v4
	v_div_fmas_f32 v2, v2, v3, v5
	v_div_fixup_f32 v0, v2, v0, 1.0
	v_pk_mul_f32 v[2:3], v[46:47], v[0:1] op_sel_hi:[1,0]
	v_pk_mul_f32 v[4:5], v[48:49], v[0:1] op_sel_hi:[1,0]
	v_pk_mul_f32 v[2:3], v[204:205], v[2:3]
	v_pk_mul_f32 v[4:5], v[206:207], v[4:5]
	global_store_dwordx4 v[152:153], v[2:5], off
	v_pk_mul_f32 v[12:13], v[210:211], v[12:13]
	v_pk_mul_f32 v[10:11], v[208:209], v[10:11]
	v_pk_mul_f32 v[2:3], v[42:43], v[0:1] op_sel_hi:[1,0]
	v_pk_mul_f32 v[4:5], v[44:45], v[0:1] op_sel_hi:[1,0]
	v_pk_mul_f32 v[2:3], v[208:209], v[2:3]
	v_pk_mul_f32 v[4:5], v[210:211], v[4:5]
	global_store_dwordx4 v[168:169], v[106:109], off offset:1024
	global_store_dwordx4 v[160:161], v[90:93], off offset:1024
	global_store_dwordx4 v[158:159], v[74:77], off offset:1024
	global_store_dwordx4 v[156:157], v[58:61], off offset:1024
	global_store_dwordx4 v[154:155], v[26:29], off offset:1024
	global_store_dwordx4 v[150:151], v[10:13], off offset:1024
	global_store_dwordx4 v[152:153], v[2:5], off offset:1024
	s_add_i32 s2, s4, s97
	s_cmp_lt_i32 s2, 0x10000
	v_pk_mul_f32 v[2:3], v[38:39], v[0:1] op_sel_hi:[1,0]
	v_pk_mul_f32 v[4:5], v[40:41], v[0:1] op_sel_hi:[1,0]
	v_pk_mul_f32 v[2:3], v[212:213], v[2:3]
	v_pk_mul_f32 v[4:5], v[214:215], v[4:5]
	global_store_dwordx4 v[152:153], v[2:5], off offset:2048
	s_nop 1
	v_pk_mul_f32 v[2:3], v[30:31], v[0:1] op_sel_hi:[1,0]
	v_pk_mul_f32 v[4:5], v[32:33], v[0:1] op_sel_hi:[1,0]
	v_pk_mul_f32 v[2:3], v[216:217], v[2:3]
	v_pk_mul_f32 v[4:5], v[218:219], v[4:5]
	global_store_dwordx4 v[152:153], v[2:5], off offset:3072
	s_cbranch_scc1 .LBB0_951

.LBB0_953:
	s_andn2_b64 vcc, exec, s[2:3]
	s_cbranch_vccnz .LBB0_957
	s_and_b64 vcc, exec, s[0:1]
	s_cbranch_vccnz .LBB0_957
	v_and_b32_e32 v2, 64, v197
	v_add_u32_e32 v2, 64, v2
	v_xor_b32_e32 v3, 1, v197
	v_cmp_lt_i32_e32 vcc, v3, v2
	s_load_dwordx2 s[0:1], s[12:13], 0x10
	v_lshlrev_b32_e32 v0, 4, v163
	v_cndmask_b32_e32 v3, v197, v3, vcc
	v_lshlrev_b32_e32 v152, 2, v3
	v_xor_b32_e32 v3, 2, v197
	v_cmp_lt_i32_e32 vcc, v3, v2
	s_waitcnt lgkmcnt(0)
	v_lshl_add_u64 v[146:147], s[6:7], 0, v[0:1]
	v_cndmask_b32_e32 v3, v197, v3, vcc
	v_lshlrev_b32_e32 v153, 2, v3
	v_xor_b32_e32 v3, 4, v197
	v_cmp_lt_i32_e32 vcc, v3, v2
	s_nop 1
	v_cndmask_b32_e32 v3, v197, v3, vcc
	v_lshlrev_b32_e32 v154, 2, v3
	v_xor_b32_e32 v3, 8, v197
	v_cmp_lt_i32_e32 vcc, v3, v2
	s_nop 1
	v_cndmask_b32_e32 v3, v197, v3, vcc
	v_lshlrev_b32_e32 v155, 2, v3
	v_xor_b32_e32 v3, 16, v197
	v_cmp_lt_i32_e32 vcc, v3, v2
	s_nop 1
	v_cndmask_b32_e32 v3, v197, v3, vcc
	v_lshlrev_b32_e32 v156, 2, v3
	v_xor_b32_e32 v3, 32, v197
	v_cmp_lt_i32_e32 vcc, v3, v2
	s_nop 1
	v_cndmask_b32_e32 v2, v197, v3, vcc
	v_lshlrev_b32_e32 v157, 2, v2
	v_lshl_add_u64 v[2:3], s[0:1], 0, v[0:1]
	v_lshlrev_b32_e32 v0, 3, v163
	v_lshl_add_u64 v[148:149], v[2:3], 0, s[30:31]
	v_lshl_add_u64 v[150:151], s[10:11], 0, v[0:1]
	global_load_dwordx4 v[204:207], v[148:149], off
	global_load_dwordx4 v[208:211], v[148:149], off offset:1024
	global_load_dwordx4 v[212:215], v[148:149], off offset:2048
	global_load_dwordx4 v[216:219], v[148:149], off offset:3072
.LBB0_956:
	s_ashr_i32 s9, s8, 31
	s_lshl_b64 s[0:1], s[8:9], 12
	v_lshl_add_u64 v[2:3], v[146:147], 0, s[0:1]
	global_load_dwordx4 v[126:129], v[2:3], off
	global_load_dwordx4 v[122:125], v[2:3], off offset:1024
	global_load_dwordx4 v[118:121], v[2:3], off offset:2048
	global_load_dwordx4 v[114:117], v[2:3], off offset:3072
	s_add_i32 s16, s8, s97
	s_ashr_i32 s17, s16, 31
	s_lshl_b64 s[0:1], s[16:17], 12
	v_lshl_add_u64 v[2:3], v[146:147], 0, s[0:1]
	global_load_dwordx4 v[110:113], v[2:3], off
	global_load_dwordx4 v[106:109], v[2:3], off offset:1024
	global_load_dwordx4 v[102:105], v[2:3], off offset:2048
	global_load_dwordx4 v[98:101], v[2:3], off offset:3072
	s_add_i32 s14, s88, s8
	s_ashr_i32 s15, s14, 31
	s_lshl_b64 s[0:1], s[14:15], 12
	v_lshl_add_u64 v[2:3], v[146:147], 0, s[0:1]
	global_load_dwordx4 v[94:97], v[2:3], off
	global_load_dwordx4 v[90:93], v[2:3], off offset:1024
	global_load_dwordx4 v[86:89], v[2:3], off offset:2048
	global_load_dwordx4 v[82:85], v[2:3], off offset:3072
	s_add_i32 s12, s75, s8
	s_ashr_i32 s13, s12, 31
	s_lshl_b64 s[0:1], s[12:13], 12
	v_lshl_add_u64 v[2:3], v[146:147], 0, s[0:1]
	global_load_dwordx4 v[78:81], v[2:3], off
	global_load_dwordx4 v[74:77], v[2:3], off offset:1024
	global_load_dwordx4 v[70:73], v[2:3], off offset:2048
	global_load_dwordx4 v[66:69], v[2:3], off offset:3072
	s_add_i32 s10, s89, s8
	s_ashr_i32 s11, s10, 31
	s_lshl_b64 s[0:1], s[10:11], 12
	v_lshl_add_u64 v[2:3], v[146:147], 0, s[0:1]
	global_load_dwordx4 v[62:65], v[2:3], off
	global_load_dwordx4 v[58:61], v[2:3], off offset:1024
	global_load_dwordx4 v[54:57], v[2:3], off offset:2048
	global_load_dwordx4 v[50:53], v[2:3], off offset:3072
	s_add_i32 s6, s77, s8
	s_ashr_i32 s7, s6, 31
	s_lshl_b64 s[0:1], s[6:7], 12
	v_lshl_add_u64 v[2:3], v[146:147], 0, s[0:1]
	global_load_dwordx4 v[46:49], v[2:3], off
	global_load_dwordx4 v[42:45], v[2:3], off offset:1024
	global_load_dwordx4 v[34:37], v[2:3], off offset:2048
	global_load_dwordx4 v[26:29], v[2:3], off offset:3072
	s_add_i32 s4, s78, s8
	s_ashr_i32 s5, s4, 31
	s_lshl_b64 s[0:1], s[4:5], 12
	v_lshl_add_u64 v[2:3], v[146:147], 0, s[0:1]
	global_load_dwordx4 v[14:17], v[2:3], off
	global_load_dwordx4 v[10:13], v[2:3], off offset:1024
	global_load_dwordx4 v[6:9], v[2:3], off offset:2048
	s_nop 0
	global_load_dwordx4 v[2:5], v[2:3], off offset:3072
	s_add_i32 s2, s16, s97
	s_add_i32 s2, s2, s97
	s_add_i32 s2, s2, s97
	s_add_i32 s2, s2, s97
	s_add_i32 s18, s2, s97
	s_add_i32 s2, s79, s8
	s_ashr_i32 s3, s2, 31
	s_lshl_b64 s[0:1], s[2:3], 12
	v_lshl_add_u64 v[18:19], v[146:147], 0, s[0:1]
	global_load_dwordx4 v[38:41], v[18:19], off
	global_load_dwordx4 v[30:33], v[18:19], off offset:1024
	global_load_dwordx4 v[22:25], v[18:19], off offset:2048
	s_nop 0
	global_load_dwordx4 v[18:21], v[18:19], off offset:3072
	s_add_i32 s18, s18, s97
	s_waitcnt vmcnt(31)
	v_mul_f32_e32 v0, v127, v127
	v_mul_f32_e32 v130, v129, v129
	v_fmac_f32_e32 v0, v126, v126
	v_fmac_f32_e32 v130, v128, v128
	v_add_f32_e32 v0, v0, v130
	s_waitcnt vmcnt(30)
	v_mul_f32_e32 v130, v123, v123
	v_mul_f32_e32 v131, v125, v125
	v_fmac_f32_e32 v130, v122, v122
	v_fmac_f32_e32 v131, v124, v124
	v_add_f32_e32 v130, v130, v131
	v_add_f32_e32 v0, v0, v130
	s_waitcnt vmcnt(29)
	v_mul_f32_e32 v130, v119, v119
	v_mul_f32_e32 v131, v121, v121
	v_fmac_f32_e32 v130, v118, v118
	v_fmac_f32_e32 v131, v120, v120
	v_add_f32_e32 v130, v130, v131
	v_add_f32_e32 v0, v0, v130
	s_waitcnt vmcnt(28)
	v_mul_f32_e32 v130, v115, v115
	v_mul_f32_e32 v131, v117, v117
	v_fmac_f32_e32 v130, v114, v114
	v_fmac_f32_e32 v131, v116, v116
	v_add_f32_e32 v130, v130, v131
	v_add_f32_e32 v0, v0, v130
	s_waitcnt vmcnt(27)
	v_mul_f32_e32 v130, v111, v111
	v_mul_f32_e32 v131, v113, v113
	v_fmac_f32_e32 v130, v110, v110
	v_fmac_f32_e32 v131, v112, v112
	v_add_f32_e32 v130, v130, v131
	s_waitcnt vmcnt(26)
	v_mul_f32_e32 v131, v107, v107
	v_mul_f32_e32 v132, v109, v109
	v_fmac_f32_e32 v131, v106, v106
	v_fmac_f32_e32 v132, v108, v108
	v_add_f32_e32 v131, v131, v132
	v_add_f32_e32 v130, v130, v131
	s_waitcnt vmcnt(25)
	v_mul_f32_e32 v131, v103, v103
	v_mul_f32_e32 v132, v105, v105
	v_fmac_f32_e32 v131, v102, v102
	v_fmac_f32_e32 v132, v104, v104
	v_add_f32_e32 v131, v131, v132
	v_add_f32_e32 v130, v130, v131
	s_waitcnt vmcnt(24)
	v_mul_f32_e32 v131, v99, v99
	v_mul_f32_e32 v132, v101, v101
	v_fmac_f32_e32 v131, v98, v98
	v_fmac_f32_e32 v132, v100, v100
	v_add_f32_e32 v131, v131, v132
	v_add_f32_e32 v130, v130, v131
	s_waitcnt vmcnt(23)
	v_mul_f32_e32 v131, v95, v95
	v_mul_f32_e32 v132, v97, v97
	v_fmac_f32_e32 v131, v94, v94
	v_fmac_f32_e32 v132, v96, v96
	v_add_f32_e32 v131, v131, v132
	s_waitcnt vmcnt(22)
	v_mul_f32_e32 v132, v91, v91
	v_mul_f32_e32 v133, v93, v93
	v_fmac_f32_e32 v132, v90, v90
	v_fmac_f32_e32 v133, v92, v92
	v_add_f32_e32 v132, v132, v133
	v_add_f32_e32 v131, v131, v132
	s_waitcnt vmcnt(21)
	v_mul_f32_e32 v132, v87, v87
	v_mul_f32_e32 v133, v89, v89
	v_fmac_f32_e32 v132, v86, v86
	v_fmac_f32_e32 v133, v88, v88
	v_add_f32_e32 v132, v132, v133
	v_add_f32_e32 v131, v131, v132
	s_waitcnt vmcnt(20)
	v_mul_f32_e32 v132, v83, v83
	v_mul_f32_e32 v133, v85, v85
	v_fmac_f32_e32 v132, v82, v82
	v_fmac_f32_e32 v133, v84, v84
	v_add_f32_e32 v132, v132, v133
	v_add_f32_e32 v131, v131, v132
	s_waitcnt vmcnt(19)
	v_mul_f32_e32 v132, v79, v79
	v_mul_f32_e32 v133, v81, v81
	v_fmac_f32_e32 v132, v78, v78
	v_fmac_f32_e32 v133, v80, v80
	v_add_f32_e32 v132, v132, v133
	s_waitcnt vmcnt(18)
	v_mul_f32_e32 v133, v75, v75
	v_mul_f32_e32 v134, v77, v77
	v_fmac_f32_e32 v133, v74, v74
	v_fmac_f32_e32 v134, v76, v76
	v_add_f32_e32 v133, v133, v134
	v_add_f32_e32 v132, v132, v133
	s_waitcnt vmcnt(17)
	v_mul_f32_e32 v133, v71, v71
	v_mul_f32_e32 v134, v73, v73
	v_fmac_f32_e32 v133, v70, v70
	v_fmac_f32_e32 v134, v72, v72
	v_add_f32_e32 v133, v133, v134
	v_add_f32_e32 v132, v132, v133
	s_waitcnt vmcnt(16)
	v_mul_f32_e32 v133, v67, v67
	v_mul_f32_e32 v134, v69, v69
	v_fmac_f32_e32 v133, v66, v66
	v_fmac_f32_e32 v134, v68, v68
	v_add_f32_e32 v133, v133, v134
	v_add_f32_e32 v132, v132, v133
	s_waitcnt vmcnt(15)
	v_mul_f32_e32 v133, v63, v63
	v_mul_f32_e32 v134, v65, v65
	v_fmac_f32_e32 v133, v62, v62
	v_fmac_f32_e32 v134, v64, v64
	v_add_f32_e32 v133, v133, v134
	s_waitcnt vmcnt(14)
	v_mul_f32_e32 v134, v59, v59
	v_mul_f32_e32 v135, v61, v61
	v_fmac_f32_e32 v134, v58, v58
	v_fmac_f32_e32 v135, v60, v60
	v_add_f32_e32 v134, v134, v135
	v_add_f32_e32 v133, v133, v134
	s_waitcnt vmcnt(13)
	v_mul_f32_e32 v134, v55, v55
	v_mul_f32_e32 v135, v57, v57
	v_fmac_f32_e32 v134, v54, v54
	v_fmac_f32_e32 v135, v56, v56
	v_add_f32_e32 v134, v134, v135
	v_add_f32_e32 v133, v133, v134
	s_waitcnt vmcnt(12)
	v_mul_f32_e32 v134, v51, v51
	v_mul_f32_e32 v135, v53, v53
	v_fmac_f32_e32 v134, v50, v50
	v_fmac_f32_e32 v135, v52, v52
	v_add_f32_e32 v134, v134, v135
	v_add_f32_e32 v133, v133, v134
	s_waitcnt vmcnt(11)
	v_mul_f32_e32 v134, v47, v47
	v_mul_f32_e32 v135, v49, v49
	v_fmac_f32_e32 v134, v46, v46
	v_fmac_f32_e32 v135, v48, v48
	v_add_f32_e32 v134, v134, v135
	s_waitcnt vmcnt(10)
	v_mul_f32_e32 v135, v43, v43
	v_mul_f32_e32 v136, v45, v45
	v_fmac_f32_e32 v135, v42, v42
	v_fmac_f32_e32 v136, v44, v44
	v_add_f32_e32 v135, v135, v136
	v_add_f32_e32 v134, v134, v135
	s_waitcnt vmcnt(9)
	v_mul_f32_e32 v135, v35, v35
	v_mul_f32_e32 v136, v37, v37
	v_fmac_f32_e32 v135, v34, v34
	v_fmac_f32_e32 v136, v36, v36
	v_add_f32_e32 v135, v135, v136
	v_add_f32_e32 v134, v134, v135
	s_waitcnt vmcnt(8)
	v_mul_f32_e32 v135, v27, v27
	v_mul_f32_e32 v136, v29, v29
	v_fmac_f32_e32 v135, v26, v26
	v_fmac_f32_e32 v136, v28, v28
	v_add_f32_e32 v135, v135, v136
	v_add_f32_e32 v134, v134, v135
	s_waitcnt vmcnt(7)
	v_mul_f32_e32 v135, v15, v15
	v_mul_f32_e32 v136, v17, v17
	v_fmac_f32_e32 v135, v14, v14
	v_fmac_f32_e32 v136, v16, v16
	v_add_f32_e32 v135, v135, v136
	s_waitcnt vmcnt(6)
	v_mul_f32_e32 v136, v11, v11
	v_mul_f32_e32 v137, v13, v13
	v_fmac_f32_e32 v136, v10, v10
	v_fmac_f32_e32 v137, v12, v12
	v_add_f32_e32 v136, v136, v137
	v_add_f32_e32 v135, v135, v136
	s_waitcnt vmcnt(5)
	v_mul_f32_e32 v136, v7, v7
	v_mul_f32_e32 v137, v9, v9
	v_fmac_f32_e32 v136, v6, v6
	v_fmac_f32_e32 v137, v8, v8
	v_add_f32_e32 v136, v136, v137
	v_add_f32_e32 v135, v135, v136
	s_waitcnt vmcnt(4)
	v_mul_f32_e32 v136, v3, v3
	v_mul_f32_e32 v137, v5, v5
	v_fmac_f32_e32 v136, v2, v2
	v_fmac_f32_e32 v137, v4, v4
	v_add_f32_e32 v136, v136, v137
	v_add_f32_e32 v135, v135, v136
	s_waitcnt vmcnt(3)
	v_mul_f32_e32 v136, v39, v39
	v_mul_f32_e32 v137, v41, v41
	v_fmac_f32_e32 v136, v38, v38
	v_fmac_f32_e32 v137, v40, v40
	v_add_f32_e32 v136, v136, v137
	s_waitcnt vmcnt(2)
	v_mul_f32_e32 v137, v31, v31
	v_mul_f32_e32 v138, v33, v33
	v_fmac_f32_e32 v137, v30, v30
	v_fmac_f32_e32 v138, v32, v32
	v_add_f32_e32 v137, v137, v138
	v_add_f32_e32 v136, v136, v137
	s_waitcnt vmcnt(1)
	v_mul_f32_e32 v137, v23, v23
	v_mul_f32_e32 v138, v25, v25
	v_fmac_f32_e32 v137, v22, v22
	v_fmac_f32_e32 v138, v24, v24
	v_add_f32_e32 v137, v137, v138
	v_add_f32_e32 v136, v136, v137
	s_waitcnt vmcnt(0)
	v_mul_f32_e32 v137, v19, v19
	v_mul_f32_e32 v138, v21, v21
	v_fmac_f32_e32 v137, v18, v18
	v_fmac_f32_e32 v138, v20, v20
	v_add_f32_e32 v137, v137, v138
	v_add_f32_e32 v136, v136, v137
	ds_bpermute_b32 v137, v152, v0
	ds_bpermute_b32 v200, v152, v130
	ds_bpermute_b32 v201, v152, v131
	ds_bpermute_b32 v202, v152, v132
	ds_bpermute_b32 v196, v152, v133
	ds_bpermute_b32 v162, v152, v134
	ds_bpermute_b32 v250, v152, v135
	ds_bpermute_b32 v251, v152, v136
	s_waitcnt lgkmcnt(0)
	v_add_f32_e32 v0, v0, v137
	v_add_f32_e32 v130, v130, v200
	v_add_f32_e32 v131, v131, v201
	v_add_f32_e32 v132, v132, v202
	v_add_f32_e32 v133, v133, v196
	v_add_f32_e32 v134, v134, v162
	v_add_f32_e32 v135, v135, v250
	v_add_f32_e32 v136, v136, v251
	ds_bpermute_b32 v137, v153, v0
	ds_bpermute_b32 v200, v153, v130
	ds_bpermute_b32 v201, v153, v131
	ds_bpermute_b32 v202, v153, v132
	ds_bpermute_b32 v196, v153, v133
	ds_bpermute_b32 v162, v153, v134
	ds_bpermute_b32 v250, v153, v135
	ds_bpermute_b32 v251, v153, v136
	s_waitcnt lgkmcnt(0)
	v_add_f32_e32 v0, v0, v137
	v_add_f32_e32 v130, v130, v200
	v_add_f32_e32 v131, v131, v201
	v_add_f32_e32 v132, v132, v202
	v_add_f32_e32 v133, v133, v196
	v_add_f32_e32 v134, v134, v162
	v_add_f32_e32 v135, v135, v250
	v_add_f32_e32 v136, v136, v251
	ds_bpermute_b32 v137, v154, v0
	ds_bpermute_b32 v200, v154, v130
	ds_bpermute_b32 v201, v154, v131
	ds_bpermute_b32 v202, v154, v132
	ds_bpermute_b32 v196, v154, v133
	ds_bpermute_b32 v162, v154, v134
	ds_bpermute_b32 v250, v154, v135
	ds_bpermute_b32 v251, v154, v136
	s_waitcnt lgkmcnt(0)
	v_add_f32_e32 v0, v0, v137
	v_add_f32_e32 v130, v130, v200
	v_add_f32_e32 v131, v131, v201
	v_add_f32_e32 v132, v132, v202
	v_add_f32_e32 v133, v133, v196
	v_add_f32_e32 v134, v134, v162
	v_add_f32_e32 v135, v135, v250
	v_add_f32_e32 v136, v136, v251
	ds_bpermute_b32 v137, v155, v0
	ds_bpermute_b32 v200, v155, v130
	ds_bpermute_b32 v201, v155, v131
	ds_bpermute_b32 v202, v155, v132
	ds_bpermute_b32 v196, v155, v133
	ds_bpermute_b32 v162, v155, v134
	ds_bpermute_b32 v250, v155, v135
	ds_bpermute_b32 v251, v155, v136
	s_waitcnt lgkmcnt(0)
	v_add_f32_e32 v0, v0, v137
	v_add_f32_e32 v130, v130, v200
	v_add_f32_e32 v131, v131, v201
	v_add_f32_e32 v132, v132, v202
	v_add_f32_e32 v133, v133, v196
	v_add_f32_e32 v134, v134, v162
	v_add_f32_e32 v135, v135, v250
	v_add_f32_e32 v136, v136, v251
	ds_bpermute_b32 v137, v156, v0
	ds_bpermute_b32 v200, v156, v130
	ds_bpermute_b32 v201, v156, v131
	ds_bpermute_b32 v202, v156, v132
	ds_bpermute_b32 v196, v156, v133
	ds_bpermute_b32 v162, v156, v134
	ds_bpermute_b32 v250, v156, v135
	ds_bpermute_b32 v251, v156, v136
	s_waitcnt lgkmcnt(0)
	v_add_f32_e32 v0, v0, v137
	v_add_f32_e32 v130, v130, v200
	v_add_f32_e32 v131, v131, v201
	v_add_f32_e32 v132, v132, v202
	v_add_f32_e32 v133, v133, v196
	v_add_f32_e32 v134, v134, v162
	v_add_f32_e32 v135, v135, v250
	v_add_f32_e32 v136, v136, v251
	ds_bpermute_b32 v220, v157, v0
	ds_bpermute_b32 v221, v157, v130
	ds_bpermute_b32 v222, v157, v131
	ds_bpermute_b32 v223, v157, v132
	ds_bpermute_b32 v224, v157, v133
	ds_bpermute_b32 v225, v157, v134
	ds_bpermute_b32 v226, v157, v135
	ds_bpermute_b32 v227, v157, v136
	s_waitcnt lgkmcnt(0)
	v_add_f32_e32 v164, v0, v220
	v_add_f32_e32 v166, v130, v221
	v_add_f32_e32 v163, v131, v222
	v_add_f32_e32 v161, v132, v223
	v_add_f32_e32 v160, v133, v224
	v_add_f32_e32 v159, v134, v225
	v_add_f32_e32 v158, v135, v226
	v_add_f32_e32 v0, v136, v227
	s_nop 0
	s_nop 0
	s_nop 0
	s_nop 0
	v_fmamk_f32 v164, v164, 0x3a800000, v194
	v_cmp_gt_f32_e32 vcc, s61, v164
	v_mul_f32_e32 v165, 0x4f800000, v164
	s_nop 0
	s_nop 0
	s_nop 0
	v_cndmask_b32_e32 v164, v164, v165, vcc
	v_sqrt_f32_e32 v165, v164
	s_nop 0
	s_nop 0
	s_nop 0
	v_add_u32_e32 v167, -1, v165
	v_fma_f32 v168, -v167, v165, v164
	v_cmp_ge_f32_e64 s[0:1], 0, v168
	v_add_u32_e32 v168, 1, v165
	s_nop 0
	s_nop 0
	s_nop 0
	v_cndmask_b32_e64 v167, v165, v167, s[0:1]
	v_fma_f32 v165, -v168, v165, v164
	v_cmp_lt_f32_e64 s[0:1], 0, v165
	s_nop 0
	s_nop 0
	s_nop 0
	v_cndmask_b32_e64 v165, v167, v168, s[0:1]
	v_mul_f32_e32 v167, 0x37800000, v165
	v_cndmask_b32_e32 v165, v165, v167, vcc
	v_cmp_class_f32_e32 vcc, v164, v195
	s_nop 0
	s_nop 0
	s_nop 0
	v_cndmask_b32_e32 v164, v165, v164, vcc
	v_div_scale_f32 v165, s[0:1], v164, v164, 1.0
	v_rcp_f32_e32 v167, v165
	s_nop 0
	s_nop 0
	s_nop 0
	s_lshl_b64 s[0:1], s[8:9], 11
	v_fma_f32 v168, -v165, v167, 1.0
	v_fmac_f32_e32 v167, v168, v167
	v_div_scale_f32 v168, vcc, 1.0, v164, 1.0
	s_nop 0
	s_nop 0
	s_nop 0
	s_nop 0
	s_nop 0
	s_nop 0
	v_mul_f32_e32 v169, v168, v167
	v_fma_f32 v170, -v165, v169, v168
	v_fmac_f32_e32 v169, v170, v167
	v_fma_f32 v165, -v165, v169, v168
	v_div_fmas_f32 v165, v165, v167, v169
	v_div_fixup_f32 v167, v165, v164, 1.0
	v_mul_f32_e32 v114, v114, v167
	v_mul_f32_e32 v115, v115, v167
	v_lshl_add_u64 v[164:165], v[150:151], 0, s[0:1]
	v_mul_f32_e32 v118, v118, v167
	v_mul_f32_e32 v119, v119, v167
	v_fmamk_f32 v0, v0, 0x3a800000, v194
	v_mul_f32_e32 v126, v126, v167
	v_mul_f32_e32 v127, v127, v167
	v_mul_f32_e32 v122, v122, v167
	v_mul_f32_e32 v123, v123, v167
	s_add_i32 s8, s18, s97
	s_nop 0
	v_mul_f32_e32 v126, v126, v204
	v_mul_f32_e32 v127, v127, v205
	s_nop 0
	v_mul_f32_e32 v118, v118, v212
	s_nop 0
	v_mul_f32_e32 v114, v114, v216
	v_mul_f32_e32 v115, v115, v217
	v_cvt_pk_bf16_f32 v114, v114, v115
	v_mul_f32_e32 v115, v116, v167
	v_mul_f32_e32 v115, v115, v218
	v_mul_f32_e32 v116, v117, v167
	v_mul_f32_e32 v116, v116, v219
	v_cvt_pk_bf16_f32 v115, v115, v116
	global_store_dwordx2 v[164:165], v[114:115], off offset:1536
	v_fmamk_f32 v114, v166, 0x3a800000, v194
	v_cmp_gt_f32_e32 vcc, s61, v114
	v_mul_f32_e32 v115, 0x4f800000, v114
	v_mul_f32_e32 v119, v119, v213
	v_cndmask_b32_e32 v114, v114, v115, vcc
	v_sqrt_f32_e32 v115, v114
	v_cvt_pk_bf16_f32 v118, v118, v119
	v_mul_f32_e32 v119, v120, v167
	v_mul_f32_e32 v119, v119, v214
	v_add_u32_e32 v116, -1, v115
	v_fma_f32 v117, -v116, v115, v114
	v_cmp_ge_f32_e64 s[0:1], 0, v117
	v_add_u32_e32 v117, 1, v115
	v_mul_f32_e32 v120, v121, v167
	v_cndmask_b32_e64 v116, v115, v116, s[0:1]
	v_fma_f32 v115, -v117, v115, v114
	v_cmp_lt_f32_e64 s[0:1], 0, v115
	v_mul_f32_e32 v120, v120, v215
	v_cvt_pk_bf16_f32 v119, v119, v120
	global_store_dwordx2 v[164:165], v[118:119], off offset:1024
	v_cndmask_b32_e64 v115, v116, v117, s[0:1]
	v_mul_f32_e32 v116, 0x37800000, v115
	v_cndmask_b32_e32 v115, v115, v116, vcc
	v_cmp_class_f32_e32 vcc, v114, v195
	v_cvt_pk_bf16_f32 v126, v126, v127
	v_mul_f32_e32 v127, v128, v167
	v_mul_f32_e32 v127, v127, v206
	v_cndmask_b32_e32 v114, v115, v114, vcc
	v_div_scale_f32 v115, s[0:1], v114, v114, 1.0
	v_rcp_f32_e32 v116, v115
	s_lshl_b64 s[0:1], s[16:17], 11
	v_mul_f32_e32 v128, v129, v167
	v_mul_f32_e32 v128, v128, v207
	v_fma_f32 v117, -v115, v116, 1.0
	v_fmac_f32_e32 v116, v117, v116
	v_div_scale_f32 v117, vcc, 1.0, v114, 1.0
	v_mul_f32_e32 v118, v117, v116
	v_fma_f32 v119, -v115, v118, v117
	v_fmac_f32_e32 v118, v119, v116
	v_fma_f32 v115, -v115, v118, v117
	v_div_fmas_f32 v115, v115, v116, v118
	v_div_fixup_f32 v116, v115, v114, 1.0
	v_mul_f32_e32 v98, v98, v116
	v_mul_f32_e32 v99, v99, v116
	v_mul_f32_e32 v98, v98, v216
	v_mul_f32_e32 v99, v99, v217
	v_cvt_pk_bf16_f32 v98, v98, v99
	v_mul_f32_e32 v99, v100, v116
	v_lshl_add_u64 v[114:115], v[150:151], 0, s[0:1]
	v_mul_f32_e32 v99, v99, v218
	v_mul_f32_e32 v100, v101, v116
	v_mul_f32_e32 v100, v100, v219
	v_cvt_pk_bf16_f32 v99, v99, v100
	global_store_dwordx2 v[114:115], v[98:99], off offset:1536
	v_fmamk_f32 v98, v163, 0x3a800000, v194
	v_cmp_gt_f32_e32 vcc, s61, v98
	v_mul_f32_e32 v99, 0x4f800000, v98
	v_mul_f32_e32 v102, v102, v116
	v_cndmask_b32_e32 v98, v98, v99, vcc
	v_sqrt_f32_e32 v99, v98
	v_mul_f32_e32 v103, v103, v116
	v_mul_f32_e32 v102, v102, v212
	v_mul_f32_e32 v103, v103, v213
	v_add_u32_e32 v100, -1, v99
	v_fma_f32 v101, -v100, v99, v98
	v_cmp_ge_f32_e64 s[0:1], 0, v101
	v_add_u32_e32 v101, 1, v99
	v_cvt_pk_bf16_f32 v102, v102, v103
	v_mul_f32_e32 v103, v104, v116
	v_cndmask_b32_e64 v100, v99, v100, s[0:1]
	v_fma_f32 v99, -v101, v99, v98
	v_cmp_lt_f32_e64 s[0:1], 0, v99
	v_mul_f32_e32 v103, v103, v214
	v_mul_f32_e32 v104, v105, v116
	v_cndmask_b32_e64 v99, v100, v101, s[0:1]
	v_mul_f32_e32 v100, 0x37800000, v99
	v_cndmask_b32_e32 v99, v99, v100, vcc
	v_cmp_class_f32_e32 vcc, v98, v195
	v_mul_f32_e32 v104, v104, v215
	v_cvt_pk_bf16_f32 v103, v103, v104
	global_store_dwordx2 v[114:115], v[102:103], off offset:1024
	v_cndmask_b32_e32 v98, v99, v98, vcc
	v_div_scale_f32 v99, s[0:1], v98, v98, 1.0
	v_rcp_f32_e32 v100, v99
	s_lshl_b64 s[0:1], s[14:15], 11
	v_mul_f32_e32 v110, v110, v116
	v_mul_f32_e32 v111, v111, v116
	v_fma_f32 v101, -v99, v100, 1.0
	v_fmac_f32_e32 v100, v101, v100
	v_div_scale_f32 v101, vcc, 1.0, v98, 1.0
	v_mul_f32_e32 v102, v101, v100
	v_fma_f32 v103, -v99, v102, v101
	v_fmac_f32_e32 v102, v103, v100
	v_fma_f32 v99, -v99, v102, v101
	v_div_fmas_f32 v99, v99, v100, v102
	v_div_fixup_f32 v100, v99, v98, 1.0
	v_mul_f32_e32 v82, v82, v100
	v_mul_f32_e32 v83, v83, v100
	v_mul_f32_e32 v82, v82, v216
	v_mul_f32_e32 v83, v83, v217
	v_cvt_pk_bf16_f32 v82, v82, v83
	v_mul_f32_e32 v83, v84, v100
	v_lshl_add_u64 v[98:99], v[150:151], 0, s[0:1]
	v_mul_f32_e32 v83, v83, v218
	v_mul_f32_e32 v84, v85, v100
	v_mul_f32_e32 v84, v84, v219
	v_cvt_pk_bf16_f32 v83, v83, v84
	global_store_dwordx2 v[98:99], v[82:83], off offset:1536
	v_fmamk_f32 v82, v161, 0x3a800000, v194
	v_cmp_gt_f32_e32 vcc, s61, v82
	v_mul_f32_e32 v83, 0x4f800000, v82
	v_mul_f32_e32 v86, v86, v100
	v_cndmask_b32_e32 v82, v82, v83, vcc
	v_sqrt_f32_e32 v83, v82
	v_mul_f32_e32 v87, v87, v100
	v_mul_f32_e32 v86, v86, v212
	v_mul_f32_e32 v87, v87, v213
	v_add_u32_e32 v84, -1, v83
	v_fma_f32 v85, -v84, v83, v82
	v_cmp_ge_f32_e64 s[0:1], 0, v85
	v_add_u32_e32 v85, 1, v83
	v_cvt_pk_bf16_f32 v86, v86, v87
	v_mul_f32_e32 v87, v88, v100
	v_cndmask_b32_e64 v84, v83, v84, s[0:1]
	v_fma_f32 v83, -v85, v83, v82
	v_cmp_lt_f32_e64 s[0:1], 0, v83
	v_mul_f32_e32 v87, v87, v214
	v_mul_f32_e32 v88, v89, v100
	v_cndmask_b32_e64 v83, v84, v85, s[0:1]
	v_mul_f32_e32 v84, 0x37800000, v83
	v_cndmask_b32_e32 v83, v83, v84, vcc
	v_cmp_class_f32_e32 vcc, v82, v195
	v_mul_f32_e32 v88, v88, v215
	v_cvt_pk_bf16_f32 v87, v87, v88
	global_store_dwordx2 v[98:99], v[86:87], off offset:1024
	v_cndmask_b32_e32 v82, v83, v82, vcc
	v_div_scale_f32 v83, s[0:1], v82, v82, 1.0
	v_rcp_f32_e32 v84, v83
	s_lshl_b64 s[0:1], s[12:13], 11
	v_mul_f32_e32 v94, v94, v100
	v_mul_f32_e32 v95, v95, v100
	v_fma_f32 v85, -v83, v84, 1.0
	v_fmac_f32_e32 v84, v85, v84
	v_div_scale_f32 v85, vcc, 1.0, v82, 1.0
	v_mul_f32_e32 v86, v85, v84
	v_fma_f32 v87, -v83, v86, v85
	v_fmac_f32_e32 v86, v87, v84
	v_fma_f32 v83, -v83, v86, v85
	v_div_fmas_f32 v83, v83, v84, v86
	v_div_fixup_f32 v84, v83, v82, 1.0
	v_mul_f32_e32 v66, v66, v84
	v_mul_f32_e32 v67, v67, v84
	v_mul_f32_e32 v66, v66, v216
	v_mul_f32_e32 v67, v67, v217
	v_cvt_pk_bf16_f32 v66, v66, v67
	v_mul_f32_e32 v67, v68, v84
	v_lshl_add_u64 v[82:83], v[150:151], 0, s[0:1]
	v_mul_f32_e32 v67, v67, v218
	v_mul_f32_e32 v68, v69, v84
	v_mul_f32_e32 v68, v68, v219
	v_cvt_pk_bf16_f32 v67, v67, v68
	global_store_dwordx2 v[82:83], v[66:67], off offset:1536
	v_fmamk_f32 v66, v160, 0x3a800000, v194
	v_cmp_gt_f32_e32 vcc, s61, v66
	v_mul_f32_e32 v67, 0x4f800000, v66
	v_mul_f32_e32 v70, v70, v84
	v_cndmask_b32_e32 v66, v66, v67, vcc
	v_sqrt_f32_e32 v67, v66
	v_mul_f32_e32 v71, v71, v84
	v_mul_f32_e32 v70, v70, v212
	v_mul_f32_e32 v71, v71, v213
	v_add_u32_e32 v68, -1, v67
	v_fma_f32 v69, -v68, v67, v66
	v_cmp_ge_f32_e64 s[0:1], 0, v69
	v_add_u32_e32 v69, 1, v67
	v_cvt_pk_bf16_f32 v70, v70, v71
	v_mul_f32_e32 v71, v72, v84
	v_cndmask_b32_e64 v68, v67, v68, s[0:1]
	v_fma_f32 v67, -v69, v67, v66
	v_cmp_lt_f32_e64 s[0:1], 0, v67
	v_mul_f32_e32 v71, v71, v214
	v_mul_f32_e32 v72, v73, v84
	v_cndmask_b32_e64 v67, v68, v69, s[0:1]
	v_mul_f32_e32 v68, 0x37800000, v67
	v_cndmask_b32_e32 v67, v67, v68, vcc
	v_cmp_class_f32_e32 vcc, v66, v195
	v_mul_f32_e32 v72, v72, v215
	v_cvt_pk_bf16_f32 v71, v71, v72
	global_store_dwordx2 v[82:83], v[70:71], off offset:1024
	v_cndmask_b32_e32 v66, v67, v66, vcc
	v_div_scale_f32 v67, s[0:1], v66, v66, 1.0
	v_rcp_f32_e32 v68, v67
	s_lshl_b64 s[0:1], s[10:11], 11
	v_mul_f32_e32 v78, v78, v84
	v_mul_f32_e32 v79, v79, v84
	v_fma_f32 v69, -v67, v68, 1.0
	v_fmac_f32_e32 v68, v69, v68
	v_div_scale_f32 v69, vcc, 1.0, v66, 1.0
	v_mul_f32_e32 v70, v69, v68
	v_fma_f32 v71, -v67, v70, v69
	v_fmac_f32_e32 v70, v71, v68
	v_fma_f32 v67, -v67, v70, v69
	v_div_fmas_f32 v67, v67, v68, v70
	v_div_fixup_f32 v68, v67, v66, 1.0
	v_mul_f32_e32 v50, v50, v68
	v_mul_f32_e32 v51, v51, v68
	v_mul_f32_e32 v50, v50, v216
	v_mul_f32_e32 v51, v51, v217
	v_cvt_pk_bf16_f32 v50, v50, v51
	v_mul_f32_e32 v51, v52, v68
	v_lshl_add_u64 v[66:67], v[150:151], 0, s[0:1]
	v_mul_f32_e32 v51, v51, v218
	v_mul_f32_e32 v52, v53, v68
	v_mul_f32_e32 v52, v52, v219
	v_cvt_pk_bf16_f32 v51, v51, v52
	global_store_dwordx2 v[66:67], v[50:51], off offset:1536
	v_fmamk_f32 v50, v159, 0x3a800000, v194
	v_cmp_gt_f32_e32 vcc, s61, v50
	v_mul_f32_e32 v51, 0x4f800000, v50
	v_mul_f32_e32 v54, v54, v68
	v_cndmask_b32_e32 v50, v50, v51, vcc
	v_sqrt_f32_e32 v51, v50
	v_mul_f32_e32 v55, v55, v68
	v_mul_f32_e32 v54, v54, v212
	v_mul_f32_e32 v55, v55, v213
	v_add_u32_e32 v52, -1, v51
	v_fma_f32 v53, -v52, v51, v50
	v_cmp_ge_f32_e64 s[0:1], 0, v53
	v_add_u32_e32 v53, 1, v51
	v_cvt_pk_bf16_f32 v54, v54, v55
	v_mul_f32_e32 v55, v56, v68
	v_cndmask_b32_e64 v52, v51, v52, s[0:1]
	v_fma_f32 v51, -v53, v51, v50
	v_cmp_lt_f32_e64 s[0:1], 0, v51
	v_mul_f32_e32 v55, v55, v214
	v_mul_f32_e32 v56, v57, v68
	v_cndmask_b32_e64 v51, v52, v53, s[0:1]
	v_mul_f32_e32 v52, 0x37800000, v51
	v_cndmask_b32_e32 v51, v51, v52, vcc
	v_cmp_class_f32_e32 vcc, v50, v195
	v_mul_f32_e32 v56, v56, v215
	v_cvt_pk_bf16_f32 v55, v55, v56
	global_store_dwordx2 v[66:67], v[54:55], off offset:1024
	v_cndmask_b32_e32 v50, v51, v50, vcc
	v_div_scale_f32 v51, s[0:1], v50, v50, 1.0
	v_rcp_f32_e32 v52, v51
	s_lshl_b64 s[0:1], s[6:7], 11
	v_mul_f32_e32 v62, v62, v68
	v_mul_f32_e32 v63, v63, v68
	v_fma_f32 v53, -v51, v52, 1.0
	v_fmac_f32_e32 v52, v53, v52
	v_div_scale_f32 v53, vcc, 1.0, v50, 1.0
	v_mul_f32_e32 v54, v53, v52
	v_fma_f32 v55, -v51, v54, v53
	v_fmac_f32_e32 v54, v55, v52
	v_fma_f32 v51, -v51, v54, v53
	v_div_fmas_f32 v51, v51, v52, v54
	v_div_fixup_f32 v52, v51, v50, 1.0
	v_mul_f32_e32 v26, v26, v52
	v_mul_f32_e32 v27, v27, v52
	v_mul_f32_e32 v26, v26, v216
	v_mul_f32_e32 v27, v27, v217
	v_cvt_pk_bf16_f32 v26, v26, v27
	v_mul_f32_e32 v27, v28, v52
	v_lshl_add_u64 v[50:51], v[150:151], 0, s[0:1]
	v_mul_f32_e32 v27, v27, v218
	v_mul_f32_e32 v28, v29, v52
	v_mul_f32_e32 v28, v28, v219
	v_cvt_pk_bf16_f32 v27, v27, v28
	global_store_dwordx2 v[50:51], v[26:27], off offset:1536
	v_fmamk_f32 v26, v158, 0x3a800000, v194
	v_cmp_gt_f32_e32 vcc, s61, v26
	v_mul_f32_e32 v27, 0x4f800000, v26
	v_mul_f32_e32 v34, v34, v52
	v_cndmask_b32_e32 v26, v26, v27, vcc
	v_sqrt_f32_e32 v27, v26
	v_mul_f32_e32 v35, v35, v52
	v_mul_f32_e32 v34, v212, v34
	v_mul_f32_e32 v35, v213, v35
	v_add_u32_e32 v28, -1, v27
	v_fma_f32 v29, -v28, v27, v26
	v_cmp_ge_f32_e64 s[0:1], 0, v29
	v_add_u32_e32 v29, 1, v27
	v_cvt_pk_bf16_f32 v34, v34, v35
	v_mul_f32_e32 v35, v36, v52
	v_cndmask_b32_e64 v28, v27, v28, s[0:1]
	v_fma_f32 v27, -v29, v27, v26
	v_cmp_lt_f32_e64 s[0:1], 0, v27
	v_mul_f32_e32 v35, v214, v35
	v_mul_f32_e32 v36, v37, v52
	v_cndmask_b32_e64 v27, v28, v29, s[0:1]
	v_mul_f32_e32 v28, 0x37800000, v27
	v_cndmask_b32_e32 v27, v27, v28, vcc
	v_cmp_class_f32_e32 vcc, v26, v195
	v_mul_f32_e32 v36, v215, v36
	v_cvt_pk_bf16_f32 v35, v35, v36
	global_store_dwordx2 v[50:51], v[34:35], off offset:1024
	v_cndmask_b32_e32 v26, v27, v26, vcc
	v_div_scale_f32 v27, s[0:1], v26, v26, 1.0
	v_rcp_f32_e32 v28, v27
	s_lshl_b64 s[0:1], s[4:5], 11
	v_mul_f32_e32 v46, v46, v52
	v_mul_f32_e32 v47, v47, v52
	v_fma_f32 v29, -v27, v28, 1.0
	v_fmac_f32_e32 v28, v29, v28
	v_div_scale_f32 v29, vcc, 1.0, v26, 1.0
	v_mul_f32_e32 v34, v29, v28
	v_fma_f32 v35, -v27, v34, v29
	v_fmac_f32_e32 v34, v35, v28
	v_fma_f32 v27, -v27, v34, v29
	v_div_fmas_f32 v27, v27, v28, v34
	v_div_fixup_f32 v28, v27, v26, 1.0
	v_mul_f32_e32 v2, v2, v28
	v_mul_f32_e32 v3, v3, v28
	v_mul_f32_e32 v2, v216, v2
	v_mul_f32_e32 v3, v217, v3
	v_cvt_pk_bf16_f32 v2, v2, v3
	v_mul_f32_e32 v3, v4, v28
	v_lshl_add_u64 v[26:27], v[150:151], 0, s[0:1]
	v_mul_f32_e32 v3, v218, v3
	v_mul_f32_e32 v4, v5, v28
	v_mul_f32_e32 v4, v219, v4
	v_cvt_pk_bf16_f32 v3, v3, v4
	global_store_dwordx2 v[26:27], v[2:3], off offset:1536
	v_cmp_gt_f32_e32 vcc, s61, v0
	v_mul_f32_e32 v2, 0x4f800000, v0
	v_mul_f32_e32 v6, v6, v28
	v_cndmask_b32_e32 v0, v0, v2, vcc
	v_sqrt_f32_e32 v2, v0
	v_mul_f32_e32 v7, v7, v28
	v_mul_f32_e32 v6, v212, v6
	v_mul_f32_e32 v7, v213, v7
	v_add_u32_e32 v3, -1, v2
	v_fma_f32 v4, -v3, v2, v0
	v_cmp_ge_f32_e64 s[0:1], 0, v4
	v_add_u32_e32 v4, 1, v2
	v_cvt_pk_bf16_f32 v6, v6, v7
	v_mul_f32_e32 v7, v8, v28
	v_cndmask_b32_e64 v3, v2, v3, s[0:1]
	v_fma_f32 v2, -v4, v2, v0
	v_cmp_lt_f32_e64 s[0:1], 0, v2
	v_mul_f32_e32 v7, v214, v7
	v_mul_f32_e32 v8, v9, v28
	v_cndmask_b32_e64 v2, v3, v4, s[0:1]
	v_mul_f32_e32 v3, 0x37800000, v2
	v_cndmask_b32_e32 v2, v2, v3, vcc
	v_cmp_class_f32_e32 vcc, v0, v195
	v_mul_f32_e32 v8, v215, v8
	v_cvt_pk_bf16_f32 v7, v7, v8
	global_store_dwordx2 v[26:27], v[6:7], off offset:1024
	v_cndmask_b32_e32 v0, v2, v0, vcc
	v_div_scale_f32 v2, s[0:1], v0, v0, 1.0
	v_rcp_f32_e32 v3, v2
	v_mul_f32_e32 v14, v14, v28
	v_mul_f32_e32 v15, v15, v28
	v_mul_f32_e32 v110, v110, v204
	v_fma_f32 v4, -v2, v3, 1.0
	v_fmac_f32_e32 v3, v4, v3
	v_div_scale_f32 v4, vcc, 1.0, v0, 1.0
	v_mul_f32_e32 v5, v4, v3
	v_fma_f32 v6, -v2, v5, v4
	v_fmac_f32_e32 v5, v6, v3
	v_fma_f32 v2, -v2, v5, v4
	v_div_fmas_f32 v2, v2, v3, v5
	v_div_fixup_f32 v0, v2, v0, 1.0
	v_mul_f32_e32 v4, v38, v0
	v_mul_f32_e32 v5, v39, v0
	v_mul_f32_e32 v4, v204, v4
	v_mul_f32_e32 v5, v205, v5
	v_mul_f32_e32 v111, v111, v205
	v_mul_f32_e32 v94, v94, v204
	v_mul_f32_e32 v95, v95, v205
	v_mul_f32_e32 v78, v204, v78
	v_mul_f32_e32 v79, v205, v79
	v_mul_f32_e32 v62, v204, v62
	v_mul_f32_e32 v63, v205, v63
	v_mul_f32_e32 v46, v204, v46
	v_mul_f32_e32 v47, v205, v47
	v_mul_f32_e32 v14, v204, v14
	v_mul_f32_e32 v15, v205, v15
	v_cvt_pk_bf16_f32 v4, v4, v5
	v_mul_f32_e32 v5, v40, v0
	v_cvt_pk_bf16_f32 v110, v110, v111
	v_mul_f32_e32 v111, v112, v116
	v_cvt_pk_bf16_f32 v94, v94, v95
	v_mul_f32_e32 v95, v96, v100
	v_cvt_pk_bf16_f32 v78, v78, v79
	v_mul_f32_e32 v79, v80, v84
	v_cvt_pk_bf16_f32 v62, v62, v63
	v_mul_f32_e32 v63, v64, v68
	v_cvt_pk_bf16_f32 v46, v46, v47
	v_mul_f32_e32 v47, v48, v52
	v_cvt_pk_bf16_f32 v14, v14, v15
	v_mul_f32_e32 v15, v16, v28
	s_lshl_b64 s[0:1], s[2:3], 11
	v_mul_f32_e32 v5, v206, v5
	v_mul_f32_e32 v6, v41, v0
	v_mul_f32_e32 v111, v111, v206
	v_mul_f32_e32 v112, v113, v116
	v_mul_f32_e32 v95, v95, v206
	v_mul_f32_e32 v96, v97, v100
	v_mul_f32_e32 v79, v206, v79
	v_mul_f32_e32 v80, v81, v84
	v_mul_f32_e32 v63, v206, v63
	v_mul_f32_e32 v64, v65, v68
	v_mul_f32_e32 v47, v206, v47
	v_mul_f32_e32 v48, v49, v52
	v_mul_f32_e32 v15, v206, v15
	v_mul_f32_e32 v16, v17, v28
	v_lshl_add_u64 v[2:3], v[150:151], 0, s[0:1]
	v_mul_f32_e32 v6, v207, v6
	v_cvt_pk_bf16_f32 v5, v5, v6
	v_cvt_pk_bf16_f32 v127, v127, v128
	global_store_dwordx2 v[164:165], v[126:127], off
	v_mul_f32_e32 v112, v112, v207
	v_cvt_pk_bf16_f32 v111, v111, v112
	global_store_dwordx2 v[114:115], v[110:111], off
	v_mul_f32_e32 v96, v96, v207
	v_cvt_pk_bf16_f32 v95, v95, v96
	global_store_dwordx2 v[98:99], v[94:95], off
	v_mul_f32_e32 v80, v207, v80
	v_cvt_pk_bf16_f32 v79, v79, v80
	global_store_dwordx2 v[82:83], v[78:79], off
	v_mul_f32_e32 v64, v207, v64
	v_cvt_pk_bf16_f32 v63, v63, v64
	global_store_dwordx2 v[66:67], v[62:63], off
	v_mul_f32_e32 v48, v207, v48
	v_cvt_pk_bf16_f32 v47, v47, v48
	global_store_dwordx2 v[50:51], v[46:47], off
	v_mul_f32_e32 v16, v207, v16
	v_cvt_pk_bf16_f32 v15, v15, v16
	global_store_dwordx2 v[26:27], v[14:15], off
	global_store_dwordx2 v[2:3], v[4:5], off
	v_mul_f32_e32 v4, v30, v0
	v_mul_f32_e32 v5, v31, v0
	v_mul_f32_e32 v106, v106, v116
	v_mul_f32_e32 v107, v107, v116
	v_mul_f32_e32 v90, v90, v100
	v_mul_f32_e32 v91, v91, v100
	v_mul_f32_e32 v74, v74, v84
	v_mul_f32_e32 v75, v75, v84
	v_mul_f32_e32 v58, v58, v68
	v_mul_f32_e32 v59, v59, v68
	v_mul_f32_e32 v42, v42, v52
	v_mul_f32_e32 v43, v43, v52
	v_mul_f32_e32 v10, v10, v28
	v_mul_f32_e32 v11, v11, v28
	v_mul_f32_e32 v4, v208, v4
	v_mul_f32_e32 v5, v209, v5
	v_mul_f32_e32 v122, v122, v208
	v_mul_f32_e32 v123, v123, v209
	v_mul_f32_e32 v106, v106, v208
	v_mul_f32_e32 v107, v107, v209
	v_mul_f32_e32 v90, v90, v208
	v_mul_f32_e32 v91, v91, v209
	v_mul_f32_e32 v74, v74, v208
	v_mul_f32_e32 v75, v75, v209
	v_mul_f32_e32 v58, v208, v58
	v_mul_f32_e32 v59, v209, v59
	v_mul_f32_e32 v42, v208, v42
	v_mul_f32_e32 v43, v209, v43
	v_mul_f32_e32 v10, v208, v10
	v_mul_f32_e32 v11, v209, v11
	v_cvt_pk_bf16_f32 v4, v4, v5
	v_mul_f32_e32 v5, v32, v0
	v_cvt_pk_bf16_f32 v122, v122, v123
	v_mul_f32_e32 v123, v124, v167
	v_cvt_pk_bf16_f32 v106, v106, v107
	v_mul_f32_e32 v107, v108, v116
	v_cvt_pk_bf16_f32 v90, v90, v91
	v_mul_f32_e32 v91, v92, v100
	v_cvt_pk_bf16_f32 v74, v74, v75
	v_mul_f32_e32 v75, v76, v84
	v_cvt_pk_bf16_f32 v58, v58, v59
	v_mul_f32_e32 v59, v60, v68
	v_cvt_pk_bf16_f32 v42, v42, v43
	v_mul_f32_e32 v43, v44, v52
	v_cvt_pk_bf16_f32 v10, v10, v11
	v_mul_f32_e32 v11, v12, v28
	v_mul_f32_e32 v5, v210, v5
	v_mul_f32_e32 v6, v33, v0
	v_mul_f32_e32 v123, v123, v210
	v_mul_f32_e32 v124, v125, v167
	v_mul_f32_e32 v107, v107, v210
	v_mul_f32_e32 v108, v109, v116
	v_mul_f32_e32 v91, v91, v210
	v_mul_f32_e32 v92, v93, v100
	v_mul_f32_e32 v75, v75, v210
	v_mul_f32_e32 v76, v77, v84
	v_mul_f32_e32 v59, v210, v59
	v_mul_f32_e32 v60, v61, v68
	v_mul_f32_e32 v43, v210, v43
	v_mul_f32_e32 v44, v45, v52
	v_mul_f32_e32 v11, v210, v11
	v_mul_f32_e32 v12, v13, v28
	v_mul_f32_e32 v6, v211, v6
	v_cvt_pk_bf16_f32 v5, v5, v6
	v_mul_f32_e32 v124, v124, v211
	v_cvt_pk_bf16_f32 v123, v123, v124
	global_store_dwordx2 v[164:165], v[122:123], off offset:512
	v_mul_f32_e32 v108, v108, v211
	v_cvt_pk_bf16_f32 v107, v107, v108
	global_store_dwordx2 v[114:115], v[106:107], off offset:512
	v_mul_f32_e32 v92, v92, v211
	v_cvt_pk_bf16_f32 v91, v91, v92
	global_store_dwordx2 v[98:99], v[90:91], off offset:512
	v_mul_f32_e32 v76, v76, v211
	v_cvt_pk_bf16_f32 v75, v75, v76
	global_store_dwordx2 v[82:83], v[74:75], off offset:512
	v_mul_f32_e32 v60, v211, v60
	v_cvt_pk_bf16_f32 v59, v59, v60
	global_store_dwordx2 v[66:67], v[58:59], off offset:512
	v_mul_f32_e32 v44, v211, v44
	v_cvt_pk_bf16_f32 v43, v43, v44
	global_store_dwordx2 v[50:51], v[42:43], off offset:512
	v_mul_f32_e32 v12, v211, v12
	v_cvt_pk_bf16_f32 v11, v11, v12
	global_store_dwordx2 v[26:27], v[10:11], off offset:512
	global_store_dwordx2 v[2:3], v[4:5], off offset:512
	v_mul_f32_e32 v4, v22, v0
	v_mul_f32_e32 v5, v23, v0
	v_mul_f32_e32 v4, v212, v4
	v_mul_f32_e32 v5, v213, v5
	v_cvt_pk_bf16_f32 v4, v4, v5
	v_mul_f32_e32 v5, v24, v0
	v_mul_f32_e32 v5, v214, v5
	v_mul_f32_e32 v6, v25, v0
	v_mul_f32_e32 v6, v215, v6
	v_cvt_pk_bf16_f32 v5, v5, v6
	global_store_dwordx2 v[2:3], v[4:5], off offset:1024
	v_mul_f32_e32 v4, v18, v0
	v_mul_f32_e32 v5, v19, v0
	v_mul_f32_e32 v4, v216, v4
	v_mul_f32_e32 v5, v217, v5
	v_cvt_pk_bf16_f32 v4, v4, v5
	v_mul_f32_e32 v5, v20, v0
	v_mul_f32_e32 v5, v218, v5
	v_mul_f32_e32 v0, v21, v0
	s_cmp_gt_i32 s8, 0xffff
	v_mul_f32_e32 v0, v219, v0
	v_cvt_pk_bf16_f32 v5, v5, v0
	global_store_dwordx2 v[2:3], v[4:5], off offset:1536
	s_cbranch_scc0 .LBB0_956
